# GEMM K-loops: the two segment-closing waits (vmcnt(8), lgkmcnt(0)) merged into one s_waitcnt before the barrier; on top of v92
# baseline (speedup 1.0000x reference)
; #define PG8_STAGE(bufoff, gbase, voff) do { _Pragma("unroll") for (int _i = 0; _i < 2; ++_i) \
;         __builtin_amdgcn_global_load_lds((const unsigned*)((const char*)(gbase) + (voff)[_i]), (LAS unsigned*)(lds + (bufoff) + ldsw + _i * 8192), 16, 0, 0); } while (0)
; #define PG8_LDA(dst, b, h) do { _Pragma("unroll") for (int m = 0; m < 4; ++m) _Pragma("unroll") for (int k = 0; k < 2; ++k) dst[m][k] = *(const LAS bf16x8*)(lds + PG8_SA(b, h) + aoff + m * 2048 + k * 1024); } while (0)
; #define PG8_LDB(dst, b, h) do { _Pragma("unroll") for (int n = 0; n < 2; ++n) _Pragma("unroll") for (int k = 0; k < 2; ++k) dst[n][k] = *(const LAS bf16x8*)(lds + PG8_SB(b, h) + boff + n * 2048 + k * 1024); } while (0)
; #define PG8_MMA(ai, bj, At, Bt) do { __builtin_amdgcn_s_setprio(1); _Pragma("unroll") for (int m = 0; m < 4; ++m) _Pragma("unroll") for (int n = 0; n < 2; ++n) _Pragma("unroll") for (int k = 0; k < 2; ++k) \
;         acc[ai][bj][m][n] = __builtin_amdgcn_mfma_f32_16x16x32_bf16(Bt[n][k], At[m][k], acc[ai][bj][m][n], 0, 0, 0); __builtin_amdgcn_s_setprio(0); } while (0)
; template <class Epi, bool SP2 = false>
; __device__ __forceinline__ void gemm_phase(LAS unsigned char* lds, const Gemm g, const StaticOrder& S, const Epi& E) {
;     ...
;         const bool has_next = S.next(ui + 1, nxt);
;         const char* nA = has_next ? (const char*)g.A + (size_t)nxt.pm * tstepA : cA; const char* nB = has_next ? (const char*)g.Bt + (size_t)nxt.pn * tstepB : cB;
;         for (int t = 0; t < nt; t += 2) {
;             const bool last = (t == nt - 2);
;             const char* a1 = cA + (size_t)(t + 1) * kstep;
;             const char* a2 = last ? nA : cA + (size_t)(t + 2) * kstep; const char* b2 = last ? nB : cB + (size_t)(t + 2) * kstep;
;             const char* a3 = a2 + kstep; const char* b3 = b2 + kstep;
;             if constexpr (SP2) {
;             PG8_LDB(B0, 0, 0); PG8_LDB(B1, 0, 1); PG8_SCHED; PG8_LDA(At, 0, 0); PG8_STAGE(PG8_SA(1, 1), a1 + hstepA, voffA);
;             PG8_WAIT_V(8); PG8_WAIT_L(0); PG8_BAR; PG8_MMA(0, 0, At, B0); PG8_MMA(0, 1, At, B1); PG8_BAR; PG8_SCHED;
;             PG8_LDA(At, 0, 1); PG8_STAGE(PG8_SB(0, 0), b2, voffB); PG8_STAGE(PG8_SB(0, 1), b2 + hstepB, voffB); PG8_STAGE(PG8_SA(0, 0), a2, voffA);
;             PG8_WAIT_V(8); PG8_WAIT_L(0); PG8_BAR; PG8_MMA(1, 0, At, B0); PG8_MMA(1, 1, At, B1); PG8_BAR; PG8_SCHED;
.LBB0_263:
	ds_read_b128 v[152:155], v149
	ds_read_b128 v[156:159], v149 offset:1024
	ds_read_b128 v[160:163], v149 offset:2048
	ds_read_b128 v[164:167], v149 offset:3072
	ds_read_b128 v[168:171], v150
	ds_read_b128 v[172:175], v150 offset:1024
	ds_read_b128 v[176:179], v150 offset:2048
	ds_read_b128 v[180:183], v150 offset:3072
	s_add_u32 s44, s34, 0xfffc0080
	s_addc_u32 s45, s35, -1
	s_cmp_eq_u32 s75, 12
	s_cselect_b32 s51, s27, s45
	s_cselect_b32 s50, s67, s44
	s_cselect_b32 s45, s25, s74
	s_cselect_b32 s44, s72, s73
	v_lshl_add_u64 v[146:147], s[34:35], 0, v[138:139]
	s_add_i32 m0, s41, 0xc000
	ds_read_b128 v[184:187], v151
	ds_read_b128 v[188:191], v151 offset:1024
	ds_read_b128 v[192:195], v151 offset:2048
	ds_read_b128 v[196:199], v151 offset:3072
	ds_read_b128 v[200:203], v151 offset:4096
	ds_read_b128 v[204:207], v151 offset:5120
	ds_read_b128 v[208:211], v151 offset:6144
	ds_read_b128 v[212:215], v151 offset:7168
	global_load_lds_dwordx4 v[146:147], off
	v_lshl_add_u64 v[146:147], s[34:35], 0, v[140:141]
	s_add_i32 m0, s41, 0xe000
	s_nop 0
	global_load_lds_dwordx4 v[146:147], off
	s_waitcnt vmcnt(8) lgkmcnt(0)
	s_barrier
	v_mfma_f32_16x16x32_bf16 v[124:127], v[152:155], v[184:187], v[124:127]
	v_mfma_f32_16x16x32_bf16 v[120:123], v[160:163], v[184:187], v[120:123]
	v_mfma_f32_16x16x32_bf16 v[108:111], v[152:155], v[192:195], v[108:111]
	v_mfma_f32_16x16x32_bf16 v[104:107], v[160:163], v[192:195], v[104:107]
	v_mfma_f32_16x16x32_bf16 v[92:95], v[152:155], v[200:203], v[92:95]
	v_mfma_f32_16x16x32_bf16 v[88:91], v[160:163], v[200:203], v[88:91]
	v_mfma_f32_16x16x32_bf16 v[76:79], v[152:155], v[208:211], v[76:79]
	v_mfma_f32_16x16x32_bf16 v[72:75], v[160:163], v[208:211], v[72:75]
	v_mfma_f32_16x16x32_bf16 v[124:127], v[156:159], v[188:191], v[124:127]
	v_mfma_f32_16x16x32_bf16 v[120:123], v[164:167], v[188:191], v[120:123]
	v_mfma_f32_16x16x32_bf16 v[108:111], v[156:159], v[196:199], v[108:111]
	v_mfma_f32_16x16x32_bf16 v[104:107], v[164:167], v[196:199], v[104:107]
	v_mfma_f32_16x16x32_bf16 v[92:95], v[156:159], v[204:207], v[92:95]
	v_mfma_f32_16x16x32_bf16 v[88:91], v[164:167], v[204:207], v[88:91]
	v_mfma_f32_16x16x32_bf16 v[76:79], v[156:159], v[212:215], v[76:79]
	v_mfma_f32_16x16x32_bf16 v[72:75], v[164:167], v[212:215], v[72:75]
	v_mfma_f32_16x16x32_bf16 v[116:119], v[168:171], v[184:187], v[116:119]
	v_mfma_f32_16x16x32_bf16 v[112:115], v[176:179], v[184:187], v[112:115]
	v_mfma_f32_16x16x32_bf16 v[100:103], v[168:171], v[192:195], v[100:103]
	v_mfma_f32_16x16x32_bf16 v[96:99], v[176:179], v[192:195], v[96:99]
	v_mfma_f32_16x16x32_bf16 v[84:87], v[168:171], v[200:203], v[84:87]
	v_mfma_f32_16x16x32_bf16 v[80:83], v[176:179], v[200:203], v[80:83]
	v_mfma_f32_16x16x32_bf16 v[68:71], v[168:171], v[208:211], v[68:71]
	v_mfma_f32_16x16x32_bf16 v[64:67], v[176:179], v[208:211], v[64:67]
	v_mfma_f32_16x16x32_bf16 v[116:119], v[172:175], v[188:191], v[116:119]
	v_mfma_f32_16x16x32_bf16 v[112:115], v[180:183], v[188:191], v[112:115]
	v_mfma_f32_16x16x32_bf16 v[100:103], v[172:175], v[196:199], v[100:103]
	v_mfma_f32_16x16x32_bf16 v[96:99], v[180:183], v[196:199], v[96:99]
	v_mfma_f32_16x16x32_bf16 v[84:87], v[172:175], v[204:207], v[84:87]
	v_mfma_f32_16x16x32_bf16 v[80:83], v[180:183], v[204:207], v[80:83]
	v_mfma_f32_16x16x32_bf16 v[68:71], v[172:175], v[212:215], v[68:71]
	v_mfma_f32_16x16x32_bf16 v[64:67], v[180:183], v[212:215], v[64:67]
	s_barrier
	s_add_i32 s68, s64, s3
	v_lshl_add_u64 v[146:147], s[44:45], 0, v[134:135]
	s_mov_b32 m0, s68
	ds_read_b128 v[184:187], v151 offset:16384
	ds_read_b128 v[188:191], v151 offset:17408
	ds_read_b128 v[192:195], v151 offset:18432
	ds_read_b128 v[196:199], v151 offset:19456
	ds_read_b128 v[200:203], v151 offset:20480
	ds_read_b128 v[204:207], v151 offset:21504
	ds_read_b128 v[208:211], v151 offset:22528
	ds_read_b128 v[212:215], v151 offset:23552
	global_load_lds_dwordx4 v[146:147], off
	s_add_i32 m0, s68, 0x2000
	s_add_u32 s68, s44, 0x40000
	v_lshl_add_u64 v[216:217], s[44:45], 0, v[130:131]
	s_addc_u32 s69, s45, 0
	s_add_i32 s70, s65, s3
	global_load_lds_dwordx4 v[216:217], off
	v_lshl_add_u64 v[218:219], s[68:69], 0, v[134:135]
	s_mov_b32 m0, s70
	v_lshl_add_u64 v[220:221], s[50:51], 0, v[132:133]
	global_load_lds_dwordx4 v[218:219], off
	v_lshl_add_u64 v[218:219], s[68:69], 0, v[130:131]
	s_add_i32 m0, s70, 0x2000
	s_nop 0
	global_load_lds_dwordx4 v[218:219], off
	v_lshl_add_u64 v[218:219], s[50:51], 0, v[136:137]
	s_mov_b32 m0, s41
	s_nop 0
	global_load_lds_dwordx4 v[218:219], off
	s_mov_b32 m0, s54
	s_nop 0
	global_load_lds_dwordx4 v[220:221], off
	s_waitcnt vmcnt(8) lgkmcnt(0)
	s_barrier
; #define PG8_STAGE(bufoff, gbase, voff) do { _Pragma("unroll") for (int _i = 0; _i < 2; ++_i) \
;         __builtin_amdgcn_global_load_lds((const unsigned*)((const char*)(gbase) + (voff)[_i]), (LAS unsigned*)(lds + (bufoff) + ldsw + _i * 8192), 16, 0, 0); } while (0)
; #define PG8_LDA(dst, b, h) do { _Pragma("unroll") for (int m = 0; m < 4; ++m) _Pragma("unroll") for (int k = 0; k < 2; ++k) dst[m][k] = *(const LAS bf16x8*)(lds + PG8_SA(b, h) + aoff + m * 2048 + k * 1024); } while (0)
; #define PG8_LDB(dst, b, h) do { _Pragma("unroll") for (int n = 0; n < 2; ++n) _Pragma("unroll") for (int k = 0; k < 2; ++k) dst[n][k] = *(const LAS bf16x8*)(lds + PG8_SB(b, h) + boff + n * 2048 + k * 1024); } while (0)
; #define PG8_MMA(ai, bj, At, Bt) do { __builtin_amdgcn_s_setprio(1); _Pragma("unroll") for (int m = 0; m < 4; ++m) _Pragma("unroll") for (int n = 0; n < 2; ++n) _Pragma("unroll") for (int k = 0; k < 2; ++k) \
;         acc[ai][bj][m][n] = __builtin_amdgcn_mfma_f32_16x16x32_bf16(Bt[n][k], At[m][k], acc[ai][bj][m][n], 0, 0, 0); __builtin_amdgcn_s_setprio(0); } while (0)
; #define PG8_WAIT_V(n) asm volatile("s_waitcnt vmcnt(" #n ")" ::: "memory")
; #define PG8_WAIT_L(n) asm volatile("s_waitcnt lgkmcnt(" #n ")" ::: "memory")
; #define PG8_BAR __builtin_amdgcn_s_barrier()
; #define PG8_SCHED __builtin_amdgcn_sched_barrier(0)
; template <class Epi, bool SP2 = false>
; __device__ __forceinline__ void gemm_phase(LAS unsigned char* lds, const Gemm g, const StaticOrder& S, const Epi& E) {
;     ...
;             PG8_WAIT_V(8); PG8_WAIT_L(0); PG8_BAR; PG8_MMA(0, 0, At, B0); PG8_MMA(0, 1, At, B1); PG8_BAR; PG8_SCHED;
;             PG8_LDA(At, 0, 1); PG8_STAGE(PG8_SB(0, 0), b2, voffB); PG8_STAGE(PG8_SB(0, 1), b2 + hstepB, voffB); PG8_STAGE(PG8_SA(0, 0), a2, voffA);
;             PG8_WAIT_V(8); PG8_WAIT_L(0); PG8_BAR; PG8_MMA(1, 0, At, B0); PG8_MMA(1, 1, At, B1); PG8_BAR; PG8_SCHED;
;             PG8_LDB(B0, 1, 0); PG8_LDB(B1, 1, 1); PG8_SCHED; PG8_LDA(At, 1, 0); PG8_STAGE(PG8_SA(0, 1), a2 + hstepA, voffA);
;             PG8_WAIT_V(8); PG8_WAIT_L(0); PG8_BAR; PG8_MMA(0, 0, At, B0); PG8_MMA(0, 1, At, B1); PG8_BAR; PG8_SCHED;
	v_mfma_f32_16x16x32_bf16 v[60:63], v[152:155], v[184:187], v[60:63]
	v_mfma_f32_16x16x32_bf16 v[56:59], v[160:163], v[184:187], v[56:59]
	v_mfma_f32_16x16x32_bf16 v[44:47], v[152:155], v[192:195], v[44:47]
	v_mfma_f32_16x16x32_bf16 v[40:43], v[160:163], v[192:195], v[40:43]
	v_mfma_f32_16x16x32_bf16 v[28:31], v[152:155], v[200:203], v[28:31]
	v_mfma_f32_16x16x32_bf16 v[24:27], v[160:163], v[200:203], v[24:27]
	v_mfma_f32_16x16x32_bf16 v[12:15], v[152:155], v[208:211], v[12:15]
	v_mfma_f32_16x16x32_bf16 v[8:11], v[160:163], v[208:211], v[8:11]
	v_mfma_f32_16x16x32_bf16 v[60:63], v[156:159], v[188:191], v[60:63]
	v_mfma_f32_16x16x32_bf16 v[56:59], v[164:167], v[188:191], v[56:59]
	v_mfma_f32_16x16x32_bf16 v[44:47], v[156:159], v[196:199], v[44:47]
	v_mfma_f32_16x16x32_bf16 v[40:43], v[164:167], v[196:199], v[40:43]
	v_mfma_f32_16x16x32_bf16 v[28:31], v[156:159], v[204:207], v[28:31]
	v_mfma_f32_16x16x32_bf16 v[24:27], v[164:167], v[204:207], v[24:27]
	v_mfma_f32_16x16x32_bf16 v[12:15], v[156:159], v[212:215], v[12:15]
	v_mfma_f32_16x16x32_bf16 v[8:11], v[164:167], v[212:215], v[8:11]
	v_mfma_f32_16x16x32_bf16 v[52:55], v[168:171], v[184:187], v[52:55]
	v_mfma_f32_16x16x32_bf16 v[48:51], v[176:179], v[184:187], v[48:51]
	v_mfma_f32_16x16x32_bf16 v[36:39], v[168:171], v[192:195], v[36:39]
	v_mfma_f32_16x16x32_bf16 v[32:35], v[176:179], v[192:195], v[32:35]
	v_mfma_f32_16x16x32_bf16 v[20:23], v[168:171], v[200:203], v[20:23]
	v_mfma_f32_16x16x32_bf16 v[16:19], v[176:179], v[200:203], v[16:19]
	v_mfma_f32_16x16x32_bf16 v[4:7], v[168:171], v[208:211], v[4:7]
	v_mfma_f32_16x16x32_bf16 v[0:3], v[176:179], v[208:211], v[0:3]
	v_mfma_f32_16x16x32_bf16 v[52:55], v[172:175], v[188:191], v[52:55]
	v_mfma_f32_16x16x32_bf16 v[48:51], v[180:183], v[188:191], v[48:51]
	v_mfma_f32_16x16x32_bf16 v[36:39], v[172:175], v[196:199], v[36:39]
	v_mfma_f32_16x16x32_bf16 v[32:35], v[180:183], v[196:199], v[32:35]
	v_mfma_f32_16x16x32_bf16 v[20:23], v[172:175], v[204:207], v[20:23]
	v_mfma_f32_16x16x32_bf16 v[16:19], v[180:183], v[204:207], v[16:19]
	v_mfma_f32_16x16x32_bf16 v[4:7], v[172:175], v[212:215], v[4:7]
	v_mfma_f32_16x16x32_bf16 v[0:3], v[180:183], v[212:215], v[0:3]
	s_barrier
	s_add_i32 s68, 0, 0x18000
	s_add_i32 s69, 0, 0x1c000
	v_add_u32_e32 v164, s68, v148
	v_add_u32_e32 v180, s69, v148
	ds_read_b128 v[152:155], v164
	ds_read_b128 v[156:159], v164 offset:1024
	ds_read_b128 v[160:163], v164 offset:2048
	ds_read_b128 v[164:167], v164 offset:3072
	ds_read_b128 v[168:171], v180
	ds_read_b128 v[172:175], v180 offset:1024
	ds_read_b128 v[176:179], v180 offset:2048
	ds_read_b128 v[180:183], v180 offset:3072
	s_add_u32 s50, s50, 0x40000
	s_addc_u32 s51, s51, 0
	s_mov_b32 m0, s55
	v_lshl_add_u64 v[222:223], s[50:51], 0, v[136:137]
	ds_read_b128 v[184:187], v151 offset:32768
	ds_read_b128 v[188:191], v151 offset:33792
	ds_read_b128 v[192:195], v151 offset:34816
	ds_read_b128 v[196:199], v151 offset:35840
	ds_read_b128 v[200:203], v151 offset:36864
	ds_read_b128 v[204:207], v151 offset:37888
	ds_read_b128 v[208:211], v151 offset:38912
	ds_read_b128 v[212:215], v151 offset:39936
	global_load_lds_dwordx4 v[222:223], off
	v_lshl_add_u64 v[222:223], s[50:51], 0, v[132:133]
	s_mov_b32 m0, s56
	s_nop 0
	global_load_lds_dwordx4 v[222:223], off
	s_waitcnt vmcnt(8) lgkmcnt(0)
	s_barrier
	v_mfma_f32_16x16x32_bf16 v[124:127], v[152:155], v[184:187], v[124:127]
	v_mfma_f32_16x16x32_bf16 v[120:123], v[160:163], v[184:187], v[120:123]
	v_mfma_f32_16x16x32_bf16 v[108:111], v[152:155], v[192:195], v[108:111]
	v_mfma_f32_16x16x32_bf16 v[104:107], v[160:163], v[192:195], v[104:107]
	v_mfma_f32_16x16x32_bf16 v[92:95], v[152:155], v[200:203], v[92:95]
	v_mfma_f32_16x16x32_bf16 v[88:91], v[160:163], v[200:203], v[88:91]
	v_mfma_f32_16x16x32_bf16 v[76:79], v[152:155], v[208:211], v[76:79]
	v_mfma_f32_16x16x32_bf16 v[72:75], v[160:163], v[208:211], v[72:75]
	v_mfma_f32_16x16x32_bf16 v[124:127], v[156:159], v[188:191], v[124:127]
	v_mfma_f32_16x16x32_bf16 v[120:123], v[164:167], v[188:191], v[120:123]
	v_mfma_f32_16x16x32_bf16 v[108:111], v[156:159], v[196:199], v[108:111]
	v_mfma_f32_16x16x32_bf16 v[104:107], v[164:167], v[196:199], v[104:107]
	v_mfma_f32_16x16x32_bf16 v[92:95], v[156:159], v[204:207], v[92:95]
	v_mfma_f32_16x16x32_bf16 v[88:91], v[164:167], v[204:207], v[88:91]
	v_mfma_f32_16x16x32_bf16 v[76:79], v[156:159], v[212:215], v[76:79]
	v_mfma_f32_16x16x32_bf16 v[72:75], v[164:167], v[212:215], v[72:75]
	v_mfma_f32_16x16x32_bf16 v[116:119], v[168:171], v[184:187], v[116:119]
	v_mfma_f32_16x16x32_bf16 v[112:115], v[176:179], v[184:187], v[112:115]
	v_mfma_f32_16x16x32_bf16 v[100:103], v[168:171], v[192:195], v[100:103]
	v_mfma_f32_16x16x32_bf16 v[96:99], v[176:179], v[192:195], v[96:99]
	v_mfma_f32_16x16x32_bf16 v[84:87], v[168:171], v[200:203], v[84:87]
	v_mfma_f32_16x16x32_bf16 v[80:83], v[176:179], v[200:203], v[80:83]
	v_mfma_f32_16x16x32_bf16 v[68:71], v[168:171], v[208:211], v[68:71]
	v_mfma_f32_16x16x32_bf16 v[64:67], v[176:179], v[208:211], v[64:67]
	v_mfma_f32_16x16x32_bf16 v[116:119], v[172:175], v[188:191], v[116:119]
	v_mfma_f32_16x16x32_bf16 v[112:115], v[180:183], v[188:191], v[112:115]
	v_mfma_f32_16x16x32_bf16 v[100:103], v[172:175], v[196:199], v[100:103]
	v_mfma_f32_16x16x32_bf16 v[96:99], v[180:183], v[196:199], v[96:99]
	v_mfma_f32_16x16x32_bf16 v[84:87], v[172:175], v[204:207], v[84:87]
	v_mfma_f32_16x16x32_bf16 v[80:83], v[180:183], v[204:207], v[80:83]
	v_mfma_f32_16x16x32_bf16 v[68:71], v[172:175], v[212:215], v[68:71]
	v_mfma_f32_16x16x32_bf16 v[64:67], v[180:183], v[212:215], v[64:67]
	s_barrier
; #define PG8_STAGE(bufoff, gbase, voff) do { _Pragma("unroll") for (int _i = 0; _i < 2; ++_i) \
;         __builtin_amdgcn_global_load_lds((const unsigned*)((const char*)(gbase) + (voff)[_i]), (LAS unsigned*)(lds + (bufoff) + ldsw + _i * 8192), 16, 0, 0); } while (0)
; #define PG8_LDA(dst, b, h) do { _Pragma("unroll") for (int m = 0; m < 4; ++m) _Pragma("unroll") for (int k = 0; k < 2; ++k) dst[m][k] = *(const LAS bf16x8*)(lds + PG8_SA(b, h) + aoff + m * 2048 + k * 1024); } while (0)
; #define PG8_MMA(ai, bj, At, Bt) do { __builtin_amdgcn_s_setprio(1); _Pragma("unroll") for (int m = 0; m < 4; ++m) _Pragma("unroll") for (int n = 0; n < 2; ++n) _Pragma("unroll") for (int k = 0; k < 2; ++k) \
;         acc[ai][bj][m][n] = __builtin_amdgcn_mfma_f32_16x16x32_bf16(Bt[n][k], At[m][k], acc[ai][bj][m][n], 0, 0, 0); __builtin_amdgcn_s_setprio(0); } while (0)
; #define PG8_WAIT_V(n) asm volatile("s_waitcnt vmcnt(" #n ")" ::: "memory")
; #define PG8_WAIT_L(n) asm volatile("s_waitcnt lgkmcnt(" #n ")" ::: "memory")
; #define PG8_BAR __builtin_amdgcn_s_barrier()
; #define PG8_SCHED __builtin_amdgcn_sched_barrier(0)
; template <class Epi, bool SP2 = false>
; __device__ __forceinline__ void gemm_phase(LAS unsigned char* lds, const Gemm g, const StaticOrder& S, const Epi& E) {
;     ...
;             PG8_LDA(At, 1, 1); PG8_STAGE(PG8_SB(1, 0), b3, voffB); PG8_STAGE(PG8_SB(1, 1), b3 + hstepB, voffB); PG8_STAGE(PG8_SA(1, 0), a3, voffA);
;             PG8_WAIT_V(8); PG8_WAIT_L(0); PG8_BAR; PG8_MMA(1, 0, At, B0); PG8_MMA(1, 1, At, B1); PG8_BAR; PG8_SCHED;
	s_add_i32 s50, s68, s3
	v_lshl_add_u64 v[146:147], v[146:147], 0, s[12:13]
	s_mov_b32 m0, s50
	ds_read_b128 v[184:187], v151 offset:49152
	ds_read_b128 v[188:191], v151 offset:50176
	ds_read_b128 v[192:195], v151 offset:51200
	ds_read_b128 v[196:199], v151 offset:52224
	ds_read_b128 v[200:203], v151 offset:53248
	ds_read_b128 v[204:207], v151 offset:54272
	ds_read_b128 v[208:211], v151 offset:55296
	ds_read_b128 v[212:215], v151 offset:56320
	global_load_lds_dwordx4 v[146:147], off
	s_add_i32 m0, s50, 0x2000
	s_add_u32 s44, s44, 0x40080
	v_lshl_add_u64 v[146:147], v[216:217], 0, s[12:13]
	s_addc_u32 s45, s45, 0
	s_add_i32 s50, s69, s3
	global_load_lds_dwordx4 v[146:147], off
	v_lshl_add_u64 v[146:147], s[44:45], 0, v[134:135]
	s_mov_b32 m0, s50
	s_nop 0
	global_load_lds_dwordx4 v[146:147], off
	v_lshl_add_u64 v[146:147], s[44:45], 0, v[130:131]
	s_add_i32 m0, s50, 0x2000
	s_nop 0
	global_load_lds_dwordx4 v[146:147], off
	v_lshl_add_u64 v[146:147], v[218:219], 0, s[12:13]
	s_mov_b32 m0, s60
	s_nop 0
	global_load_lds_dwordx4 v[146:147], off
	v_lshl_add_u64 v[146:147], v[220:221], 0, s[12:13]
	s_mov_b32 m0, s61
	s_nop 0
	global_load_lds_dwordx4 v[146:147], off
	s_waitcnt vmcnt(8) lgkmcnt(0)
	s_barrier
	v_mfma_f32_16x16x32_bf16 v[60:63], v[152:155], v[184:187], v[60:63]
	v_mfma_f32_16x16x32_bf16 v[56:59], v[160:163], v[184:187], v[56:59]
	v_mfma_f32_16x16x32_bf16 v[44:47], v[152:155], v[192:195], v[44:47]
	v_mfma_f32_16x16x32_bf16 v[40:43], v[160:163], v[192:195], v[40:43]
	v_mfma_f32_16x16x32_bf16 v[28:31], v[152:155], v[200:203], v[28:31]
	v_mfma_f32_16x16x32_bf16 v[24:27], v[160:163], v[200:203], v[24:27]
	v_mfma_f32_16x16x32_bf16 v[12:15], v[152:155], v[208:211], v[12:15]
	v_mfma_f32_16x16x32_bf16 v[8:11], v[160:163], v[208:211], v[8:11]
	v_mfma_f32_16x16x32_bf16 v[60:63], v[156:159], v[188:191], v[60:63]
	v_mfma_f32_16x16x32_bf16 v[56:59], v[164:167], v[188:191], v[56:59]
	v_mfma_f32_16x16x32_bf16 v[44:47], v[156:159], v[196:199], v[44:47]
	v_mfma_f32_16x16x32_bf16 v[40:43], v[164:167], v[196:199], v[40:43]
	v_mfma_f32_16x16x32_bf16 v[28:31], v[156:159], v[204:207], v[28:31]
	v_mfma_f32_16x16x32_bf16 v[24:27], v[164:167], v[204:207], v[24:27]
	v_mfma_f32_16x16x32_bf16 v[12:15], v[156:159], v[212:215], v[12:15]
	v_mfma_f32_16x16x32_bf16 v[8:11], v[164:167], v[212:215], v[8:11]
	v_mfma_f32_16x16x32_bf16 v[52:55], v[168:171], v[184:187], v[52:55]
	v_mfma_f32_16x16x32_bf16 v[48:51], v[176:179], v[184:187], v[48:51]
	v_mfma_f32_16x16x32_bf16 v[36:39], v[168:171], v[192:195], v[36:39]
	v_mfma_f32_16x16x32_bf16 v[32:35], v[176:179], v[192:195], v[32:35]
	v_mfma_f32_16x16x32_bf16 v[20:23], v[168:171], v[200:203], v[20:23]
	v_mfma_f32_16x16x32_bf16 v[16:19], v[176:179], v[200:203], v[16:19]
	v_mfma_f32_16x16x32_bf16 v[4:7], v[168:171], v[208:211], v[4:7]
	v_mfma_f32_16x16x32_bf16 v[0:3], v[176:179], v[208:211], v[0:3]
	v_mfma_f32_16x16x32_bf16 v[52:55], v[172:175], v[188:191], v[52:55]
	v_mfma_f32_16x16x32_bf16 v[48:51], v[180:183], v[188:191], v[48:51]
	v_mfma_f32_16x16x32_bf16 v[36:39], v[172:175], v[196:199], v[36:39]
	v_mfma_f32_16x16x32_bf16 v[32:35], v[180:183], v[196:199], v[32:35]
	v_mfma_f32_16x16x32_bf16 v[20:23], v[172:175], v[204:207], v[20:23]
	v_mfma_f32_16x16x32_bf16 v[16:19], v[180:183], v[204:207], v[16:19]
	v_mfma_f32_16x16x32_bf16 v[4:7], v[172:175], v[212:215], v[4:7]
	v_mfma_f32_16x16x32_bf16 v[0:3], v[180:183], v[212:215], v[0:3]
	s_barrier
	s_add_i32 s75, s75, 2
	s_add_u32 s34, s34, 0x100
	s_addc_u32 s35, s35, 0
	s_add_u32 s73, s73, 0x100
	s_addc_u32 s74, s74, 0
	s_cmp_gt_u32 s75, 13
	s_cbranch_scc0 .LBB0_263
	s_and_b64 vcc, exec, s[18:19]
	s_cbranch_vccz .LBB0_266
	s_barrier

; #define PG8_STAGE(bufoff, gbase, voff) do { _Pragma("unroll") for (int _i = 0; _i < 2; ++_i) \
;         __builtin_amdgcn_global_load_lds((const unsigned*)((const char*)(gbase) + (voff)[_i]), (LAS unsigned*)(lds + (bufoff) + ldsw + _i * 8192), 16, 0, 0); } while (0)
; #define PG8_LDA(dst, b, h) do { _Pragma("unroll") for (int m = 0; m < 4; ++m) _Pragma("unroll") for (int k = 0; k < 2; ++k) dst[m][k] = *(const LAS bf16x8*)(lds + PG8_SA(b, h) + aoff + m * 2048 + k * 1024); } while (0)
; #define PG8_LDB(dst, b, h) do { _Pragma("unroll") for (int n = 0; n < 2; ++n) _Pragma("unroll") for (int k = 0; k < 2; ++k) dst[n][k] = *(const LAS bf16x8*)(lds + PG8_SB(b, h) + boff + n * 2048 + k * 1024); } while (0)
; #define PG8_MMA(ai, bj, At, Bt) do { __builtin_amdgcn_s_setprio(1); _Pragma("unroll") for (int m = 0; m < 4; ++m) _Pragma("unroll") for (int n = 0; n < 2; ++n) _Pragma("unroll") for (int k = 0; k < 2; ++k) \
;         acc[ai][bj][m][n] = __builtin_amdgcn_mfma_f32_16x16x32_bf16(Bt[n][k], At[m][k], acc[ai][bj][m][n], 0, 0, 0); __builtin_amdgcn_s_setprio(0); } while (0)
; template <class Epi, bool SP2 = false>
; __device__ __forceinline__ void gemm_phase(LAS unsigned char* lds, const Gemm g, const StaticOrder& S, const Epi& E) {
;     ...
;         const bool has_next = S.next(ui + 1, nxt);
;         const char* nA = has_next ? (const char*)g.A + (size_t)nxt.pm * tstepA : cA; const char* nB = has_next ? (const char*)g.Bt + (size_t)nxt.pn * tstepB : cB;
;         for (int t = 0; t < nt; t += 2) {
;             const bool last = (t == nt - 2);
;             const char* a1 = cA + (size_t)(t + 1) * kstep;
;             const char* a2 = last ? nA : cA + (size_t)(t + 2) * kstep; const char* b2 = last ? nB : cB + (size_t)(t + 2) * kstep;
;             const char* a3 = a2 + kstep; const char* b3 = b2 + kstep;
;             if constexpr (SP2) {
;             PG8_LDB(B0, 0, 0); PG8_LDB(B1, 0, 1); PG8_SCHED; PG8_LDA(At, 0, 0); PG8_STAGE(PG8_SA(1, 1), a1 + hstepA, voffA);
;             PG8_WAIT_V(8); PG8_WAIT_L(0); PG8_BAR; PG8_MMA(0, 0, At, B0); PG8_MMA(0, 1, At, B1); PG8_BAR; PG8_SCHED;
;             PG8_LDA(At, 0, 1); PG8_STAGE(PG8_SB(0, 0), b2, voffB); PG8_STAGE(PG8_SB(0, 1), b2 + hstepB, voffB); PG8_STAGE(PG8_SA(0, 0), a2, voffA);
;             PG8_WAIT_V(8); PG8_WAIT_L(0); PG8_BAR; PG8_MMA(1, 0, At, B0); PG8_MMA(1, 1, At, B1); PG8_BAR; PG8_SCHED;
.LBB0_334:
	ds_read_b128 v[150:153], v147
	ds_read_b128 v[154:157], v147 offset:1024
	ds_read_b128 v[158:161], v147 offset:2048
	ds_read_b128 v[162:165], v147 offset:3072
	ds_read_b128 v[166:169], v148
	ds_read_b128 v[170:173], v148 offset:1024
	ds_read_b128 v[174:177], v148 offset:2048
	ds_read_b128 v[178:181], v148 offset:3072
	s_add_u32 s52, s34, 0xfff50080
	s_addc_u32 s53, s35, -1
	s_cmp_eq_u32 s86, 40
	s_cselect_b32 s55, s5, s53
	s_cselect_b32 s54, s4, s52
	s_cselect_b32 s53, s51, s85
	s_cselect_b32 s52, s50, s84
	v_lshl_add_u64 v[214:215], s[34:35], 0, v[138:139]
	s_add_i32 m0, s59, 0xc000
	ds_read_b128 v[182:185], v149
	ds_read_b128 v[186:189], v149 offset:1024
	ds_read_b128 v[190:193], v149 offset:2048
	ds_read_b128 v[194:197], v149 offset:3072
	ds_read_b128 v[198:201], v149 offset:4096
	ds_read_b128 v[202:205], v149 offset:5120
	ds_read_b128 v[206:209], v149 offset:6144
	ds_read_b128 v[210:213], v149 offset:7168
	global_load_lds_dwordx4 v[214:215], off
	v_lshl_add_u64 v[214:215], s[34:35], 0, v[140:141]
	s_add_i32 m0, s59, 0xe000
	s_nop 0
	global_load_lds_dwordx4 v[214:215], off
	s_waitcnt vmcnt(8) lgkmcnt(0)
	s_barrier
	v_mfma_f32_16x16x32_bf16 v[124:127], v[150:153], v[182:185], v[124:127]
	v_mfma_f32_16x16x32_bf16 v[120:123], v[158:161], v[182:185], v[120:123]
	v_mfma_f32_16x16x32_bf16 v[116:119], v[150:153], v[190:193], v[116:119]
	v_mfma_f32_16x16x32_bf16 v[112:115], v[158:161], v[190:193], v[112:115]
	v_mfma_f32_16x16x32_bf16 v[100:103], v[150:153], v[198:201], v[100:103]
	v_mfma_f32_16x16x32_bf16 v[96:99], v[158:161], v[198:201], v[96:99]
	v_mfma_f32_16x16x32_bf16 v[84:87], v[150:153], v[206:209], v[84:87]
	v_mfma_f32_16x16x32_bf16 v[80:83], v[158:161], v[206:209], v[80:83]
	v_mfma_f32_16x16x32_bf16 v[124:127], v[154:157], v[186:189], v[124:127]
	v_mfma_f32_16x16x32_bf16 v[120:123], v[162:165], v[186:189], v[120:123]
	v_mfma_f32_16x16x32_bf16 v[116:119], v[154:157], v[194:197], v[116:119]
	v_mfma_f32_16x16x32_bf16 v[112:115], v[162:165], v[194:197], v[112:115]
	v_mfma_f32_16x16x32_bf16 v[100:103], v[154:157], v[202:205], v[100:103]
	v_mfma_f32_16x16x32_bf16 v[96:99], v[162:165], v[202:205], v[96:99]
	v_mfma_f32_16x16x32_bf16 v[84:87], v[154:157], v[210:213], v[84:87]
	v_mfma_f32_16x16x32_bf16 v[80:83], v[162:165], v[210:213], v[80:83]
	v_mfma_f32_16x16x32_bf16 v[108:111], v[166:169], v[182:185], v[108:111]
	v_mfma_f32_16x16x32_bf16 v[104:107], v[174:177], v[182:185], v[104:107]
	v_mfma_f32_16x16x32_bf16 v[92:95], v[166:169], v[190:193], v[92:95]
	v_mfma_f32_16x16x32_bf16 v[88:91], v[174:177], v[190:193], v[88:91]
	v_mfma_f32_16x16x32_bf16 v[76:79], v[166:169], v[198:201], v[76:79]
	v_mfma_f32_16x16x32_bf16 v[72:75], v[174:177], v[198:201], v[72:75]
	v_mfma_f32_16x16x32_bf16 v[68:71], v[166:169], v[206:209], v[68:71]
	v_mfma_f32_16x16x32_bf16 v[64:67], v[174:177], v[206:209], v[64:67]
	v_mfma_f32_16x16x32_bf16 v[108:111], v[170:173], v[186:189], v[108:111]
	v_mfma_f32_16x16x32_bf16 v[104:107], v[178:181], v[186:189], v[104:107]
	v_mfma_f32_16x16x32_bf16 v[92:95], v[170:173], v[194:197], v[92:95]
	v_mfma_f32_16x16x32_bf16 v[88:91], v[178:181], v[194:197], v[88:91]
	v_mfma_f32_16x16x32_bf16 v[76:79], v[170:173], v[202:205], v[76:79]
	v_mfma_f32_16x16x32_bf16 v[72:75], v[178:181], v[202:205], v[72:75]
	v_mfma_f32_16x16x32_bf16 v[68:71], v[170:173], v[210:213], v[68:71]
	v_mfma_f32_16x16x32_bf16 v[64:67], v[178:181], v[210:213], v[64:67]
	s_barrier
	s_add_i32 s68, s74, s56
	v_lshl_add_u64 v[214:215], s[52:53], 0, v[134:135]
	s_mov_b32 m0, s68
	ds_read_b128 v[182:185], v149 offset:16384
	ds_read_b128 v[186:189], v149 offset:17408
	ds_read_b128 v[190:193], v149 offset:18432
	ds_read_b128 v[194:197], v149 offset:19456
	ds_read_b128 v[198:201], v149 offset:20480
	ds_read_b128 v[202:205], v149 offset:21504
	ds_read_b128 v[206:209], v149 offset:22528
	ds_read_b128 v[210:213], v149 offset:23552
	global_load_lds_dwordx4 v[214:215], off
	s_add_i32 m0, s68, 0x2000
	s_add_u32 s68, s52, 0xb0000
	v_lshl_add_u64 v[216:217], s[52:53], 0, v[130:131]
	s_addc_u32 s69, s53, 0
	s_add_i32 s70, s75, s56
	global_load_lds_dwordx4 v[216:217], off
	v_lshl_add_u64 v[218:219], s[68:69], 0, v[134:135]
	s_mov_b32 m0, s70
	v_lshl_add_u64 v[220:221], s[54:55], 0, v[132:133]
	global_load_lds_dwordx4 v[218:219], off
	v_lshl_add_u64 v[218:219], s[68:69], 0, v[130:131]
	s_add_i32 m0, s70, 0x2000
	s_nop 0
	global_load_lds_dwordx4 v[218:219], off
	v_lshl_add_u64 v[218:219], s[54:55], 0, v[136:137]
	s_mov_b32 m0, s59
	s_nop 0
	global_load_lds_dwordx4 v[218:219], off
	s_mov_b32 m0, s60
	s_nop 0
	global_load_lds_dwordx4 v[220:221], off
	s_waitcnt vmcnt(8) lgkmcnt(0)
	s_barrier
; #define PG8_STAGE(bufoff, gbase, voff) do { _Pragma("unroll") for (int _i = 0; _i < 2; ++_i) \
;         __builtin_amdgcn_global_load_lds((const unsigned*)((const char*)(gbase) + (voff)[_i]), (LAS unsigned*)(lds + (bufoff) + ldsw + _i * 8192), 16, 0, 0); } while (0)
; #define PG8_LDA(dst, b, h) do { _Pragma("unroll") for (int m = 0; m < 4; ++m) _Pragma("unroll") for (int k = 0; k < 2; ++k) dst[m][k] = *(const LAS bf16x8*)(lds + PG8_SA(b, h) + aoff + m * 2048 + k * 1024); } while (0)
; #define PG8_LDB(dst, b, h) do { _Pragma("unroll") for (int n = 0; n < 2; ++n) _Pragma("unroll") for (int k = 0; k < 2; ++k) dst[n][k] = *(const LAS bf16x8*)(lds + PG8_SB(b, h) + boff + n * 2048 + k * 1024); } while (0)
; #define PG8_MMA(ai, bj, At, Bt) do { __builtin_amdgcn_s_setprio(1); _Pragma("unroll") for (int m = 0; m < 4; ++m) _Pragma("unroll") for (int n = 0; n < 2; ++n) _Pragma("unroll") for (int k = 0; k < 2; ++k) \
;         acc[ai][bj][m][n] = __builtin_amdgcn_mfma_f32_16x16x32_bf16(Bt[n][k], At[m][k], acc[ai][bj][m][n], 0, 0, 0); __builtin_amdgcn_s_setprio(0); } while (0)
; #define PG8_WAIT_V(n) asm volatile("s_waitcnt vmcnt(" #n ")" ::: "memory")
; #define PG8_WAIT_L(n) asm volatile("s_waitcnt lgkmcnt(" #n ")" ::: "memory")
; #define PG8_BAR __builtin_amdgcn_s_barrier()
; #define PG8_SCHED __builtin_amdgcn_sched_barrier(0)
; template <class Epi, bool SP2 = false>
; __device__ __forceinline__ void gemm_phase(LAS unsigned char* lds, const Gemm g, const StaticOrder& S, const Epi& E) {
;     ...
;             PG8_WAIT_V(8); PG8_WAIT_L(0); PG8_BAR; PG8_MMA(0, 0, At, B0); PG8_MMA(0, 1, At, B1); PG8_BAR; PG8_SCHED;
;             PG8_LDA(At, 0, 1); PG8_STAGE(PG8_SB(0, 0), b2, voffB); PG8_STAGE(PG8_SB(0, 1), b2 + hstepB, voffB); PG8_STAGE(PG8_SA(0, 0), a2, voffA);
;             PG8_WAIT_V(8); PG8_WAIT_L(0); PG8_BAR; PG8_MMA(1, 0, At, B0); PG8_MMA(1, 1, At, B1); PG8_BAR; PG8_SCHED;
;             PG8_LDB(B0, 1, 0); PG8_LDB(B1, 1, 1); PG8_SCHED; PG8_LDA(At, 1, 0); PG8_STAGE(PG8_SA(0, 1), a2 + hstepA, voffA);
;             PG8_WAIT_V(8); PG8_WAIT_L(0); PG8_BAR; PG8_MMA(0, 0, At, B0); PG8_MMA(0, 1, At, B1); PG8_BAR; PG8_SCHED;
	v_mfma_f32_16x16x32_bf16 v[60:63], v[150:153], v[182:185], v[60:63]
	v_mfma_f32_16x16x32_bf16 v[56:59], v[158:161], v[182:185], v[56:59]
	v_mfma_f32_16x16x32_bf16 v[52:55], v[150:153], v[190:193], v[52:55]
	v_mfma_f32_16x16x32_bf16 v[48:51], v[158:161], v[190:193], v[48:51]
	v_mfma_f32_16x16x32_bf16 v[36:39], v[150:153], v[198:201], v[36:39]
	v_mfma_f32_16x16x32_bf16 v[32:35], v[158:161], v[198:201], v[32:35]
	v_mfma_f32_16x16x32_bf16 v[20:23], v[150:153], v[206:209], v[20:23]
	v_mfma_f32_16x16x32_bf16 v[16:19], v[158:161], v[206:209], v[16:19]
	v_mfma_f32_16x16x32_bf16 v[60:63], v[154:157], v[186:189], v[60:63]
	v_mfma_f32_16x16x32_bf16 v[56:59], v[162:165], v[186:189], v[56:59]
	v_mfma_f32_16x16x32_bf16 v[52:55], v[154:157], v[194:197], v[52:55]
	v_mfma_f32_16x16x32_bf16 v[48:51], v[162:165], v[194:197], v[48:51]
	v_mfma_f32_16x16x32_bf16 v[36:39], v[154:157], v[202:205], v[36:39]
	v_mfma_f32_16x16x32_bf16 v[32:35], v[162:165], v[202:205], v[32:35]
	v_mfma_f32_16x16x32_bf16 v[20:23], v[154:157], v[210:213], v[20:23]
	v_mfma_f32_16x16x32_bf16 v[16:19], v[162:165], v[210:213], v[16:19]
	v_mfma_f32_16x16x32_bf16 v[44:47], v[166:169], v[182:185], v[44:47]
	v_mfma_f32_16x16x32_bf16 v[40:43], v[174:177], v[182:185], v[40:43]
	v_mfma_f32_16x16x32_bf16 v[28:31], v[166:169], v[190:193], v[28:31]
	v_mfma_f32_16x16x32_bf16 v[24:27], v[174:177], v[190:193], v[24:27]
	v_mfma_f32_16x16x32_bf16 v[12:15], v[166:169], v[198:201], v[12:15]
	v_mfma_f32_16x16x32_bf16 v[8:11], v[174:177], v[198:201], v[8:11]
	v_mfma_f32_16x16x32_bf16 v[4:7], v[166:169], v[206:209], v[4:7]
	v_mfma_f32_16x16x32_bf16 v[0:3], v[174:177], v[206:209], v[0:3]
	v_mfma_f32_16x16x32_bf16 v[44:47], v[170:173], v[186:189], v[44:47]
	v_mfma_f32_16x16x32_bf16 v[40:43], v[178:181], v[186:189], v[40:43]
	v_mfma_f32_16x16x32_bf16 v[28:31], v[170:173], v[194:197], v[28:31]
	v_mfma_f32_16x16x32_bf16 v[24:27], v[178:181], v[194:197], v[24:27]
	v_mfma_f32_16x16x32_bf16 v[12:15], v[170:173], v[202:205], v[12:15]
	v_mfma_f32_16x16x32_bf16 v[8:11], v[178:181], v[202:205], v[8:11]
	v_mfma_f32_16x16x32_bf16 v[4:7], v[170:173], v[210:213], v[4:7]
	v_mfma_f32_16x16x32_bf16 v[0:3], v[178:181], v[210:213], v[0:3]
	s_barrier
	s_add_i32 s68, 0, 0x18000
	s_add_i32 s69, 0, 0x1c000
	v_add_u32_e32 v162, s68, v146
	v_add_u32_e32 v178, s69, v146
	ds_read_b128 v[150:153], v162
	ds_read_b128 v[154:157], v162 offset:1024
	ds_read_b128 v[158:161], v162 offset:2048
	ds_read_b128 v[162:165], v162 offset:3072
	ds_read_b128 v[166:169], v178
	ds_read_b128 v[170:173], v178 offset:1024
	ds_read_b128 v[174:177], v178 offset:2048
	ds_read_b128 v[178:181], v178 offset:3072
	s_add_u32 s54, s54, 0xb0000
	s_addc_u32 s55, s55, 0
	s_mov_b32 m0, s61
	v_lshl_add_u64 v[222:223], s[54:55], 0, v[136:137]
	ds_read_b128 v[182:185], v149 offset:32768
	ds_read_b128 v[186:189], v149 offset:33792
	ds_read_b128 v[190:193], v149 offset:34816
	ds_read_b128 v[194:197], v149 offset:35840
	ds_read_b128 v[198:201], v149 offset:36864
	ds_read_b128 v[202:205], v149 offset:37888
	ds_read_b128 v[206:209], v149 offset:38912
	ds_read_b128 v[210:213], v149 offset:39936
	global_load_lds_dwordx4 v[222:223], off
	v_lshl_add_u64 v[222:223], s[54:55], 0, v[132:133]
	s_mov_b32 m0, s62
	s_nop 0
	global_load_lds_dwordx4 v[222:223], off
	s_waitcnt vmcnt(8) lgkmcnt(0)
	s_barrier
	v_mfma_f32_16x16x32_bf16 v[124:127], v[150:153], v[182:185], v[124:127]
	v_mfma_f32_16x16x32_bf16 v[120:123], v[158:161], v[182:185], v[120:123]
	v_mfma_f32_16x16x32_bf16 v[116:119], v[150:153], v[190:193], v[116:119]
	v_mfma_f32_16x16x32_bf16 v[112:115], v[158:161], v[190:193], v[112:115]
	v_mfma_f32_16x16x32_bf16 v[100:103], v[150:153], v[198:201], v[100:103]
	v_mfma_f32_16x16x32_bf16 v[96:99], v[158:161], v[198:201], v[96:99]
	v_mfma_f32_16x16x32_bf16 v[84:87], v[150:153], v[206:209], v[84:87]
	v_mfma_f32_16x16x32_bf16 v[80:83], v[158:161], v[206:209], v[80:83]
	v_mfma_f32_16x16x32_bf16 v[124:127], v[154:157], v[186:189], v[124:127]
	v_mfma_f32_16x16x32_bf16 v[120:123], v[162:165], v[186:189], v[120:123]
	v_mfma_f32_16x16x32_bf16 v[116:119], v[154:157], v[194:197], v[116:119]
	v_mfma_f32_16x16x32_bf16 v[112:115], v[162:165], v[194:197], v[112:115]
	v_mfma_f32_16x16x32_bf16 v[100:103], v[154:157], v[202:205], v[100:103]
	v_mfma_f32_16x16x32_bf16 v[96:99], v[162:165], v[202:205], v[96:99]
	v_mfma_f32_16x16x32_bf16 v[84:87], v[154:157], v[210:213], v[84:87]
	v_mfma_f32_16x16x32_bf16 v[80:83], v[162:165], v[210:213], v[80:83]
	v_mfma_f32_16x16x32_bf16 v[108:111], v[166:169], v[182:185], v[108:111]
	v_mfma_f32_16x16x32_bf16 v[104:107], v[174:177], v[182:185], v[104:107]
	v_mfma_f32_16x16x32_bf16 v[92:95], v[166:169], v[190:193], v[92:95]
	v_mfma_f32_16x16x32_bf16 v[88:91], v[174:177], v[190:193], v[88:91]
	v_mfma_f32_16x16x32_bf16 v[76:79], v[166:169], v[198:201], v[76:79]
	v_mfma_f32_16x16x32_bf16 v[72:75], v[174:177], v[198:201], v[72:75]
	v_mfma_f32_16x16x32_bf16 v[68:71], v[166:169], v[206:209], v[68:71]
	v_mfma_f32_16x16x32_bf16 v[64:67], v[174:177], v[206:209], v[64:67]
	v_mfma_f32_16x16x32_bf16 v[108:111], v[170:173], v[186:189], v[108:111]
	v_mfma_f32_16x16x32_bf16 v[104:107], v[178:181], v[186:189], v[104:107]
	v_mfma_f32_16x16x32_bf16 v[92:95], v[170:173], v[194:197], v[92:95]
	v_mfma_f32_16x16x32_bf16 v[88:91], v[178:181], v[194:197], v[88:91]
	v_mfma_f32_16x16x32_bf16 v[76:79], v[170:173], v[202:205], v[76:79]
	v_mfma_f32_16x16x32_bf16 v[72:75], v[178:181], v[202:205], v[72:75]
	v_mfma_f32_16x16x32_bf16 v[68:71], v[170:173], v[210:213], v[68:71]
	v_mfma_f32_16x16x32_bf16 v[64:67], v[178:181], v[210:213], v[64:67]
	s_barrier
; #define PG8_STAGE(bufoff, gbase, voff) do { _Pragma("unroll") for (int _i = 0; _i < 2; ++_i) \
;         __builtin_amdgcn_global_load_lds((const unsigned*)((const char*)(gbase) + (voff)[_i]), (LAS unsigned*)(lds + (bufoff) + ldsw + _i * 8192), 16, 0, 0); } while (0)
; #define PG8_LDA(dst, b, h) do { _Pragma("unroll") for (int m = 0; m < 4; ++m) _Pragma("unroll") for (int k = 0; k < 2; ++k) dst[m][k] = *(const LAS bf16x8*)(lds + PG8_SA(b, h) + aoff + m * 2048 + k * 1024); } while (0)
; #define PG8_MMA(ai, bj, At, Bt) do { __builtin_amdgcn_s_setprio(1); _Pragma("unroll") for (int m = 0; m < 4; ++m) _Pragma("unroll") for (int n = 0; n < 2; ++n) _Pragma("unroll") for (int k = 0; k < 2; ++k) \
;         acc[ai][bj][m][n] = __builtin_amdgcn_mfma_f32_16x16x32_bf16(Bt[n][k], At[m][k], acc[ai][bj][m][n], 0, 0, 0); __builtin_amdgcn_s_setprio(0); } while (0)
; #define PG8_WAIT_V(n) asm volatile("s_waitcnt vmcnt(" #n ")" ::: "memory")
; #define PG8_WAIT_L(n) asm volatile("s_waitcnt lgkmcnt(" #n ")" ::: "memory")
; #define PG8_BAR __builtin_amdgcn_s_barrier()
; #define PG8_SCHED __builtin_amdgcn_sched_barrier(0)
; template <class Epi, bool SP2 = false>
; __device__ __forceinline__ void gemm_phase(LAS unsigned char* lds, const Gemm g, const StaticOrder& S, const Epi& E) {
;     ...
;             PG8_LDA(At, 1, 1); PG8_STAGE(PG8_SB(1, 0), b3, voffB); PG8_STAGE(PG8_SB(1, 1), b3 + hstepB, voffB); PG8_STAGE(PG8_SA(1, 0), a3, voffA);
;             PG8_WAIT_V(8); PG8_WAIT_L(0); PG8_BAR; PG8_MMA(1, 0, At, B0); PG8_MMA(1, 1, At, B1); PG8_BAR; PG8_SCHED;
	s_add_i32 s54, s68, s56
	v_lshl_add_u64 v[214:215], v[214:215], 0, s[24:25]
	s_mov_b32 m0, s54
	ds_read_b128 v[182:185], v149 offset:49152
	ds_read_b128 v[186:189], v149 offset:50176
	ds_read_b128 v[190:193], v149 offset:51200
	ds_read_b128 v[194:197], v149 offset:52224
	ds_read_b128 v[198:201], v149 offset:53248
	ds_read_b128 v[202:205], v149 offset:54272
	ds_read_b128 v[206:209], v149 offset:55296
	ds_read_b128 v[210:213], v149 offset:56320
	global_load_lds_dwordx4 v[214:215], off
	s_add_i32 m0, s54, 0x2000
	s_add_u32 s52, s52, 0xb0080
	v_lshl_add_u64 v[214:215], v[216:217], 0, s[24:25]
	s_addc_u32 s53, s53, 0
	s_add_i32 s54, s69, s56
	global_load_lds_dwordx4 v[214:215], off
	v_lshl_add_u64 v[214:215], s[52:53], 0, v[134:135]
	s_mov_b32 m0, s54
	s_nop 0
	global_load_lds_dwordx4 v[214:215], off
	v_lshl_add_u64 v[214:215], s[52:53], 0, v[130:131]
	s_add_i32 m0, s54, 0x2000
	s_nop 0
	global_load_lds_dwordx4 v[214:215], off
	v_lshl_add_u64 v[214:215], v[218:219], 0, s[24:25]
	s_mov_b32 m0, s66
	s_nop 0
	global_load_lds_dwordx4 v[214:215], off
	v_lshl_add_u64 v[214:215], v[220:221], 0, s[24:25]
	s_mov_b32 m0, s67
	s_nop 0
	global_load_lds_dwordx4 v[214:215], off
	s_waitcnt vmcnt(8) lgkmcnt(0)
	s_barrier
	v_mfma_f32_16x16x32_bf16 v[60:63], v[150:153], v[182:185], v[60:63]
	v_mfma_f32_16x16x32_bf16 v[56:59], v[158:161], v[182:185], v[56:59]
	v_mfma_f32_16x16x32_bf16 v[52:55], v[150:153], v[190:193], v[52:55]
	v_mfma_f32_16x16x32_bf16 v[48:51], v[158:161], v[190:193], v[48:51]
	v_mfma_f32_16x16x32_bf16 v[36:39], v[150:153], v[198:201], v[36:39]
	v_mfma_f32_16x16x32_bf16 v[32:35], v[158:161], v[198:201], v[32:35]
	v_mfma_f32_16x16x32_bf16 v[20:23], v[150:153], v[206:209], v[20:23]
	v_mfma_f32_16x16x32_bf16 v[16:19], v[158:161], v[206:209], v[16:19]
	v_mfma_f32_16x16x32_bf16 v[60:63], v[154:157], v[186:189], v[60:63]
	v_mfma_f32_16x16x32_bf16 v[56:59], v[162:165], v[186:189], v[56:59]
	v_mfma_f32_16x16x32_bf16 v[52:55], v[154:157], v[194:197], v[52:55]
	v_mfma_f32_16x16x32_bf16 v[48:51], v[162:165], v[194:197], v[48:51]
	v_mfma_f32_16x16x32_bf16 v[36:39], v[154:157], v[202:205], v[36:39]
	v_mfma_f32_16x16x32_bf16 v[32:35], v[162:165], v[202:205], v[32:35]
	v_mfma_f32_16x16x32_bf16 v[20:23], v[154:157], v[210:213], v[20:23]
	v_mfma_f32_16x16x32_bf16 v[16:19], v[162:165], v[210:213], v[16:19]
	v_mfma_f32_16x16x32_bf16 v[44:47], v[166:169], v[182:185], v[44:47]
	v_mfma_f32_16x16x32_bf16 v[40:43], v[174:177], v[182:185], v[40:43]
	v_mfma_f32_16x16x32_bf16 v[28:31], v[166:169], v[190:193], v[28:31]
	v_mfma_f32_16x16x32_bf16 v[24:27], v[174:177], v[190:193], v[24:27]
	v_mfma_f32_16x16x32_bf16 v[12:15], v[166:169], v[198:201], v[12:15]
	v_mfma_f32_16x16x32_bf16 v[8:11], v[174:177], v[198:201], v[8:11]
	v_mfma_f32_16x16x32_bf16 v[4:7], v[166:169], v[206:209], v[4:7]
	v_mfma_f32_16x16x32_bf16 v[0:3], v[174:177], v[206:209], v[0:3]
	v_mfma_f32_16x16x32_bf16 v[44:47], v[170:173], v[186:189], v[44:47]
	v_mfma_f32_16x16x32_bf16 v[40:43], v[178:181], v[186:189], v[40:43]
	v_mfma_f32_16x16x32_bf16 v[28:31], v[170:173], v[194:197], v[28:31]
	v_mfma_f32_16x16x32_bf16 v[24:27], v[178:181], v[194:197], v[24:27]
	v_mfma_f32_16x16x32_bf16 v[12:15], v[170:173], v[202:205], v[12:15]
	v_mfma_f32_16x16x32_bf16 v[8:11], v[178:181], v[202:205], v[8:11]
	v_mfma_f32_16x16x32_bf16 v[4:7], v[170:173], v[210:213], v[4:7]
	v_mfma_f32_16x16x32_bf16 v[0:3], v[178:181], v[210:213], v[0:3]
	s_barrier
	s_add_i32 s86, s86, 2
	s_add_u32 s34, s34, 0x100
	s_addc_u32 s35, s35, 0
	s_add_u32 s84, s84, 0x100
	s_addc_u32 s85, s85, 0
	s_cmp_gt_u32 s86, 41
	s_cbranch_scc0 .LBB0_334
	s_and_b64 vcc, exec, s[26:27]
	s_cbranch_vccz .LBB0_337
	s_barrier

; #define PG8_STAGE(bufoff, gbase, voff) do { _Pragma("unroll") for (int _i = 0; _i < 2; ++_i) \
;         __builtin_amdgcn_global_load_lds((const unsigned*)((const char*)(gbase) + (voff)[_i]), (LAS unsigned*)(lds + (bufoff) + ldsw + _i * 8192), 16, 0, 0); } while (0)
; #define PG8_LDA(dst, b, h) do { _Pragma("unroll") for (int m = 0; m < 4; ++m) _Pragma("unroll") for (int k = 0; k < 2; ++k) dst[m][k] = *(const LAS bf16x8*)(lds + PG8_SA(b, h) + aoff + m * 2048 + k * 1024); } while (0)
; #define PG8_LDB(dst, b, h) do { _Pragma("unroll") for (int n = 0; n < 2; ++n) _Pragma("unroll") for (int k = 0; k < 2; ++k) dst[n][k] = *(const LAS bf16x8*)(lds + PG8_SB(b, h) + boff + n * 2048 + k * 1024); } while (0)
; #define PG8_MMA(ai, bj, At, Bt) do { __builtin_amdgcn_s_setprio(1); _Pragma("unroll") for (int m = 0; m < 4; ++m) _Pragma("unroll") for (int n = 0; n < 2; ++n) _Pragma("unroll") for (int k = 0; k < 2; ++k) \
;         acc[ai][bj][m][n] = __builtin_amdgcn_mfma_f32_16x16x32_bf16(Bt[n][k], At[m][k], acc[ai][bj][m][n], 0, 0, 0); __builtin_amdgcn_s_setprio(0); } while (0)
; #define PG8_WAIT_V(n) asm volatile("s_waitcnt vmcnt(" #n ")" ::: "memory")
; #define PG8_WAIT_L(n) asm volatile("s_waitcnt lgkmcnt(" #n ")" ::: "memory")
; #define PG8_BAR __builtin_amdgcn_s_barrier()
; #define PG8_SCHED __builtin_amdgcn_sched_barrier(0)
; template <class Epi, bool SP2 = false>
; __device__ __forceinline__ void gemm_phase(LAS unsigned char* lds, const Gemm g, const StaticOrder& S, const Epi& E) {
;     ...
;             const bool last = (t == nt - 2);
;             const char* a1 = cA + (size_t)(t + 1) * kstep;
;             const char* a2 = last ? nA : cA + (size_t)(t + 2) * kstep; const char* b2 = last ? nB : cB + (size_t)(t + 2) * kstep;
;             const char* a3 = a2 + kstep; const char* b3 = b2 + kstep;
;             if constexpr (SP2) {
;             PG8_LDB(B0, 0, 0); PG8_LDB(B1, 0, 1); PG8_SCHED; PG8_LDA(At, 0, 0); PG8_STAGE(PG8_SA(1, 1), a1 + hstepA, voffA);
;             PG8_WAIT_V(8); PG8_WAIT_L(0); PG8_BAR; PG8_MMA(0, 0, At, B0); PG8_MMA(0, 1, At, B1); PG8_BAR; PG8_SCHED;
;             PG8_LDA(At, 0, 1); PG8_STAGE(PG8_SB(0, 0), b2, voffB); PG8_STAGE(PG8_SB(0, 1), b2 + hstepB, voffB); PG8_STAGE(PG8_SA(0, 0), a2, voffA);
;             PG8_WAIT_V(8); PG8_WAIT_L(0); PG8_BAR; PG8_MMA(1, 0, At, B0); PG8_MMA(1, 1, At, B1); PG8_BAR; PG8_SCHED;
.LBB0_462:
	ds_read_b128 v[146:149], v153
	ds_read_b128 v[156:159], v153 offset:1024
	ds_read_b128 v[160:163], v153 offset:2048
	ds_read_b128 v[164:167], v153 offset:3072
	ds_read_b128 v[168:171], v154
	ds_read_b128 v[172:175], v154 offset:1024
	ds_read_b128 v[176:179], v154 offset:2048
	ds_read_b128 v[180:183], v154 offset:3072
	s_add_u32 s44, s34, 0xfffc0080
	s_addc_u32 s45, s35, -1
	s_cmp_eq_u32 s74, 12
	s_cselect_b32 s51, s5, s45
	s_cselect_b32 s50, s27, s44
	s_cselect_b32 s45, s25, s73
	s_cselect_b32 s44, s33, s72
	v_lshl_add_u64 v[150:151], s[34:35], 0, v[138:139]
	s_add_i32 m0, s31, 0xc000
	ds_read_b128 v[184:187], v155
	ds_read_b128 v[188:191], v155 offset:1024
	ds_read_b128 v[192:195], v155 offset:2048
	ds_read_b128 v[196:199], v155 offset:3072
	ds_read_b128 v[200:203], v155 offset:4096
	ds_read_b128 v[204:207], v155 offset:5120
	ds_read_b128 v[208:211], v155 offset:6144
	ds_read_b128 v[212:215], v155 offset:7168
	global_load_lds_dwordx4 v[150:151], off
	v_lshl_add_u64 v[150:151], s[34:35], 0, v[140:141]
	s_add_i32 m0, s31, 0xe000
	s_nop 0
	global_load_lds_dwordx4 v[150:151], off
	s_waitcnt vmcnt(8) lgkmcnt(0)
	s_barrier
	v_mfma_f32_16x16x32_bf16 v[124:127], v[146:149], v[184:187], v[124:127]
	v_mfma_f32_16x16x32_bf16 v[120:123], v[160:163], v[184:187], v[120:123]
	v_mfma_f32_16x16x32_bf16 v[108:111], v[146:149], v[192:195], v[108:111]
	v_mfma_f32_16x16x32_bf16 v[104:107], v[160:163], v[192:195], v[104:107]
	v_mfma_f32_16x16x32_bf16 v[92:95], v[146:149], v[200:203], v[92:95]
	v_mfma_f32_16x16x32_bf16 v[88:91], v[160:163], v[200:203], v[88:91]
	v_mfma_f32_16x16x32_bf16 v[76:79], v[146:149], v[208:211], v[76:79]
	v_mfma_f32_16x16x32_bf16 v[72:75], v[160:163], v[208:211], v[72:75]
	v_mfma_f32_16x16x32_bf16 v[124:127], v[156:159], v[188:191], v[124:127]
	v_mfma_f32_16x16x32_bf16 v[120:123], v[164:167], v[188:191], v[120:123]
	v_mfma_f32_16x16x32_bf16 v[108:111], v[156:159], v[196:199], v[108:111]
	v_mfma_f32_16x16x32_bf16 v[104:107], v[164:167], v[196:199], v[104:107]
	v_mfma_f32_16x16x32_bf16 v[92:95], v[156:159], v[204:207], v[92:95]
	v_mfma_f32_16x16x32_bf16 v[88:91], v[164:167], v[204:207], v[88:91]
	v_mfma_f32_16x16x32_bf16 v[76:79], v[156:159], v[212:215], v[76:79]
	v_mfma_f32_16x16x32_bf16 v[72:75], v[164:167], v[212:215], v[72:75]
	v_mfma_f32_16x16x32_bf16 v[116:119], v[168:171], v[184:187], v[116:119]
	v_mfma_f32_16x16x32_bf16 v[112:115], v[176:179], v[184:187], v[112:115]
	v_mfma_f32_16x16x32_bf16 v[100:103], v[168:171], v[192:195], v[100:103]
	v_mfma_f32_16x16x32_bf16 v[96:99], v[176:179], v[192:195], v[96:99]
	v_mfma_f32_16x16x32_bf16 v[84:87], v[168:171], v[200:203], v[84:87]
	v_mfma_f32_16x16x32_bf16 v[80:83], v[176:179], v[200:203], v[80:83]
	v_mfma_f32_16x16x32_bf16 v[68:71], v[168:171], v[208:211], v[68:71]
	v_mfma_f32_16x16x32_bf16 v[64:67], v[176:179], v[208:211], v[64:67]
	v_mfma_f32_16x16x32_bf16 v[116:119], v[172:175], v[188:191], v[116:119]
	v_mfma_f32_16x16x32_bf16 v[112:115], v[180:183], v[188:191], v[112:115]
	v_mfma_f32_16x16x32_bf16 v[100:103], v[172:175], v[196:199], v[100:103]
	v_mfma_f32_16x16x32_bf16 v[96:99], v[180:183], v[196:199], v[96:99]
	v_mfma_f32_16x16x32_bf16 v[84:87], v[172:175], v[204:207], v[84:87]
	v_mfma_f32_16x16x32_bf16 v[80:83], v[180:183], v[204:207], v[80:83]
	v_mfma_f32_16x16x32_bf16 v[68:71], v[172:175], v[212:215], v[68:71]
	v_mfma_f32_16x16x32_bf16 v[64:67], v[180:183], v[212:215], v[64:67]
	s_barrier
	s_add_i32 s68, s66, s53
	v_lshl_add_u64 v[150:151], s[44:45], 0, v[132:133]
	s_mov_b32 m0, s68
	ds_read_b128 v[184:187], v155 offset:16384
	ds_read_b128 v[188:191], v155 offset:17408
	ds_read_b128 v[192:195], v155 offset:18432
	ds_read_b128 v[196:199], v155 offset:19456
	ds_read_b128 v[200:203], v155 offset:20480
	ds_read_b128 v[204:207], v155 offset:21504
	ds_read_b128 v[208:211], v155 offset:22528
	ds_read_b128 v[212:215], v155 offset:23552
	global_load_lds_dwordx4 v[150:151], off
	s_add_i32 m0, s68, 0x2000
	s_add_u32 s68, s44, 0x40000
	v_lshl_add_u64 v[216:217], s[44:45], 0, v[136:137]
	s_addc_u32 s69, s45, 0
	s_add_i32 s70, s67, s53
	global_load_lds_dwordx4 v[216:217], off
	v_lshl_add_u64 v[218:219], s[68:69], 0, v[132:133]
	s_mov_b32 m0, s70
	v_lshl_add_u64 v[220:221], s[50:51], 0, v[134:135]
	global_load_lds_dwordx4 v[218:219], off
	v_lshl_add_u64 v[218:219], s[68:69], 0, v[136:137]
	s_add_i32 m0, s70, 0x2000
	s_nop 0
	global_load_lds_dwordx4 v[218:219], off
	v_lshl_add_u64 v[218:219], s[50:51], 0, v[130:131]
	s_mov_b32 m0, s31
	s_nop 0
	global_load_lds_dwordx4 v[218:219], off
	s_mov_b32 m0, s54
	s_nop 0
	global_load_lds_dwordx4 v[220:221], off
	s_waitcnt vmcnt(8) lgkmcnt(0)
	s_barrier
; #define PG8_STAGE(bufoff, gbase, voff) do { _Pragma("unroll") for (int _i = 0; _i < 2; ++_i) \
;         __builtin_amdgcn_global_load_lds((const unsigned*)((const char*)(gbase) + (voff)[_i]), (LAS unsigned*)(lds + (bufoff) + ldsw + _i * 8192), 16, 0, 0); } while (0)
; #define PG8_LDA(dst, b, h) do { _Pragma("unroll") for (int m = 0; m < 4; ++m) _Pragma("unroll") for (int k = 0; k < 2; ++k) dst[m][k] = *(const LAS bf16x8*)(lds + PG8_SA(b, h) + aoff + m * 2048 + k * 1024); } while (0)
; #define PG8_LDB(dst, b, h) do { _Pragma("unroll") for (int n = 0; n < 2; ++n) _Pragma("unroll") for (int k = 0; k < 2; ++k) dst[n][k] = *(const LAS bf16x8*)(lds + PG8_SB(b, h) + boff + n * 2048 + k * 1024); } while (0)
; #define PG8_MMA(ai, bj, At, Bt) do { __builtin_amdgcn_s_setprio(1); _Pragma("unroll") for (int m = 0; m < 4; ++m) _Pragma("unroll") for (int n = 0; n < 2; ++n) _Pragma("unroll") for (int k = 0; k < 2; ++k) \
;         acc[ai][bj][m][n] = __builtin_amdgcn_mfma_f32_16x16x32_bf16(Bt[n][k], At[m][k], acc[ai][bj][m][n], 0, 0, 0); __builtin_amdgcn_s_setprio(0); } while (0)
; #define PG8_WAIT_V(n) asm volatile("s_waitcnt vmcnt(" #n ")" ::: "memory")
; #define PG8_WAIT_L(n) asm volatile("s_waitcnt lgkmcnt(" #n ")" ::: "memory")
; #define PG8_BAR __builtin_amdgcn_s_barrier()
; #define PG8_SCHED __builtin_amdgcn_sched_barrier(0)
; template <class Epi, bool SP2 = false>
; __device__ __forceinline__ void gemm_phase(LAS unsigned char* lds, const Gemm g, const StaticOrder& S, const Epi& E) {
;     ...
;             PG8_WAIT_V(8); PG8_WAIT_L(0); PG8_BAR; PG8_MMA(1, 0, At, B0); PG8_MMA(1, 1, At, B1); PG8_BAR; PG8_SCHED;
;             PG8_LDB(B0, 1, 0); PG8_LDB(B1, 1, 1); PG8_SCHED; PG8_LDA(At, 1, 0); PG8_STAGE(PG8_SA(0, 1), a2 + hstepA, voffA);
;             PG8_WAIT_V(8); PG8_WAIT_L(0); PG8_BAR; PG8_MMA(0, 0, At, B0); PG8_MMA(0, 1, At, B1); PG8_BAR; PG8_SCHED;
	v_mfma_f32_16x16x32_bf16 v[60:63], v[146:149], v[184:187], v[60:63]
	v_mfma_f32_16x16x32_bf16 v[56:59], v[160:163], v[184:187], v[56:59]
	v_mfma_f32_16x16x32_bf16 v[44:47], v[146:149], v[192:195], v[44:47]
	v_mfma_f32_16x16x32_bf16 v[40:43], v[160:163], v[192:195], v[40:43]
	v_mfma_f32_16x16x32_bf16 v[28:31], v[146:149], v[200:203], v[28:31]
	v_mfma_f32_16x16x32_bf16 v[24:27], v[160:163], v[200:203], v[24:27]
	v_mfma_f32_16x16x32_bf16 v[12:15], v[146:149], v[208:211], v[12:15]
	v_mfma_f32_16x16x32_bf16 v[8:11], v[160:163], v[208:211], v[8:11]
	v_mfma_f32_16x16x32_bf16 v[60:63], v[156:159], v[188:191], v[60:63]
	v_mfma_f32_16x16x32_bf16 v[56:59], v[164:167], v[188:191], v[56:59]
	v_mfma_f32_16x16x32_bf16 v[44:47], v[156:159], v[196:199], v[44:47]
	v_mfma_f32_16x16x32_bf16 v[40:43], v[164:167], v[196:199], v[40:43]
	v_mfma_f32_16x16x32_bf16 v[28:31], v[156:159], v[204:207], v[28:31]
	v_mfma_f32_16x16x32_bf16 v[24:27], v[164:167], v[204:207], v[24:27]
	v_mfma_f32_16x16x32_bf16 v[12:15], v[156:159], v[212:215], v[12:15]
	v_mfma_f32_16x16x32_bf16 v[8:11], v[164:167], v[212:215], v[8:11]
	v_mfma_f32_16x16x32_bf16 v[52:55], v[168:171], v[184:187], v[52:55]
	v_mfma_f32_16x16x32_bf16 v[48:51], v[176:179], v[184:187], v[48:51]
	v_mfma_f32_16x16x32_bf16 v[36:39], v[168:171], v[192:195], v[36:39]
	v_mfma_f32_16x16x32_bf16 v[32:35], v[176:179], v[192:195], v[32:35]
	v_mfma_f32_16x16x32_bf16 v[20:23], v[168:171], v[200:203], v[20:23]
	v_mfma_f32_16x16x32_bf16 v[16:19], v[176:179], v[200:203], v[16:19]
	v_mfma_f32_16x16x32_bf16 v[4:7], v[168:171], v[208:211], v[4:7]
	v_mfma_f32_16x16x32_bf16 v[0:3], v[176:179], v[208:211], v[0:3]
	v_mfma_f32_16x16x32_bf16 v[52:55], v[172:175], v[188:191], v[52:55]
	v_mfma_f32_16x16x32_bf16 v[48:51], v[180:183], v[188:191], v[48:51]
	v_mfma_f32_16x16x32_bf16 v[36:39], v[172:175], v[196:199], v[36:39]
	v_mfma_f32_16x16x32_bf16 v[32:35], v[180:183], v[196:199], v[32:35]
	v_mfma_f32_16x16x32_bf16 v[20:23], v[172:175], v[204:207], v[20:23]
	v_mfma_f32_16x16x32_bf16 v[16:19], v[180:183], v[204:207], v[16:19]
	v_mfma_f32_16x16x32_bf16 v[4:7], v[172:175], v[212:215], v[4:7]
	v_mfma_f32_16x16x32_bf16 v[0:3], v[180:183], v[212:215], v[0:3]
	s_barrier
	s_add_i32 s68, 0, 0x18000
	s_add_i32 s69, 0, 0x1c000
	v_add_u32_e32 v164, s68, v152
	v_add_u32_e32 v180, s69, v152
	ds_read_b128 v[146:149], v164
	ds_read_b128 v[156:159], v164 offset:1024
	ds_read_b128 v[160:163], v164 offset:2048
	ds_read_b128 v[164:167], v164 offset:3072
	ds_read_b128 v[168:171], v180
	ds_read_b128 v[172:175], v180 offset:1024
	ds_read_b128 v[176:179], v180 offset:2048
	ds_read_b128 v[180:183], v180 offset:3072
	s_add_u32 s50, s50, 0x40000
	s_addc_u32 s51, s51, 0
	s_mov_b32 m0, s55
	v_lshl_add_u64 v[222:223], s[50:51], 0, v[130:131]
	ds_read_b128 v[184:187], v155 offset:32768
	ds_read_b128 v[188:191], v155 offset:33792
	ds_read_b128 v[192:195], v155 offset:34816
	ds_read_b128 v[196:199], v155 offset:35840
	ds_read_b128 v[200:203], v155 offset:36864
	ds_read_b128 v[204:207], v155 offset:37888
	ds_read_b128 v[208:211], v155 offset:38912
	ds_read_b128 v[212:215], v155 offset:39936
	global_load_lds_dwordx4 v[222:223], off
	v_lshl_add_u64 v[222:223], s[50:51], 0, v[134:135]
	s_mov_b32 m0, s56
	s_nop 0
	global_load_lds_dwordx4 v[222:223], off
	s_waitcnt vmcnt(8) lgkmcnt(0)
	s_barrier
	v_mfma_f32_16x16x32_bf16 v[124:127], v[146:149], v[184:187], v[124:127]
	v_mfma_f32_16x16x32_bf16 v[120:123], v[160:163], v[184:187], v[120:123]
	v_mfma_f32_16x16x32_bf16 v[108:111], v[146:149], v[192:195], v[108:111]
	v_mfma_f32_16x16x32_bf16 v[104:107], v[160:163], v[192:195], v[104:107]
	v_mfma_f32_16x16x32_bf16 v[92:95], v[146:149], v[200:203], v[92:95]
	v_mfma_f32_16x16x32_bf16 v[88:91], v[160:163], v[200:203], v[88:91]
	v_mfma_f32_16x16x32_bf16 v[76:79], v[146:149], v[208:211], v[76:79]
	v_mfma_f32_16x16x32_bf16 v[72:75], v[160:163], v[208:211], v[72:75]
	v_mfma_f32_16x16x32_bf16 v[124:127], v[156:159], v[188:191], v[124:127]
	v_mfma_f32_16x16x32_bf16 v[120:123], v[164:167], v[188:191], v[120:123]
	v_mfma_f32_16x16x32_bf16 v[108:111], v[156:159], v[196:199], v[108:111]
	v_mfma_f32_16x16x32_bf16 v[104:107], v[164:167], v[196:199], v[104:107]
	v_mfma_f32_16x16x32_bf16 v[92:95], v[156:159], v[204:207], v[92:95]
	v_mfma_f32_16x16x32_bf16 v[88:91], v[164:167], v[204:207], v[88:91]
	v_mfma_f32_16x16x32_bf16 v[76:79], v[156:159], v[212:215], v[76:79]
	v_mfma_f32_16x16x32_bf16 v[72:75], v[164:167], v[212:215], v[72:75]
	v_mfma_f32_16x16x32_bf16 v[116:119], v[168:171], v[184:187], v[116:119]
	v_mfma_f32_16x16x32_bf16 v[112:115], v[176:179], v[184:187], v[112:115]
	v_mfma_f32_16x16x32_bf16 v[100:103], v[168:171], v[192:195], v[100:103]
	v_mfma_f32_16x16x32_bf16 v[96:99], v[176:179], v[192:195], v[96:99]
	v_mfma_f32_16x16x32_bf16 v[84:87], v[168:171], v[200:203], v[84:87]
	v_mfma_f32_16x16x32_bf16 v[80:83], v[176:179], v[200:203], v[80:83]
	v_mfma_f32_16x16x32_bf16 v[68:71], v[168:171], v[208:211], v[68:71]
	v_mfma_f32_16x16x32_bf16 v[64:67], v[176:179], v[208:211], v[64:67]
	v_mfma_f32_16x16x32_bf16 v[116:119], v[172:175], v[188:191], v[116:119]
	v_mfma_f32_16x16x32_bf16 v[112:115], v[180:183], v[188:191], v[112:115]
	v_mfma_f32_16x16x32_bf16 v[100:103], v[172:175], v[196:199], v[100:103]
	v_mfma_f32_16x16x32_bf16 v[96:99], v[180:183], v[196:199], v[96:99]
	v_mfma_f32_16x16x32_bf16 v[84:87], v[172:175], v[204:207], v[84:87]
	v_mfma_f32_16x16x32_bf16 v[80:83], v[180:183], v[204:207], v[80:83]
	v_mfma_f32_16x16x32_bf16 v[68:71], v[172:175], v[212:215], v[68:71]
	v_mfma_f32_16x16x32_bf16 v[64:67], v[180:183], v[212:215], v[64:67]
	s_barrier
; #define PG8_STAGE(bufoff, gbase, voff) do { _Pragma("unroll") for (int _i = 0; _i < 2; ++_i) \
;         __builtin_amdgcn_global_load_lds((const unsigned*)((const char*)(gbase) + (voff)[_i]), (LAS unsigned*)(lds + (bufoff) + ldsw + _i * 8192), 16, 0, 0); } while (0)
; #define PG8_LDA(dst, b, h) do { _Pragma("unroll") for (int m = 0; m < 4; ++m) _Pragma("unroll") for (int k = 0; k < 2; ++k) dst[m][k] = *(const LAS bf16x8*)(lds + PG8_SA(b, h) + aoff + m * 2048 + k * 1024); } while (0)
; #define PG8_MMA(ai, bj, At, Bt) do { __builtin_amdgcn_s_setprio(1); _Pragma("unroll") for (int m = 0; m < 4; ++m) _Pragma("unroll") for (int n = 0; n < 2; ++n) _Pragma("unroll") for (int k = 0; k < 2; ++k) \
;         acc[ai][bj][m][n] = __builtin_amdgcn_mfma_f32_16x16x32_bf16(Bt[n][k], At[m][k], acc[ai][bj][m][n], 0, 0, 0); __builtin_amdgcn_s_setprio(0); } while (0)
; #define PG8_WAIT_V(n) asm volatile("s_waitcnt vmcnt(" #n ")" ::: "memory")
; #define PG8_WAIT_L(n) asm volatile("s_waitcnt lgkmcnt(" #n ")" ::: "memory")
; #define PG8_BAR __builtin_amdgcn_s_barrier()
; #define PG8_SCHED __builtin_amdgcn_sched_barrier(0)
; template <class Epi, bool SP2 = false>
; __device__ __forceinline__ void gemm_phase(LAS unsigned char* lds, const Gemm g, const StaticOrder& S, const Epi& E) {
;     ...
;         for (int t = 0; t < nt; t += 2) {
;             const bool last = (t == nt - 2);
;             const char* a1 = cA + (size_t)(t + 1) * kstep;
;             const char* a2 = last ? nA : cA + (size_t)(t + 2) * kstep; const char* b2 = last ? nB : cB + (size_t)(t + 2) * kstep;
;             const char* a3 = a2 + kstep; const char* b3 = b2 + kstep;
;     ...
;             PG8_LDA(At, 1, 1); PG8_STAGE(PG8_SB(1, 0), b3, voffB); PG8_STAGE(PG8_SB(1, 1), b3 + hstepB, voffB); PG8_STAGE(PG8_SA(1, 0), a3, voffA);
;             PG8_WAIT_V(8); PG8_WAIT_L(0); PG8_BAR; PG8_MMA(1, 0, At, B0); PG8_MMA(1, 1, At, B1); PG8_BAR; PG8_SCHED;
	s_add_i32 s50, s68, s53
	v_lshl_add_u64 v[150:151], v[150:151], 0, s[10:11]
	s_mov_b32 m0, s50
	ds_read_b128 v[184:187], v155 offset:49152
	ds_read_b128 v[188:191], v155 offset:50176
	ds_read_b128 v[192:195], v155 offset:51200
	ds_read_b128 v[196:199], v155 offset:52224
	ds_read_b128 v[200:203], v155 offset:53248
	ds_read_b128 v[204:207], v155 offset:54272
	ds_read_b128 v[208:211], v155 offset:55296
	ds_read_b128 v[212:215], v155 offset:56320
	global_load_lds_dwordx4 v[150:151], off
	s_add_i32 m0, s50, 0x2000
	s_add_u32 s44, s44, 0x40080
	v_lshl_add_u64 v[150:151], v[216:217], 0, s[10:11]
	s_addc_u32 s45, s45, 0
	s_add_i32 s50, s69, s53
	global_load_lds_dwordx4 v[150:151], off
	v_lshl_add_u64 v[150:151], s[44:45], 0, v[132:133]
	s_mov_b32 m0, s50
	s_nop 0
	global_load_lds_dwordx4 v[150:151], off
	v_lshl_add_u64 v[150:151], s[44:45], 0, v[136:137]
	s_add_i32 m0, s50, 0x2000
	s_nop 0
	global_load_lds_dwordx4 v[150:151], off
	v_lshl_add_u64 v[150:151], v[218:219], 0, s[10:11]
	s_mov_b32 m0, s60
	s_nop 0
	global_load_lds_dwordx4 v[150:151], off
	v_lshl_add_u64 v[150:151], v[220:221], 0, s[10:11]
	s_mov_b32 m0, s61
	s_nop 0
	global_load_lds_dwordx4 v[150:151], off
	s_waitcnt vmcnt(8) lgkmcnt(0)
	s_barrier
	v_mfma_f32_16x16x32_bf16 v[60:63], v[146:149], v[184:187], v[60:63]
	v_mfma_f32_16x16x32_bf16 v[56:59], v[160:163], v[184:187], v[56:59]
	v_mfma_f32_16x16x32_bf16 v[44:47], v[146:149], v[192:195], v[44:47]
	v_mfma_f32_16x16x32_bf16 v[40:43], v[160:163], v[192:195], v[40:43]
	v_mfma_f32_16x16x32_bf16 v[28:31], v[146:149], v[200:203], v[28:31]
	v_mfma_f32_16x16x32_bf16 v[24:27], v[160:163], v[200:203], v[24:27]
	v_mfma_f32_16x16x32_bf16 v[12:15], v[146:149], v[208:211], v[12:15]
	v_mfma_f32_16x16x32_bf16 v[8:11], v[160:163], v[208:211], v[8:11]
	v_mfma_f32_16x16x32_bf16 v[60:63], v[156:159], v[188:191], v[60:63]
	v_mfma_f32_16x16x32_bf16 v[56:59], v[164:167], v[188:191], v[56:59]
	v_mfma_f32_16x16x32_bf16 v[44:47], v[156:159], v[196:199], v[44:47]
	v_mfma_f32_16x16x32_bf16 v[40:43], v[164:167], v[196:199], v[40:43]
	v_mfma_f32_16x16x32_bf16 v[28:31], v[156:159], v[204:207], v[28:31]
	v_mfma_f32_16x16x32_bf16 v[24:27], v[164:167], v[204:207], v[24:27]
	v_mfma_f32_16x16x32_bf16 v[12:15], v[156:159], v[212:215], v[12:15]
	v_mfma_f32_16x16x32_bf16 v[8:11], v[164:167], v[212:215], v[8:11]
	v_mfma_f32_16x16x32_bf16 v[52:55], v[168:171], v[184:187], v[52:55]
	v_mfma_f32_16x16x32_bf16 v[48:51], v[176:179], v[184:187], v[48:51]
	v_mfma_f32_16x16x32_bf16 v[36:39], v[168:171], v[192:195], v[36:39]
	v_mfma_f32_16x16x32_bf16 v[32:35], v[176:179], v[192:195], v[32:35]
	v_mfma_f32_16x16x32_bf16 v[20:23], v[168:171], v[200:203], v[20:23]
	v_mfma_f32_16x16x32_bf16 v[16:19], v[176:179], v[200:203], v[16:19]
	v_mfma_f32_16x16x32_bf16 v[4:7], v[168:171], v[208:211], v[4:7]
	v_mfma_f32_16x16x32_bf16 v[0:3], v[176:179], v[208:211], v[0:3]
	v_mfma_f32_16x16x32_bf16 v[52:55], v[172:175], v[188:191], v[52:55]
	v_mfma_f32_16x16x32_bf16 v[48:51], v[180:183], v[188:191], v[48:51]
	v_mfma_f32_16x16x32_bf16 v[36:39], v[172:175], v[196:199], v[36:39]
	v_mfma_f32_16x16x32_bf16 v[32:35], v[180:183], v[196:199], v[32:35]
	v_mfma_f32_16x16x32_bf16 v[20:23], v[172:175], v[204:207], v[20:23]
	v_mfma_f32_16x16x32_bf16 v[16:19], v[180:183], v[204:207], v[16:19]
	v_mfma_f32_16x16x32_bf16 v[4:7], v[172:175], v[212:215], v[4:7]
	v_mfma_f32_16x16x32_bf16 v[0:3], v[180:183], v[212:215], v[0:3]
	s_barrier
	s_add_i32 s74, s74, 2
	s_add_u32 s34, s34, 0x100
	s_addc_u32 s35, s35, 0
	s_add_u32 s72, s72, 0x100
	s_addc_u32 s73, s73, 0
	s_cmp_gt_u32 s74, 13
	s_cbranch_scc0 .LBB0_462
	s_and_b64 vcc, exec, s[12:13]
	s_cbranch_vccz .LBB0_465
	s_barrier

; #define PG8_STAGE(bufoff, gbase, voff) do { _Pragma("unroll") for (int _i = 0; _i < 2; ++_i) \
;         __builtin_amdgcn_global_load_lds((const unsigned*)((const char*)(gbase) + (voff)[_i]), (LAS unsigned*)(lds + (bufoff) + ldsw + _i * 8192), 16, 0, 0); } while (0)
; #define PG8_LDA(dst, b, h) do { _Pragma("unroll") for (int m = 0; m < 4; ++m) _Pragma("unroll") for (int k = 0; k < 2; ++k) dst[m][k] = *(const LAS bf16x8*)(lds + PG8_SA(b, h) + aoff + m * 2048 + k * 1024); } while (0)
; #define PG8_LDB(dst, b, h) do { _Pragma("unroll") for (int n = 0; n < 2; ++n) _Pragma("unroll") for (int k = 0; k < 2; ++k) dst[n][k] = *(const LAS bf16x8*)(lds + PG8_SB(b, h) + boff + n * 2048 + k * 1024); } while (0)
; #define PG8_MMA(ai, bj, At, Bt) do { __builtin_amdgcn_s_setprio(1); _Pragma("unroll") for (int m = 0; m < 4; ++m) _Pragma("unroll") for (int n = 0; n < 2; ++n) _Pragma("unroll") for (int k = 0; k < 2; ++k) \
;         acc[ai][bj][m][n] = __builtin_amdgcn_mfma_f32_16x16x32_bf16(Bt[n][k], At[m][k], acc[ai][bj][m][n], 0, 0, 0); __builtin_amdgcn_s_setprio(0); } while (0)
; #define PG8_WAIT_V(n) asm volatile("s_waitcnt vmcnt(" #n ")" ::: "memory")
; #define PG8_WAIT_L(n) asm volatile("s_waitcnt lgkmcnt(" #n ")" ::: "memory")
; #define PG8_BAR __builtin_amdgcn_s_barrier()
; #define PG8_SCHED __builtin_amdgcn_sched_barrier(0)
; template <class Epi, bool SP2 = false>
; __device__ __forceinline__ void gemm_phase(LAS unsigned char* lds, const Gemm g, const StaticOrder& S, const Epi& E) {
;     ...
;             const bool last = (t == nt - 2);
;             const char* a1 = cA + (size_t)(t + 1) * kstep;
;             const char* a2 = last ? nA : cA + (size_t)(t + 2) * kstep; const char* b2 = last ? nB : cB + (size_t)(t + 2) * kstep;
;             const char* a3 = a2 + kstep; const char* b3 = b2 + kstep;
;             if constexpr (SP2) {
;             PG8_LDB(B0, 0, 0); PG8_LDB(B1, 0, 1); PG8_SCHED; PG8_LDA(At, 0, 0); PG8_STAGE(PG8_SA(1, 1), a1 + hstepA, voffA);
;             PG8_WAIT_V(8); PG8_WAIT_L(0); PG8_BAR; PG8_MMA(0, 0, At, B0); PG8_MMA(0, 1, At, B1); PG8_BAR; PG8_SCHED;
;             PG8_LDA(At, 0, 1); PG8_STAGE(PG8_SB(0, 0), b2, voffB); PG8_STAGE(PG8_SB(0, 1), b2 + hstepB, voffB); PG8_STAGE(PG8_SA(0, 0), a2, voffA);
;             PG8_WAIT_V(8); PG8_WAIT_L(0); PG8_BAR; PG8_MMA(1, 0, At, B0); PG8_MMA(1, 1, At, B1); PG8_BAR; PG8_SCHED;
.LBB0_805:
	ds_read_b128 v[146:149], v153
	ds_read_b128 v[156:159], v153 offset:1024
	ds_read_b128 v[160:163], v153 offset:2048
	ds_read_b128 v[164:167], v153 offset:3072
	ds_read_b128 v[168:171], v154
	ds_read_b128 v[172:175], v154 offset:1024
	ds_read_b128 v[176:179], v154 offset:2048
	ds_read_b128 v[180:183], v154 offset:3072
	s_add_u32 s48, s34, 0xfffc0080
	s_addc_u32 s49, s35, -1
	s_cmp_eq_u32 s80, 12
	s_cselect_b32 s51, s43, s49
	s_cselect_b32 s50, s76, s48
	s_cselect_b32 s49, s41, s79
	s_cselect_b32 s48, s77, s78
	v_lshl_add_u64 v[150:151], s[34:35], 0, v[138:139]
	s_add_i32 m0, s31, 0xc000
	ds_read_b128 v[184:187], v155
	ds_read_b128 v[188:191], v155 offset:1024
	ds_read_b128 v[192:195], v155 offset:2048
	ds_read_b128 v[196:199], v155 offset:3072
	ds_read_b128 v[200:203], v155 offset:4096
	ds_read_b128 v[204:207], v155 offset:5120
	ds_read_b128 v[208:211], v155 offset:6144
	ds_read_b128 v[212:215], v155 offset:7168
	global_load_lds_dwordx4 v[150:151], off
	v_lshl_add_u64 v[150:151], s[34:35], 0, v[140:141]
	s_add_i32 m0, s31, 0xe000
	s_nop 0
	global_load_lds_dwordx4 v[150:151], off
	s_waitcnt vmcnt(8) lgkmcnt(0)
	s_barrier
	v_mfma_f32_16x16x32_bf16 v[124:127], v[146:149], v[184:187], v[124:127]
	v_mfma_f32_16x16x32_bf16 v[120:123], v[160:163], v[184:187], v[120:123]
	v_mfma_f32_16x16x32_bf16 v[108:111], v[146:149], v[192:195], v[108:111]
	v_mfma_f32_16x16x32_bf16 v[104:107], v[160:163], v[192:195], v[104:107]
	v_mfma_f32_16x16x32_bf16 v[92:95], v[146:149], v[200:203], v[92:95]
	v_mfma_f32_16x16x32_bf16 v[88:91], v[160:163], v[200:203], v[88:91]
	v_mfma_f32_16x16x32_bf16 v[76:79], v[146:149], v[208:211], v[76:79]
	v_mfma_f32_16x16x32_bf16 v[72:75], v[160:163], v[208:211], v[72:75]
	v_mfma_f32_16x16x32_bf16 v[124:127], v[156:159], v[188:191], v[124:127]
	v_mfma_f32_16x16x32_bf16 v[120:123], v[164:167], v[188:191], v[120:123]
	v_mfma_f32_16x16x32_bf16 v[108:111], v[156:159], v[196:199], v[108:111]
	v_mfma_f32_16x16x32_bf16 v[104:107], v[164:167], v[196:199], v[104:107]
	v_mfma_f32_16x16x32_bf16 v[92:95], v[156:159], v[204:207], v[92:95]
	v_mfma_f32_16x16x32_bf16 v[88:91], v[164:167], v[204:207], v[88:91]
	v_mfma_f32_16x16x32_bf16 v[76:79], v[156:159], v[212:215], v[76:79]
	v_mfma_f32_16x16x32_bf16 v[72:75], v[164:167], v[212:215], v[72:75]
	v_mfma_f32_16x16x32_bf16 v[116:119], v[168:171], v[184:187], v[116:119]
	v_mfma_f32_16x16x32_bf16 v[112:115], v[176:179], v[184:187], v[112:115]
	v_mfma_f32_16x16x32_bf16 v[100:103], v[168:171], v[192:195], v[100:103]
	v_mfma_f32_16x16x32_bf16 v[96:99], v[176:179], v[192:195], v[96:99]
	v_mfma_f32_16x16x32_bf16 v[84:87], v[168:171], v[200:203], v[84:87]
	v_mfma_f32_16x16x32_bf16 v[80:83], v[176:179], v[200:203], v[80:83]
	v_mfma_f32_16x16x32_bf16 v[68:71], v[168:171], v[208:211], v[68:71]
	v_mfma_f32_16x16x32_bf16 v[64:67], v[176:179], v[208:211], v[64:67]
	v_mfma_f32_16x16x32_bf16 v[116:119], v[172:175], v[188:191], v[116:119]
	v_mfma_f32_16x16x32_bf16 v[112:115], v[180:183], v[188:191], v[112:115]
	v_mfma_f32_16x16x32_bf16 v[100:103], v[172:175], v[196:199], v[100:103]
	v_mfma_f32_16x16x32_bf16 v[96:99], v[180:183], v[196:199], v[96:99]
	v_mfma_f32_16x16x32_bf16 v[84:87], v[172:175], v[204:207], v[84:87]
	v_mfma_f32_16x16x32_bf16 v[80:83], v[180:183], v[204:207], v[80:83]
	v_mfma_f32_16x16x32_bf16 v[68:71], v[172:175], v[212:215], v[68:71]
	v_mfma_f32_16x16x32_bf16 v[64:67], v[180:183], v[212:215], v[64:67]
	s_barrier
	s_add_i32 s68, s66, s53
	v_lshl_add_u64 v[150:151], s[48:49], 0, v[134:135]
	s_mov_b32 m0, s68
	ds_read_b128 v[184:187], v155 offset:16384
	ds_read_b128 v[188:191], v155 offset:17408
	ds_read_b128 v[192:195], v155 offset:18432
	ds_read_b128 v[196:199], v155 offset:19456
	ds_read_b128 v[200:203], v155 offset:20480
	ds_read_b128 v[204:207], v155 offset:21504
	ds_read_b128 v[208:211], v155 offset:22528
	ds_read_b128 v[212:215], v155 offset:23552
	global_load_lds_dwordx4 v[150:151], off
	s_add_i32 m0, s68, 0x2000
	s_add_u32 s68, s48, 0x40000
	v_lshl_add_u64 v[216:217], s[48:49], 0, v[130:131]
	s_addc_u32 s69, s49, 0
	s_add_i32 s70, s67, s53
	global_load_lds_dwordx4 v[216:217], off
	v_lshl_add_u64 v[218:219], s[68:69], 0, v[134:135]
	s_mov_b32 m0, s70
	v_lshl_add_u64 v[220:221], s[50:51], 0, v[132:133]
	global_load_lds_dwordx4 v[218:219], off
	v_lshl_add_u64 v[218:219], s[68:69], 0, v[130:131]
	s_add_i32 m0, s70, 0x2000
	s_nop 0
	global_load_lds_dwordx4 v[218:219], off
	v_lshl_add_u64 v[218:219], s[50:51], 0, v[136:137]
	s_mov_b32 m0, s31
	s_nop 0
	global_load_lds_dwordx4 v[218:219], off
	s_mov_b32 m0, s56
	s_nop 0
	global_load_lds_dwordx4 v[220:221], off
	s_waitcnt vmcnt(8) lgkmcnt(0)
	s_barrier
; #define PG8_STAGE(bufoff, gbase, voff) do { _Pragma("unroll") for (int _i = 0; _i < 2; ++_i) \
;         __builtin_amdgcn_global_load_lds((const unsigned*)((const char*)(gbase) + (voff)[_i]), (LAS unsigned*)(lds + (bufoff) + ldsw + _i * 8192), 16, 0, 0); } while (0)
; #define PG8_LDA(dst, b, h) do { _Pragma("unroll") for (int m = 0; m < 4; ++m) _Pragma("unroll") for (int k = 0; k < 2; ++k) dst[m][k] = *(const LAS bf16x8*)(lds + PG8_SA(b, h) + aoff + m * 2048 + k * 1024); } while (0)
; #define PG8_LDB(dst, b, h) do { _Pragma("unroll") for (int n = 0; n < 2; ++n) _Pragma("unroll") for (int k = 0; k < 2; ++k) dst[n][k] = *(const LAS bf16x8*)(lds + PG8_SB(b, h) + boff + n * 2048 + k * 1024); } while (0)
; #define PG8_MMA(ai, bj, At, Bt) do { __builtin_amdgcn_s_setprio(1); _Pragma("unroll") for (int m = 0; m < 4; ++m) _Pragma("unroll") for (int n = 0; n < 2; ++n) _Pragma("unroll") for (int k = 0; k < 2; ++k) \
;         acc[ai][bj][m][n] = __builtin_amdgcn_mfma_f32_16x16x32_bf16(Bt[n][k], At[m][k], acc[ai][bj][m][n], 0, 0, 0); __builtin_amdgcn_s_setprio(0); } while (0)
; #define PG8_WAIT_V(n) asm volatile("s_waitcnt vmcnt(" #n ")" ::: "memory")
; #define PG8_WAIT_L(n) asm volatile("s_waitcnt lgkmcnt(" #n ")" ::: "memory")
; #define PG8_BAR __builtin_amdgcn_s_barrier()
; #define PG8_SCHED __builtin_amdgcn_sched_barrier(0)
; template <class Epi, bool SP2 = false>
; __device__ __forceinline__ void gemm_phase(LAS unsigned char* lds, const Gemm g, const StaticOrder& S, const Epi& E) {
;     ...
;             PG8_WAIT_V(8); PG8_WAIT_L(0); PG8_BAR; PG8_MMA(1, 0, At, B0); PG8_MMA(1, 1, At, B1); PG8_BAR; PG8_SCHED;
;             PG8_LDB(B0, 1, 0); PG8_LDB(B1, 1, 1); PG8_SCHED; PG8_LDA(At, 1, 0); PG8_STAGE(PG8_SA(0, 1), a2 + hstepA, voffA);
;             PG8_WAIT_V(8); PG8_WAIT_L(0); PG8_BAR; PG8_MMA(0, 0, At, B0); PG8_MMA(0, 1, At, B1); PG8_BAR; PG8_SCHED;
	v_mfma_f32_16x16x32_bf16 v[60:63], v[146:149], v[184:187], v[60:63]
	v_mfma_f32_16x16x32_bf16 v[56:59], v[160:163], v[184:187], v[56:59]
	v_mfma_f32_16x16x32_bf16 v[44:47], v[146:149], v[192:195], v[44:47]
	v_mfma_f32_16x16x32_bf16 v[40:43], v[160:163], v[192:195], v[40:43]
	v_mfma_f32_16x16x32_bf16 v[28:31], v[146:149], v[200:203], v[28:31]
	v_mfma_f32_16x16x32_bf16 v[24:27], v[160:163], v[200:203], v[24:27]
	v_mfma_f32_16x16x32_bf16 v[12:15], v[146:149], v[208:211], v[12:15]
	v_mfma_f32_16x16x32_bf16 v[8:11], v[160:163], v[208:211], v[8:11]
	v_mfma_f32_16x16x32_bf16 v[60:63], v[156:159], v[188:191], v[60:63]
	v_mfma_f32_16x16x32_bf16 v[56:59], v[164:167], v[188:191], v[56:59]
	v_mfma_f32_16x16x32_bf16 v[44:47], v[156:159], v[196:199], v[44:47]
	v_mfma_f32_16x16x32_bf16 v[40:43], v[164:167], v[196:199], v[40:43]
	v_mfma_f32_16x16x32_bf16 v[28:31], v[156:159], v[204:207], v[28:31]
	v_mfma_f32_16x16x32_bf16 v[24:27], v[164:167], v[204:207], v[24:27]
	v_mfma_f32_16x16x32_bf16 v[12:15], v[156:159], v[212:215], v[12:15]
	v_mfma_f32_16x16x32_bf16 v[8:11], v[164:167], v[212:215], v[8:11]
	v_mfma_f32_16x16x32_bf16 v[52:55], v[168:171], v[184:187], v[52:55]
	v_mfma_f32_16x16x32_bf16 v[48:51], v[176:179], v[184:187], v[48:51]
	v_mfma_f32_16x16x32_bf16 v[36:39], v[168:171], v[192:195], v[36:39]
	v_mfma_f32_16x16x32_bf16 v[32:35], v[176:179], v[192:195], v[32:35]
	v_mfma_f32_16x16x32_bf16 v[20:23], v[168:171], v[200:203], v[20:23]
	v_mfma_f32_16x16x32_bf16 v[16:19], v[176:179], v[200:203], v[16:19]
	v_mfma_f32_16x16x32_bf16 v[4:7], v[168:171], v[208:211], v[4:7]
	v_mfma_f32_16x16x32_bf16 v[0:3], v[176:179], v[208:211], v[0:3]
	v_mfma_f32_16x16x32_bf16 v[52:55], v[172:175], v[188:191], v[52:55]
	v_mfma_f32_16x16x32_bf16 v[48:51], v[180:183], v[188:191], v[48:51]
	v_mfma_f32_16x16x32_bf16 v[36:39], v[172:175], v[196:199], v[36:39]
	v_mfma_f32_16x16x32_bf16 v[32:35], v[180:183], v[196:199], v[32:35]
	v_mfma_f32_16x16x32_bf16 v[20:23], v[172:175], v[204:207], v[20:23]
	v_mfma_f32_16x16x32_bf16 v[16:19], v[180:183], v[204:207], v[16:19]
	v_mfma_f32_16x16x32_bf16 v[4:7], v[172:175], v[212:215], v[4:7]
	v_mfma_f32_16x16x32_bf16 v[0:3], v[180:183], v[212:215], v[0:3]
	s_barrier
	s_add_i32 s68, 0, 0x18000
	s_add_i32 s69, 0, 0x1c000
	v_add_u32_e32 v164, s68, v152
	v_add_u32_e32 v180, s69, v152
	ds_read_b128 v[146:149], v164
	ds_read_b128 v[156:159], v164 offset:1024
	ds_read_b128 v[160:163], v164 offset:2048
	ds_read_b128 v[164:167], v164 offset:3072
	ds_read_b128 v[168:171], v180
	ds_read_b128 v[172:175], v180 offset:1024
	ds_read_b128 v[176:179], v180 offset:2048
	ds_read_b128 v[180:183], v180 offset:3072
	s_add_u32 s50, s50, 0x40000
	s_addc_u32 s51, s51, 0
	s_mov_b32 m0, s57
	v_lshl_add_u64 v[222:223], s[50:51], 0, v[136:137]
	ds_read_b128 v[184:187], v155 offset:32768
	ds_read_b128 v[188:191], v155 offset:33792
	ds_read_b128 v[192:195], v155 offset:34816
	ds_read_b128 v[196:199], v155 offset:35840
	ds_read_b128 v[200:203], v155 offset:36864
	ds_read_b128 v[204:207], v155 offset:37888
	ds_read_b128 v[208:211], v155 offset:38912
	ds_read_b128 v[212:215], v155 offset:39936
	global_load_lds_dwordx4 v[222:223], off
	v_lshl_add_u64 v[222:223], s[50:51], 0, v[132:133]
	s_mov_b32 m0, s58
	s_nop 0
	global_load_lds_dwordx4 v[222:223], off
	s_waitcnt vmcnt(8) lgkmcnt(0)
	s_barrier
	v_mfma_f32_16x16x32_bf16 v[124:127], v[146:149], v[184:187], v[124:127]
	v_mfma_f32_16x16x32_bf16 v[120:123], v[160:163], v[184:187], v[120:123]
	v_mfma_f32_16x16x32_bf16 v[108:111], v[146:149], v[192:195], v[108:111]
	v_mfma_f32_16x16x32_bf16 v[104:107], v[160:163], v[192:195], v[104:107]
	v_mfma_f32_16x16x32_bf16 v[92:95], v[146:149], v[200:203], v[92:95]
	v_mfma_f32_16x16x32_bf16 v[88:91], v[160:163], v[200:203], v[88:91]
	v_mfma_f32_16x16x32_bf16 v[76:79], v[146:149], v[208:211], v[76:79]
	v_mfma_f32_16x16x32_bf16 v[72:75], v[160:163], v[208:211], v[72:75]
	v_mfma_f32_16x16x32_bf16 v[124:127], v[156:159], v[188:191], v[124:127]
	v_mfma_f32_16x16x32_bf16 v[120:123], v[164:167], v[188:191], v[120:123]
	v_mfma_f32_16x16x32_bf16 v[108:111], v[156:159], v[196:199], v[108:111]
	v_mfma_f32_16x16x32_bf16 v[104:107], v[164:167], v[196:199], v[104:107]
	v_mfma_f32_16x16x32_bf16 v[92:95], v[156:159], v[204:207], v[92:95]
	v_mfma_f32_16x16x32_bf16 v[88:91], v[164:167], v[204:207], v[88:91]
	v_mfma_f32_16x16x32_bf16 v[76:79], v[156:159], v[212:215], v[76:79]
	v_mfma_f32_16x16x32_bf16 v[72:75], v[164:167], v[212:215], v[72:75]
	v_mfma_f32_16x16x32_bf16 v[116:119], v[168:171], v[184:187], v[116:119]
	v_mfma_f32_16x16x32_bf16 v[112:115], v[176:179], v[184:187], v[112:115]
	v_mfma_f32_16x16x32_bf16 v[100:103], v[168:171], v[192:195], v[100:103]
	v_mfma_f32_16x16x32_bf16 v[96:99], v[176:179], v[192:195], v[96:99]
	v_mfma_f32_16x16x32_bf16 v[84:87], v[168:171], v[200:203], v[84:87]
	v_mfma_f32_16x16x32_bf16 v[80:83], v[176:179], v[200:203], v[80:83]
	v_mfma_f32_16x16x32_bf16 v[68:71], v[168:171], v[208:211], v[68:71]
	v_mfma_f32_16x16x32_bf16 v[64:67], v[176:179], v[208:211], v[64:67]
	v_mfma_f32_16x16x32_bf16 v[116:119], v[172:175], v[188:191], v[116:119]
	v_mfma_f32_16x16x32_bf16 v[112:115], v[180:183], v[188:191], v[112:115]
	v_mfma_f32_16x16x32_bf16 v[100:103], v[172:175], v[196:199], v[100:103]
	v_mfma_f32_16x16x32_bf16 v[96:99], v[180:183], v[196:199], v[96:99]
	v_mfma_f32_16x16x32_bf16 v[84:87], v[172:175], v[204:207], v[84:87]
	v_mfma_f32_16x16x32_bf16 v[80:83], v[180:183], v[204:207], v[80:83]
	v_mfma_f32_16x16x32_bf16 v[68:71], v[172:175], v[212:215], v[68:71]
	v_mfma_f32_16x16x32_bf16 v[64:67], v[180:183], v[212:215], v[64:67]
	s_barrier
; #define PG8_STAGE(bufoff, gbase, voff) do { _Pragma("unroll") for (int _i = 0; _i < 2; ++_i) \
;         __builtin_amdgcn_global_load_lds((const unsigned*)((const char*)(gbase) + (voff)[_i]), (LAS unsigned*)(lds + (bufoff) + ldsw + _i * 8192), 16, 0, 0); } while (0)
; #define PG8_LDA(dst, b, h) do { _Pragma("unroll") for (int m = 0; m < 4; ++m) _Pragma("unroll") for (int k = 0; k < 2; ++k) dst[m][k] = *(const LAS bf16x8*)(lds + PG8_SA(b, h) + aoff + m * 2048 + k * 1024); } while (0)
; #define PG8_MMA(ai, bj, At, Bt) do { __builtin_amdgcn_s_setprio(1); _Pragma("unroll") for (int m = 0; m < 4; ++m) _Pragma("unroll") for (int n = 0; n < 2; ++n) _Pragma("unroll") for (int k = 0; k < 2; ++k) \
;         acc[ai][bj][m][n] = __builtin_amdgcn_mfma_f32_16x16x32_bf16(Bt[n][k], At[m][k], acc[ai][bj][m][n], 0, 0, 0); __builtin_amdgcn_s_setprio(0); } while (0)
; #define PG8_WAIT_V(n) asm volatile("s_waitcnt vmcnt(" #n ")" ::: "memory")
; #define PG8_WAIT_L(n) asm volatile("s_waitcnt lgkmcnt(" #n ")" ::: "memory")
; #define PG8_BAR __builtin_amdgcn_s_barrier()
; #define PG8_SCHED __builtin_amdgcn_sched_barrier(0)
; template <class Epi, bool SP2 = false>
; __device__ __forceinline__ void gemm_phase(LAS unsigned char* lds, const Gemm g, const StaticOrder& S, const Epi& E) {
;     ...
;         for (int t = 0; t < nt; t += 2) {
;             const bool last = (t == nt - 2);
;             const char* a1 = cA + (size_t)(t + 1) * kstep;
;             const char* a2 = last ? nA : cA + (size_t)(t + 2) * kstep; const char* b2 = last ? nB : cB + (size_t)(t + 2) * kstep;
;             const char* a3 = a2 + kstep; const char* b3 = b2 + kstep;
;     ...
;             PG8_LDA(At, 1, 1); PG8_STAGE(PG8_SB(1, 0), b3, voffB); PG8_STAGE(PG8_SB(1, 1), b3 + hstepB, voffB); PG8_STAGE(PG8_SA(1, 0), a3, voffA);
;             PG8_WAIT_V(8); PG8_WAIT_L(0); PG8_BAR; PG8_MMA(1, 0, At, B0); PG8_MMA(1, 1, At, B1); PG8_BAR; PG8_SCHED;
	s_add_i32 s50, s68, s53
	v_lshl_add_u64 v[150:151], v[150:151], 0, s[10:11]
	s_mov_b32 m0, s50
	ds_read_b128 v[184:187], v155 offset:49152
	ds_read_b128 v[188:191], v155 offset:50176
	ds_read_b128 v[192:195], v155 offset:51200
	ds_read_b128 v[196:199], v155 offset:52224
	ds_read_b128 v[200:203], v155 offset:53248
	ds_read_b128 v[204:207], v155 offset:54272
	ds_read_b128 v[208:211], v155 offset:55296
	ds_read_b128 v[212:215], v155 offset:56320
	global_load_lds_dwordx4 v[150:151], off
	s_add_i32 m0, s50, 0x2000
	s_add_u32 s48, s48, 0x40080
	v_lshl_add_u64 v[150:151], v[216:217], 0, s[10:11]
	s_addc_u32 s49, s49, 0
	s_add_i32 s50, s69, s53
	global_load_lds_dwordx4 v[150:151], off
	v_lshl_add_u64 v[150:151], s[48:49], 0, v[134:135]
	s_mov_b32 m0, s50
	s_nop 0
	global_load_lds_dwordx4 v[150:151], off
	v_lshl_add_u64 v[150:151], s[48:49], 0, v[130:131]
	s_add_i32 m0, s50, 0x2000
	s_nop 0
	global_load_lds_dwordx4 v[150:151], off
	v_lshl_add_u64 v[150:151], v[218:219], 0, s[10:11]
	s_mov_b32 m0, s62
	s_nop 0
	global_load_lds_dwordx4 v[150:151], off
	v_lshl_add_u64 v[150:151], v[220:221], 0, s[10:11]
	s_mov_b32 m0, s63
	s_nop 0
	global_load_lds_dwordx4 v[150:151], off
	s_waitcnt vmcnt(8) lgkmcnt(0)
	s_barrier
	v_mfma_f32_16x16x32_bf16 v[60:63], v[146:149], v[184:187], v[60:63]
	v_mfma_f32_16x16x32_bf16 v[56:59], v[160:163], v[184:187], v[56:59]
	v_mfma_f32_16x16x32_bf16 v[44:47], v[146:149], v[192:195], v[44:47]
	v_mfma_f32_16x16x32_bf16 v[40:43], v[160:163], v[192:195], v[40:43]
	v_mfma_f32_16x16x32_bf16 v[28:31], v[146:149], v[200:203], v[28:31]
	v_mfma_f32_16x16x32_bf16 v[24:27], v[160:163], v[200:203], v[24:27]
	v_mfma_f32_16x16x32_bf16 v[12:15], v[146:149], v[208:211], v[12:15]
	v_mfma_f32_16x16x32_bf16 v[8:11], v[160:163], v[208:211], v[8:11]
	v_mfma_f32_16x16x32_bf16 v[60:63], v[156:159], v[188:191], v[60:63]
	v_mfma_f32_16x16x32_bf16 v[56:59], v[164:167], v[188:191], v[56:59]
	v_mfma_f32_16x16x32_bf16 v[44:47], v[156:159], v[196:199], v[44:47]
	v_mfma_f32_16x16x32_bf16 v[40:43], v[164:167], v[196:199], v[40:43]
	v_mfma_f32_16x16x32_bf16 v[28:31], v[156:159], v[204:207], v[28:31]
	v_mfma_f32_16x16x32_bf16 v[24:27], v[164:167], v[204:207], v[24:27]
	v_mfma_f32_16x16x32_bf16 v[12:15], v[156:159], v[212:215], v[12:15]
	v_mfma_f32_16x16x32_bf16 v[8:11], v[164:167], v[212:215], v[8:11]
	v_mfma_f32_16x16x32_bf16 v[52:55], v[168:171], v[184:187], v[52:55]
	v_mfma_f32_16x16x32_bf16 v[48:51], v[176:179], v[184:187], v[48:51]
	v_mfma_f32_16x16x32_bf16 v[36:39], v[168:171], v[192:195], v[36:39]
	v_mfma_f32_16x16x32_bf16 v[32:35], v[176:179], v[192:195], v[32:35]
	v_mfma_f32_16x16x32_bf16 v[20:23], v[168:171], v[200:203], v[20:23]
	v_mfma_f32_16x16x32_bf16 v[16:19], v[176:179], v[200:203], v[16:19]
	v_mfma_f32_16x16x32_bf16 v[4:7], v[168:171], v[208:211], v[4:7]
	v_mfma_f32_16x16x32_bf16 v[0:3], v[176:179], v[208:211], v[0:3]
	v_mfma_f32_16x16x32_bf16 v[52:55], v[172:175], v[188:191], v[52:55]
	v_mfma_f32_16x16x32_bf16 v[48:51], v[180:183], v[188:191], v[48:51]
	v_mfma_f32_16x16x32_bf16 v[36:39], v[172:175], v[196:199], v[36:39]
	v_mfma_f32_16x16x32_bf16 v[32:35], v[180:183], v[196:199], v[32:35]
	v_mfma_f32_16x16x32_bf16 v[20:23], v[172:175], v[204:207], v[20:23]
	v_mfma_f32_16x16x32_bf16 v[16:19], v[180:183], v[204:207], v[16:19]
	v_mfma_f32_16x16x32_bf16 v[4:7], v[172:175], v[212:215], v[4:7]
	v_mfma_f32_16x16x32_bf16 v[0:3], v[180:183], v[212:215], v[0:3]
	s_barrier
	s_add_i32 s80, s80, 2
	s_add_u32 s34, s34, 0x100
	s_addc_u32 s35, s35, 0
	s_add_u32 s78, s78, 0x100
	s_addc_u32 s79, s79, 0
	s_cmp_gt_u32 s80, 13
	s_cbranch_scc0 .LBB0_805
	s_and_b64 vcc, exec, s[12:13]
	s_cbranch_vccz .LBB0_808
	s_barrier

; #define PG8_STAGE(bufoff, gbase, voff) do { _Pragma("unroll") for (int _i = 0; _i < 2; ++_i) \
;         __builtin_amdgcn_global_load_lds((const unsigned*)((const char*)(gbase) + (voff)[_i]), (LAS unsigned*)(lds + (bufoff) + ldsw + _i * 8192), 16, 0, 0); } while (0)
; #define PG8_LDA(dst, b, h) do { _Pragma("unroll") for (int m = 0; m < 4; ++m) _Pragma("unroll") for (int k = 0; k < 2; ++k) dst[m][k] = *(const LAS bf16x8*)(lds + PG8_SA(b, h) + aoff + m * 2048 + k * 1024); } while (0)
; #define PG8_LDB(dst, b, h) do { _Pragma("unroll") for (int n = 0; n < 2; ++n) _Pragma("unroll") for (int k = 0; k < 2; ++k) dst[n][k] = *(const LAS bf16x8*)(lds + PG8_SB(b, h) + boff + n * 2048 + k * 1024); } while (0)
; #define PG8_MMA(ai, bj, At, Bt) do { __builtin_amdgcn_s_setprio(1); _Pragma("unroll") for (int m = 0; m < 4; ++m) _Pragma("unroll") for (int n = 0; n < 2; ++n) _Pragma("unroll") for (int k = 0; k < 2; ++k) \
;         acc[ai][bj][m][n] = __builtin_amdgcn_mfma_f32_16x16x32_bf16(Bt[n][k], At[m][k], acc[ai][bj][m][n], 0, 0, 0); __builtin_amdgcn_s_setprio(0); } while (0)
; #define PG8_WAIT_V(n) asm volatile("s_waitcnt vmcnt(" #n ")" ::: "memory")
; #define PG8_WAIT_L(n) asm volatile("s_waitcnt lgkmcnt(" #n ")" ::: "memory")
; #define PG8_BAR __builtin_amdgcn_s_barrier()
; #define PG8_SCHED __builtin_amdgcn_sched_barrier(0)
; template <class Epi, bool SP2 = false>
; __device__ __forceinline__ void gemm_phase(LAS unsigned char* lds, const Gemm g, const StaticOrder& S, const Epi& E) {
;     ...
;             const bool last = (t == nt - 2);
;             const char* a1 = cA + (size_t)(t + 1) * kstep;
;             const char* a2 = last ? nA : cA + (size_t)(t + 2) * kstep; const char* b2 = last ? nB : cB + (size_t)(t + 2) * kstep;
;             const char* a3 = a2 + kstep; const char* b3 = b2 + kstep;
;             if constexpr (SP2) {
;             PG8_LDB(B0, 0, 0); PG8_LDB(B1, 0, 1); PG8_SCHED; PG8_LDA(At, 0, 0); PG8_STAGE(PG8_SA(1, 1), a1 + hstepA, voffA);
;             PG8_WAIT_V(8); PG8_WAIT_L(0); PG8_BAR; PG8_MMA(0, 0, At, B0); PG8_MMA(0, 1, At, B1); PG8_BAR; PG8_SCHED;
;             PG8_LDA(At, 0, 1); PG8_STAGE(PG8_SB(0, 0), b2, voffB); PG8_STAGE(PG8_SB(0, 1), b2 + hstepB, voffB); PG8_STAGE(PG8_SA(0, 0), a2, voffA);
;             PG8_WAIT_V(8); PG8_WAIT_L(0); PG8_BAR; PG8_MMA(1, 0, At, B0); PG8_MMA(1, 1, At, B1); PG8_BAR; PG8_SCHED;
.LBB0_872:
	ds_read_b128 v[146:149], v166
	ds_read_b128 v[170:173], v166 offset:1024
	ds_read_b128 v[174:177], v166 offset:2048
	ds_read_b128 v[178:181], v166 offset:3072
	ds_read_b128 v[182:185], v167
	ds_read_b128 v[186:189], v167 offset:1024
	ds_read_b128 v[190:193], v167 offset:2048
	ds_read_b128 v[194:197], v167 offset:3072
	s_add_u32 s50, s34, 0xfffe0080
	s_addc_u32 s51, s35, -1
	s_cmp_eq_u32 s82, 4
	s_cselect_b32 s53, s45, s51
	s_cselect_b32 s52, s78, s50
	s_cselect_b32 s51, s43, s81
	s_cselect_b32 s50, s79, s80
	v_lshl_add_u64 v[150:151], s[34:35], 0, v[138:139]
	s_add_i32 m0, s31, 0xc000
	ds_read_b128 v[198:201], v168
	ds_read_b128 v[202:205], v168 offset:1024
	ds_read_b128 v[206:209], v168 offset:2048
	ds_read_b128 v[210:213], v168 offset:3072
	ds_read_b128 v[214:217], v168 offset:4096
	ds_read_b128 v[218:221], v168 offset:5120
	ds_read_b128 v[222:225], v168 offset:6144
	ds_read_b128 v[226:229], v168 offset:7168
	global_load_lds_dwordx4 v[150:151], off
	v_lshl_add_u64 v[150:151], s[34:35], 0, v[140:141]
	s_add_i32 m0, s31, 0xe000
	s_nop 0
	global_load_lds_dwordx4 v[150:151], off
	s_waitcnt vmcnt(8) lgkmcnt(0)
	s_barrier
	v_mfma_f32_16x16x32_bf16 v[124:127], v[146:149], v[198:201], v[124:127]
	v_mfma_f32_16x16x32_bf16 v[120:123], v[174:177], v[198:201], v[120:123]
	v_mfma_f32_16x16x32_bf16 v[108:111], v[146:149], v[206:209], v[108:111]
	v_mfma_f32_16x16x32_bf16 v[104:107], v[174:177], v[206:209], v[104:107]
	v_mfma_f32_16x16x32_bf16 v[92:95], v[146:149], v[214:217], v[92:95]
	v_mfma_f32_16x16x32_bf16 v[88:91], v[174:177], v[214:217], v[88:91]
	v_mfma_f32_16x16x32_bf16 v[76:79], v[146:149], v[222:225], v[76:79]
	v_mfma_f32_16x16x32_bf16 v[72:75], v[174:177], v[222:225], v[72:75]
	v_mfma_f32_16x16x32_bf16 v[124:127], v[170:173], v[202:205], v[124:127]
	v_mfma_f32_16x16x32_bf16 v[120:123], v[178:181], v[202:205], v[120:123]
	v_mfma_f32_16x16x32_bf16 v[108:111], v[170:173], v[210:213], v[108:111]
	v_mfma_f32_16x16x32_bf16 v[104:107], v[178:181], v[210:213], v[104:107]
	v_mfma_f32_16x16x32_bf16 v[92:95], v[170:173], v[218:221], v[92:95]
	v_mfma_f32_16x16x32_bf16 v[88:91], v[178:181], v[218:221], v[88:91]
	v_mfma_f32_16x16x32_bf16 v[76:79], v[170:173], v[226:229], v[76:79]
	v_mfma_f32_16x16x32_bf16 v[72:75], v[178:181], v[226:229], v[72:75]
	v_mfma_f32_16x16x32_bf16 v[116:119], v[182:185], v[198:201], v[116:119]
	v_mfma_f32_16x16x32_bf16 v[112:115], v[190:193], v[198:201], v[112:115]
	v_mfma_f32_16x16x32_bf16 v[100:103], v[182:185], v[206:209], v[100:103]
	v_mfma_f32_16x16x32_bf16 v[96:99], v[190:193], v[206:209], v[96:99]
	v_mfma_f32_16x16x32_bf16 v[84:87], v[182:185], v[214:217], v[84:87]
	v_mfma_f32_16x16x32_bf16 v[80:83], v[190:193], v[214:217], v[80:83]
	v_mfma_f32_16x16x32_bf16 v[68:71], v[182:185], v[222:225], v[68:71]
	v_mfma_f32_16x16x32_bf16 v[64:67], v[190:193], v[222:225], v[64:67]
	v_mfma_f32_16x16x32_bf16 v[116:119], v[186:189], v[202:205], v[116:119]
	v_mfma_f32_16x16x32_bf16 v[112:115], v[194:197], v[202:205], v[112:115]
	v_mfma_f32_16x16x32_bf16 v[100:103], v[186:189], v[210:213], v[100:103]
	v_mfma_f32_16x16x32_bf16 v[96:99], v[194:197], v[210:213], v[96:99]
	v_mfma_f32_16x16x32_bf16 v[84:87], v[186:189], v[218:221], v[84:87]
	v_mfma_f32_16x16x32_bf16 v[80:83], v[194:197], v[218:221], v[80:83]
	v_mfma_f32_16x16x32_bf16 v[68:71], v[186:189], v[226:229], v[68:71]
	v_mfma_f32_16x16x32_bf16 v[64:67], v[194:197], v[226:229], v[64:67]
	s_barrier
	s_add_i32 s68, s72, s55
	v_lshl_add_u64 v[150:151], s[50:51], 0, v[134:135]
	s_mov_b32 m0, s68
	ds_read_b128 v[198:201], v168 offset:16384
	ds_read_b128 v[202:205], v168 offset:17408
	ds_read_b128 v[206:209], v168 offset:18432
	ds_read_b128 v[210:213], v168 offset:19456
	ds_read_b128 v[214:217], v168 offset:20480
	ds_read_b128 v[218:221], v168 offset:21504
	ds_read_b128 v[222:225], v168 offset:22528
	ds_read_b128 v[226:229], v168 offset:23552
	global_load_lds_dwordx4 v[150:151], off
	s_add_i32 m0, s68, 0x2000
	s_add_u32 s68, s50, 0x20000
	v_lshl_add_u64 v[230:231], s[50:51], 0, v[130:131]
	s_addc_u32 s69, s51, 0
	s_add_i32 s70, s73, s55
	global_load_lds_dwordx4 v[230:231], off
	v_lshl_add_u64 v[232:233], s[68:69], 0, v[134:135]
	s_mov_b32 m0, s70
	v_lshl_add_u64 v[234:235], s[52:53], 0, v[132:133]
	global_load_lds_dwordx4 v[232:233], off
	v_lshl_add_u64 v[232:233], s[68:69], 0, v[130:131]
	s_add_i32 m0, s70, 0x2000
	s_nop 0
	global_load_lds_dwordx4 v[232:233], off
	v_lshl_add_u64 v[232:233], s[52:53], 0, v[136:137]
	s_mov_b32 m0, s31
	s_nop 0
	global_load_lds_dwordx4 v[232:233], off
	s_mov_b32 m0, s58
	s_nop 0
	global_load_lds_dwordx4 v[234:235], off
	s_waitcnt vmcnt(8) lgkmcnt(0)
	s_barrier
; #define PG8_STAGE(bufoff, gbase, voff) do { _Pragma("unroll") for (int _i = 0; _i < 2; ++_i) \
;         __builtin_amdgcn_global_load_lds((const unsigned*)((const char*)(gbase) + (voff)[_i]), (LAS unsigned*)(lds + (bufoff) + ldsw + _i * 8192), 16, 0, 0); } while (0)
; #define PG8_LDA(dst, b, h) do { _Pragma("unroll") for (int m = 0; m < 4; ++m) _Pragma("unroll") for (int k = 0; k < 2; ++k) dst[m][k] = *(const LAS bf16x8*)(lds + PG8_SA(b, h) + aoff + m * 2048 + k * 1024); } while (0)
; #define PG8_LDB(dst, b, h) do { _Pragma("unroll") for (int n = 0; n < 2; ++n) _Pragma("unroll") for (int k = 0; k < 2; ++k) dst[n][k] = *(const LAS bf16x8*)(lds + PG8_SB(b, h) + boff + n * 2048 + k * 1024); } while (0)
; #define PG8_MMA(ai, bj, At, Bt) do { __builtin_amdgcn_s_setprio(1); _Pragma("unroll") for (int m = 0; m < 4; ++m) _Pragma("unroll") for (int n = 0; n < 2; ++n) _Pragma("unroll") for (int k = 0; k < 2; ++k) \
;         acc[ai][bj][m][n] = __builtin_amdgcn_mfma_f32_16x16x32_bf16(Bt[n][k], At[m][k], acc[ai][bj][m][n], 0, 0, 0); __builtin_amdgcn_s_setprio(0); } while (0)
; #define PG8_WAIT_V(n) asm volatile("s_waitcnt vmcnt(" #n ")" ::: "memory")
; #define PG8_WAIT_L(n) asm volatile("s_waitcnt lgkmcnt(" #n ")" ::: "memory")
; #define PG8_BAR __builtin_amdgcn_s_barrier()
; #define PG8_SCHED __builtin_amdgcn_sched_barrier(0)
; template <class Epi, bool SP2 = false>
; __device__ __forceinline__ void gemm_phase(LAS unsigned char* lds, const Gemm g, const StaticOrder& S, const Epi& E) {
;     ...
;             PG8_WAIT_V(8); PG8_WAIT_L(0); PG8_BAR; PG8_MMA(1, 0, At, B0); PG8_MMA(1, 1, At, B1); PG8_BAR; PG8_SCHED;
;             PG8_LDB(B0, 1, 0); PG8_LDB(B1, 1, 1); PG8_SCHED; PG8_LDA(At, 1, 0); PG8_STAGE(PG8_SA(0, 1), a2 + hstepA, voffA);
;             PG8_WAIT_V(8); PG8_WAIT_L(0); PG8_BAR; PG8_MMA(0, 0, At, B0); PG8_MMA(0, 1, At, B1); PG8_BAR; PG8_SCHED;
	v_mfma_f32_16x16x32_bf16 v[60:63], v[146:149], v[198:201], v[60:63]
	v_mfma_f32_16x16x32_bf16 v[56:59], v[174:177], v[198:201], v[56:59]
	v_mfma_f32_16x16x32_bf16 v[44:47], v[146:149], v[206:209], v[44:47]
	v_mfma_f32_16x16x32_bf16 v[40:43], v[174:177], v[206:209], v[40:43]
	v_mfma_f32_16x16x32_bf16 v[28:31], v[146:149], v[214:217], v[28:31]
	v_mfma_f32_16x16x32_bf16 v[24:27], v[174:177], v[214:217], v[24:27]
	v_mfma_f32_16x16x32_bf16 v[12:15], v[146:149], v[222:225], v[12:15]
	v_mfma_f32_16x16x32_bf16 v[8:11], v[174:177], v[222:225], v[8:11]
	v_mfma_f32_16x16x32_bf16 v[60:63], v[170:173], v[202:205], v[60:63]
	v_mfma_f32_16x16x32_bf16 v[56:59], v[178:181], v[202:205], v[56:59]
	v_mfma_f32_16x16x32_bf16 v[44:47], v[170:173], v[210:213], v[44:47]
	v_mfma_f32_16x16x32_bf16 v[40:43], v[178:181], v[210:213], v[40:43]
	v_mfma_f32_16x16x32_bf16 v[28:31], v[170:173], v[218:221], v[28:31]
	v_mfma_f32_16x16x32_bf16 v[24:27], v[178:181], v[218:221], v[24:27]
	v_mfma_f32_16x16x32_bf16 v[12:15], v[170:173], v[226:229], v[12:15]
	v_mfma_f32_16x16x32_bf16 v[8:11], v[178:181], v[226:229], v[8:11]
	v_mfma_f32_16x16x32_bf16 v[52:55], v[182:185], v[198:201], v[52:55]
	v_mfma_f32_16x16x32_bf16 v[48:51], v[190:193], v[198:201], v[48:51]
	v_mfma_f32_16x16x32_bf16 v[36:39], v[182:185], v[206:209], v[36:39]
	v_mfma_f32_16x16x32_bf16 v[32:35], v[190:193], v[206:209], v[32:35]
	v_mfma_f32_16x16x32_bf16 v[20:23], v[182:185], v[214:217], v[20:23]
	v_mfma_f32_16x16x32_bf16 v[16:19], v[190:193], v[214:217], v[16:19]
	v_mfma_f32_16x16x32_bf16 v[4:7], v[182:185], v[222:225], v[4:7]
	v_mfma_f32_16x16x32_bf16 v[0:3], v[190:193], v[222:225], v[0:3]
	v_mfma_f32_16x16x32_bf16 v[52:55], v[186:189], v[202:205], v[52:55]
	v_mfma_f32_16x16x32_bf16 v[48:51], v[194:197], v[202:205], v[48:51]
	v_mfma_f32_16x16x32_bf16 v[36:39], v[186:189], v[210:213], v[36:39]
	v_mfma_f32_16x16x32_bf16 v[32:35], v[194:197], v[210:213], v[32:35]
	v_mfma_f32_16x16x32_bf16 v[20:23], v[186:189], v[218:221], v[20:23]
	v_mfma_f32_16x16x32_bf16 v[16:19], v[194:197], v[218:221], v[16:19]
	v_mfma_f32_16x16x32_bf16 v[4:7], v[186:189], v[226:229], v[4:7]
	v_mfma_f32_16x16x32_bf16 v[0:3], v[194:197], v[226:229], v[0:3]
	s_barrier
	s_add_i32 s68, 0, 0x18000
	v_add_u32_e32 v169, s68, v165
	s_add_i32 s69, 0, 0x1c000
	ds_read_b128 v[146:149], v169
	ds_read_b128 v[170:173], v169 offset:1024
	ds_read_b128 v[174:177], v169 offset:2048
	ds_read_b128 v[178:181], v169 offset:3072
	v_add_u32_e32 v169, s69, v165
	ds_read_b128 v[182:185], v169
	ds_read_b128 v[186:189], v169 offset:1024
	ds_read_b128 v[190:193], v169 offset:2048
	ds_read_b128 v[194:197], v169 offset:3072
	s_add_u32 s52, s52, 0x20000
	s_addc_u32 s53, s53, 0
	s_mov_b32 m0, s59
	v_lshl_add_u64 v[236:237], s[52:53], 0, v[136:137]
	ds_read_b128 v[198:201], v168 offset:32768
	ds_read_b128 v[202:205], v168 offset:33792
	ds_read_b128 v[206:209], v168 offset:34816
	ds_read_b128 v[210:213], v168 offset:35840
	ds_read_b128 v[214:217], v168 offset:36864
	ds_read_b128 v[218:221], v168 offset:37888
	ds_read_b128 v[222:225], v168 offset:38912
	ds_read_b128 v[226:229], v168 offset:39936
	global_load_lds_dwordx4 v[236:237], off
	v_lshl_add_u64 v[236:237], s[52:53], 0, v[132:133]
	s_mov_b32 m0, s60
	s_nop 0
	global_load_lds_dwordx4 v[236:237], off
	s_waitcnt vmcnt(8) lgkmcnt(0)
	s_barrier
	v_mfma_f32_16x16x32_bf16 v[124:127], v[146:149], v[198:201], v[124:127]
	v_mfma_f32_16x16x32_bf16 v[120:123], v[174:177], v[198:201], v[120:123]
	v_mfma_f32_16x16x32_bf16 v[108:111], v[146:149], v[206:209], v[108:111]
	v_mfma_f32_16x16x32_bf16 v[104:107], v[174:177], v[206:209], v[104:107]
	v_mfma_f32_16x16x32_bf16 v[92:95], v[146:149], v[214:217], v[92:95]
	v_mfma_f32_16x16x32_bf16 v[88:91], v[174:177], v[214:217], v[88:91]
	v_mfma_f32_16x16x32_bf16 v[76:79], v[146:149], v[222:225], v[76:79]
	v_mfma_f32_16x16x32_bf16 v[72:75], v[174:177], v[222:225], v[72:75]
	v_mfma_f32_16x16x32_bf16 v[124:127], v[170:173], v[202:205], v[124:127]
	v_mfma_f32_16x16x32_bf16 v[120:123], v[178:181], v[202:205], v[120:123]
	v_mfma_f32_16x16x32_bf16 v[108:111], v[170:173], v[210:213], v[108:111]
	v_mfma_f32_16x16x32_bf16 v[104:107], v[178:181], v[210:213], v[104:107]
	v_mfma_f32_16x16x32_bf16 v[92:95], v[170:173], v[218:221], v[92:95]
	v_mfma_f32_16x16x32_bf16 v[88:91], v[178:181], v[218:221], v[88:91]
	v_mfma_f32_16x16x32_bf16 v[76:79], v[170:173], v[226:229], v[76:79]
	v_mfma_f32_16x16x32_bf16 v[72:75], v[178:181], v[226:229], v[72:75]
	v_mfma_f32_16x16x32_bf16 v[116:119], v[182:185], v[198:201], v[116:119]
	v_mfma_f32_16x16x32_bf16 v[112:115], v[190:193], v[198:201], v[112:115]
	v_mfma_f32_16x16x32_bf16 v[100:103], v[182:185], v[206:209], v[100:103]
	v_mfma_f32_16x16x32_bf16 v[96:99], v[190:193], v[206:209], v[96:99]
	v_mfma_f32_16x16x32_bf16 v[84:87], v[182:185], v[214:217], v[84:87]
	v_mfma_f32_16x16x32_bf16 v[80:83], v[190:193], v[214:217], v[80:83]
	v_mfma_f32_16x16x32_bf16 v[68:71], v[182:185], v[222:225], v[68:71]
	v_mfma_f32_16x16x32_bf16 v[64:67], v[190:193], v[222:225], v[64:67]
	v_mfma_f32_16x16x32_bf16 v[116:119], v[186:189], v[202:205], v[116:119]
	v_mfma_f32_16x16x32_bf16 v[112:115], v[194:197], v[202:205], v[112:115]
	v_mfma_f32_16x16x32_bf16 v[100:103], v[186:189], v[210:213], v[100:103]
	v_mfma_f32_16x16x32_bf16 v[96:99], v[194:197], v[210:213], v[96:99]
	v_mfma_f32_16x16x32_bf16 v[84:87], v[186:189], v[218:221], v[84:87]
	v_mfma_f32_16x16x32_bf16 v[80:83], v[194:197], v[218:221], v[80:83]
	v_mfma_f32_16x16x32_bf16 v[68:71], v[186:189], v[226:229], v[68:71]
	v_mfma_f32_16x16x32_bf16 v[64:67], v[194:197], v[226:229], v[64:67]
	s_barrier
; #define PG8_STAGE(bufoff, gbase, voff) do { _Pragma("unroll") for (int _i = 0; _i < 2; ++_i) \
;         __builtin_amdgcn_global_load_lds((const unsigned*)((const char*)(gbase) + (voff)[_i]), (LAS unsigned*)(lds + (bufoff) + ldsw + _i * 8192), 16, 0, 0); } while (0)
; #define PG8_LDA(dst, b, h) do { _Pragma("unroll") for (int m = 0; m < 4; ++m) _Pragma("unroll") for (int k = 0; k < 2; ++k) dst[m][k] = *(const LAS bf16x8*)(lds + PG8_SA(b, h) + aoff + m * 2048 + k * 1024); } while (0)
; #define PG8_MMA(ai, bj, At, Bt) do { __builtin_amdgcn_s_setprio(1); _Pragma("unroll") for (int m = 0; m < 4; ++m) _Pragma("unroll") for (int n = 0; n < 2; ++n) _Pragma("unroll") for (int k = 0; k < 2; ++k) \
;         acc[ai][bj][m][n] = __builtin_amdgcn_mfma_f32_16x16x32_bf16(Bt[n][k], At[m][k], acc[ai][bj][m][n], 0, 0, 0); __builtin_amdgcn_s_setprio(0); } while (0)
; #define PG8_WAIT_V(n) asm volatile("s_waitcnt vmcnt(" #n ")" ::: "memory")
; #define PG8_WAIT_L(n) asm volatile("s_waitcnt lgkmcnt(" #n ")" ::: "memory")
; #define PG8_BAR __builtin_amdgcn_s_barrier()
; #define PG8_SCHED __builtin_amdgcn_sched_barrier(0)
; template <class Epi, bool SP2 = false>
; __device__ __forceinline__ void gemm_phase(LAS unsigned char* lds, const Gemm g, const StaticOrder& S, const Epi& E) {
;     ...
;         for (int t = 0; t < nt; t += 2) {
;             const bool last = (t == nt - 2);
;             const char* a1 = cA + (size_t)(t + 1) * kstep;
;             const char* a2 = last ? nA : cA + (size_t)(t + 2) * kstep; const char* b2 = last ? nB : cB + (size_t)(t + 2) * kstep;
;             const char* a3 = a2 + kstep; const char* b3 = b2 + kstep;
;     ...
;             PG8_LDA(At, 1, 1); PG8_STAGE(PG8_SB(1, 0), b3, voffB); PG8_STAGE(PG8_SB(1, 1), b3 + hstepB, voffB); PG8_STAGE(PG8_SA(1, 0), a3, voffA);
;             PG8_WAIT_V(8); PG8_WAIT_L(0); PG8_BAR; PG8_MMA(1, 0, At, B0); PG8_MMA(1, 1, At, B1); PG8_BAR; PG8_SCHED;
	s_add_i32 s52, s68, s55
	v_lshl_add_u64 v[150:151], v[150:151], 0, s[10:11]
	s_mov_b32 m0, s52
	ds_read_b128 v[198:201], v168 offset:49152
	ds_read_b128 v[202:205], v168 offset:50176
	ds_read_b128 v[206:209], v168 offset:51200
	ds_read_b128 v[210:213], v168 offset:52224
	ds_read_b128 v[214:217], v168 offset:53248
	ds_read_b128 v[218:221], v168 offset:54272
	ds_read_b128 v[222:225], v168 offset:55296
	ds_read_b128 v[226:229], v168 offset:56320
	global_load_lds_dwordx4 v[150:151], off
	s_add_i32 m0, s52, 0x2000
	s_add_u32 s50, s50, 0x20080
	v_lshl_add_u64 v[150:151], v[230:231], 0, s[10:11]
	s_addc_u32 s51, s51, 0
	s_add_i32 s52, s69, s55
	global_load_lds_dwordx4 v[150:151], off
	v_lshl_add_u64 v[150:151], s[50:51], 0, v[134:135]
	s_mov_b32 m0, s52
	s_nop 0
	global_load_lds_dwordx4 v[150:151], off
	v_lshl_add_u64 v[150:151], s[50:51], 0, v[130:131]
	s_add_i32 m0, s52, 0x2000
	s_nop 0
	global_load_lds_dwordx4 v[150:151], off
	v_lshl_add_u64 v[150:151], v[232:233], 0, s[10:11]
	s_mov_b32 m0, s64
	s_nop 0
	global_load_lds_dwordx4 v[150:151], off
	v_lshl_add_u64 v[150:151], v[234:235], 0, s[10:11]
	s_mov_b32 m0, s65
	s_nop 0
	global_load_lds_dwordx4 v[150:151], off
	s_waitcnt vmcnt(8) lgkmcnt(0)
	s_barrier
	v_mfma_f32_16x16x32_bf16 v[60:63], v[146:149], v[198:201], v[60:63]
	v_mfma_f32_16x16x32_bf16 v[56:59], v[174:177], v[198:201], v[56:59]
	v_mfma_f32_16x16x32_bf16 v[44:47], v[146:149], v[206:209], v[44:47]
	v_mfma_f32_16x16x32_bf16 v[40:43], v[174:177], v[206:209], v[40:43]
	v_mfma_f32_16x16x32_bf16 v[28:31], v[146:149], v[214:217], v[28:31]
	v_mfma_f32_16x16x32_bf16 v[24:27], v[174:177], v[214:217], v[24:27]
	v_mfma_f32_16x16x32_bf16 v[12:15], v[146:149], v[222:225], v[12:15]
	v_mfma_f32_16x16x32_bf16 v[8:11], v[174:177], v[222:225], v[8:11]
	v_mfma_f32_16x16x32_bf16 v[60:63], v[170:173], v[202:205], v[60:63]
	v_mfma_f32_16x16x32_bf16 v[56:59], v[178:181], v[202:205], v[56:59]
	v_mfma_f32_16x16x32_bf16 v[44:47], v[170:173], v[210:213], v[44:47]
	v_mfma_f32_16x16x32_bf16 v[40:43], v[178:181], v[210:213], v[40:43]
	v_mfma_f32_16x16x32_bf16 v[28:31], v[170:173], v[218:221], v[28:31]
	v_mfma_f32_16x16x32_bf16 v[24:27], v[178:181], v[218:221], v[24:27]
	v_mfma_f32_16x16x32_bf16 v[12:15], v[170:173], v[226:229], v[12:15]
	v_mfma_f32_16x16x32_bf16 v[8:11], v[178:181], v[226:229], v[8:11]
	v_mfma_f32_16x16x32_bf16 v[52:55], v[182:185], v[198:201], v[52:55]
	v_mfma_f32_16x16x32_bf16 v[48:51], v[190:193], v[198:201], v[48:51]
	v_mfma_f32_16x16x32_bf16 v[36:39], v[182:185], v[206:209], v[36:39]
	v_mfma_f32_16x16x32_bf16 v[32:35], v[190:193], v[206:209], v[32:35]
	v_mfma_f32_16x16x32_bf16 v[20:23], v[182:185], v[214:217], v[20:23]
	v_mfma_f32_16x16x32_bf16 v[16:19], v[190:193], v[214:217], v[16:19]
	v_mfma_f32_16x16x32_bf16 v[4:7], v[182:185], v[222:225], v[4:7]
	v_mfma_f32_16x16x32_bf16 v[0:3], v[190:193], v[222:225], v[0:3]
	v_mfma_f32_16x16x32_bf16 v[52:55], v[186:189], v[202:205], v[52:55]
	v_mfma_f32_16x16x32_bf16 v[48:51], v[194:197], v[202:205], v[48:51]
	v_mfma_f32_16x16x32_bf16 v[36:39], v[186:189], v[210:213], v[36:39]
	v_mfma_f32_16x16x32_bf16 v[32:35], v[194:197], v[210:213], v[32:35]
	v_mfma_f32_16x16x32_bf16 v[20:23], v[186:189], v[218:221], v[20:23]
	v_mfma_f32_16x16x32_bf16 v[16:19], v[194:197], v[218:221], v[16:19]
	v_mfma_f32_16x16x32_bf16 v[4:7], v[186:189], v[226:229], v[4:7]
	v_mfma_f32_16x16x32_bf16 v[0:3], v[194:197], v[226:229], v[0:3]
	s_barrier
	s_add_i32 s82, s82, 2
	s_add_u32 s34, s34, 0x100
	s_addc_u32 s35, s35, 0
	s_add_u32 s80, s80, 0x100
	s_addc_u32 s81, s81, 0
	s_cmp_gt_u32 s82, 5
	s_cbranch_scc0 .LBB0_872
	s_and_b64 vcc, exec, s[12:13]
	s_cbranch_vccz .LBB0_875
	s_barrier

; #define PG8_STAGE(bufoff, gbase, voff) do { _Pragma("unroll") for (int _i = 0; _i < 2; ++_i) \
;         __builtin_amdgcn_global_load_lds((const unsigned*)((const char*)(gbase) + (voff)[_i]), (LAS unsigned*)(lds + (bufoff) + ldsw + _i * 8192), 16, 0, 0); } while (0)
; #define PG8_LDA(dst, b, h) do { _Pragma("unroll") for (int m = 0; m < 4; ++m) _Pragma("unroll") for (int k = 0; k < 2; ++k) dst[m][k] = *(const LAS bf16x8*)(lds + PG8_SA(b, h) + aoff + m * 2048 + k * 1024); } while (0)
; #define PG8_LDB(dst, b, h) do { _Pragma("unroll") for (int n = 0; n < 2; ++n) _Pragma("unroll") for (int k = 0; k < 2; ++k) dst[n][k] = *(const LAS bf16x8*)(lds + PG8_SB(b, h) + boff + n * 2048 + k * 1024); } while (0)
; #define PG8_MMA(ai, bj, At, Bt) do { __builtin_amdgcn_s_setprio(1); _Pragma("unroll") for (int m = 0; m < 4; ++m) _Pragma("unroll") for (int n = 0; n < 2; ++n) _Pragma("unroll") for (int k = 0; k < 2; ++k) \
;         acc[ai][bj][m][n] = __builtin_amdgcn_mfma_f32_16x16x32_bf16(Bt[n][k], At[m][k], acc[ai][bj][m][n], 0, 0, 0); __builtin_amdgcn_s_setprio(0); } while (0)
; #define PG8_WAIT_V(n) asm volatile("s_waitcnt vmcnt(" #n ")" ::: "memory")
; #define PG8_WAIT_L(n) asm volatile("s_waitcnt lgkmcnt(" #n ")" ::: "memory")
; #define PG8_BAR __builtin_amdgcn_s_barrier()
; #define PG8_SCHED __builtin_amdgcn_sched_barrier(0)
; template <class Epi, bool SP2 = false>
; __device__ __forceinline__ void gemm_phase(LAS unsigned char* lds, const Gemm g, const StaticOrder& S, const Epi& E) {
;     ...
;             const bool last = (t == nt - 2);
;             const char* a1 = cA + (size_t)(t + 1) * kstep;
;             const char* a2 = last ? nA : cA + (size_t)(t + 2) * kstep; const char* b2 = last ? nB : cB + (size_t)(t + 2) * kstep;
;             const char* a3 = a2 + kstep; const char* b3 = b2 + kstep;
;             if constexpr (SP2) {
;             PG8_LDB(B0, 0, 0); PG8_LDB(B1, 0, 1); PG8_SCHED; PG8_LDA(At, 0, 0); PG8_STAGE(PG8_SA(1, 1), a1 + hstepA, voffA);
;             PG8_WAIT_V(8); PG8_WAIT_L(0); PG8_BAR; PG8_MMA(0, 0, At, B0); PG8_MMA(0, 1, At, B1); PG8_BAR; PG8_SCHED;
;             PG8_LDA(At, 0, 1); PG8_STAGE(PG8_SB(0, 0), b2, voffB); PG8_STAGE(PG8_SB(0, 1), b2 + hstepB, voffB); PG8_STAGE(PG8_SA(0, 0), a2, voffA);
;             PG8_WAIT_V(8); PG8_WAIT_L(0); PG8_BAR; PG8_MMA(1, 0, At, B0); PG8_MMA(1, 1, At, B1); PG8_BAR; PG8_SCHED;
.LBB0_888:
	ds_read_b128 v[146:149], v152
	ds_read_b128 v[156:159], v152 offset:1024
	ds_read_b128 v[160:163], v152 offset:2048
	ds_read_b128 v[164:167], v152 offset:3072
	ds_read_b128 v[168:171], v153
	ds_read_b128 v[172:175], v153 offset:1024
	ds_read_b128 v[176:179], v153 offset:2048
	ds_read_b128 v[180:183], v153 offset:3072
	s_add_u32 s48, s34, 0xfffc0080
	s_addc_u32 s49, s35, -1
	s_cmp_eq_u32 s76, 12
	s_cselect_b32 s51, s43, s49
	s_cselect_b32 s50, s72, s48
	s_cselect_b32 s49, s41, s75
	s_cselect_b32 s48, s73, s74
	v_lshl_add_u64 v[150:151], s[34:35], 0, v[138:139]
	s_add_i32 m0, s31, 0xc000
	ds_read_b128 v[184:187], v155
	ds_read_b128 v[188:191], v155 offset:1024
	ds_read_b128 v[192:195], v155 offset:2048
	ds_read_b128 v[196:199], v155 offset:3072
	ds_read_b128 v[200:203], v155 offset:4096
	ds_read_b128 v[204:207], v155 offset:5120
	ds_read_b128 v[208:211], v155 offset:6144
	ds_read_b128 v[212:215], v155 offset:7168
	global_load_lds_dwordx4 v[150:151], off
	v_lshl_add_u64 v[150:151], s[34:35], 0, v[140:141]
	s_add_i32 m0, s31, 0xe000
	s_nop 0
	global_load_lds_dwordx4 v[150:151], off
	s_waitcnt vmcnt(8) lgkmcnt(0)
	s_barrier
	v_mfma_f32_16x16x32_bf16 v[124:127], v[146:149], v[184:187], v[124:127]
	v_mfma_f32_16x16x32_bf16 v[120:123], v[160:163], v[184:187], v[120:123]
	v_mfma_f32_16x16x32_bf16 v[108:111], v[146:149], v[192:195], v[108:111]
	v_mfma_f32_16x16x32_bf16 v[104:107], v[160:163], v[192:195], v[104:107]
	v_mfma_f32_16x16x32_bf16 v[92:95], v[146:149], v[200:203], v[92:95]
	v_mfma_f32_16x16x32_bf16 v[88:91], v[160:163], v[200:203], v[88:91]
	v_mfma_f32_16x16x32_bf16 v[76:79], v[146:149], v[208:211], v[76:79]
	v_mfma_f32_16x16x32_bf16 v[72:75], v[160:163], v[208:211], v[72:75]
	v_mfma_f32_16x16x32_bf16 v[124:127], v[156:159], v[188:191], v[124:127]
	v_mfma_f32_16x16x32_bf16 v[120:123], v[164:167], v[188:191], v[120:123]
	v_mfma_f32_16x16x32_bf16 v[108:111], v[156:159], v[196:199], v[108:111]
	v_mfma_f32_16x16x32_bf16 v[104:107], v[164:167], v[196:199], v[104:107]
	v_mfma_f32_16x16x32_bf16 v[92:95], v[156:159], v[204:207], v[92:95]
	v_mfma_f32_16x16x32_bf16 v[88:91], v[164:167], v[204:207], v[88:91]
	v_mfma_f32_16x16x32_bf16 v[76:79], v[156:159], v[212:215], v[76:79]
	v_mfma_f32_16x16x32_bf16 v[72:75], v[164:167], v[212:215], v[72:75]
	v_mfma_f32_16x16x32_bf16 v[116:119], v[168:171], v[184:187], v[116:119]
	v_mfma_f32_16x16x32_bf16 v[112:115], v[176:179], v[184:187], v[112:115]
	v_mfma_f32_16x16x32_bf16 v[100:103], v[168:171], v[192:195], v[100:103]
	v_mfma_f32_16x16x32_bf16 v[96:99], v[176:179], v[192:195], v[96:99]
	v_mfma_f32_16x16x32_bf16 v[84:87], v[168:171], v[200:203], v[84:87]
	v_mfma_f32_16x16x32_bf16 v[80:83], v[176:179], v[200:203], v[80:83]
	v_mfma_f32_16x16x32_bf16 v[68:71], v[168:171], v[208:211], v[68:71]
	v_mfma_f32_16x16x32_bf16 v[64:67], v[176:179], v[208:211], v[64:67]
	v_mfma_f32_16x16x32_bf16 v[116:119], v[172:175], v[188:191], v[116:119]
	v_mfma_f32_16x16x32_bf16 v[112:115], v[180:183], v[188:191], v[112:115]
	v_mfma_f32_16x16x32_bf16 v[100:103], v[172:175], v[196:199], v[100:103]
	v_mfma_f32_16x16x32_bf16 v[96:99], v[180:183], v[196:199], v[96:99]
	v_mfma_f32_16x16x32_bf16 v[84:87], v[172:175], v[204:207], v[84:87]
	v_mfma_f32_16x16x32_bf16 v[80:83], v[180:183], v[204:207], v[80:83]
	v_mfma_f32_16x16x32_bf16 v[68:71], v[172:175], v[212:215], v[68:71]
	v_mfma_f32_16x16x32_bf16 v[64:67], v[180:183], v[212:215], v[64:67]
	s_barrier
	s_add_i32 s68, s66, s53
	v_lshl_add_u64 v[150:151], s[48:49], 0, v[134:135]
	s_mov_b32 m0, s68
	ds_read_b128 v[184:187], v155 offset:16384
	ds_read_b128 v[188:191], v155 offset:17408
	ds_read_b128 v[192:195], v155 offset:18432
	ds_read_b128 v[196:199], v155 offset:19456
	ds_read_b128 v[200:203], v155 offset:20480
	ds_read_b128 v[204:207], v155 offset:21504
	ds_read_b128 v[208:211], v155 offset:22528
	ds_read_b128 v[212:215], v155 offset:23552
	global_load_lds_dwordx4 v[150:151], off
	s_add_i32 m0, s68, 0x2000
	s_add_u32 s68, s48, 0x40000
	v_lshl_add_u64 v[216:217], s[48:49], 0, v[130:131]
	s_addc_u32 s69, s49, 0
	s_add_i32 s70, s67, s53
	global_load_lds_dwordx4 v[216:217], off
	v_lshl_add_u64 v[218:219], s[68:69], 0, v[134:135]
	s_mov_b32 m0, s70
	v_lshl_add_u64 v[220:221], s[50:51], 0, v[132:133]
	global_load_lds_dwordx4 v[218:219], off
	v_lshl_add_u64 v[218:219], s[68:69], 0, v[130:131]
	s_add_i32 m0, s70, 0x2000
	s_nop 0
	global_load_lds_dwordx4 v[218:219], off
	v_lshl_add_u64 v[218:219], s[50:51], 0, v[136:137]
	s_mov_b32 m0, s31
	s_nop 0
	global_load_lds_dwordx4 v[218:219], off
	s_mov_b32 m0, s56
	s_nop 0
	global_load_lds_dwordx4 v[220:221], off
	s_waitcnt vmcnt(8) lgkmcnt(0)
	s_barrier
; #define PG8_STAGE(bufoff, gbase, voff) do { _Pragma("unroll") for (int _i = 0; _i < 2; ++_i) \
;         __builtin_amdgcn_global_load_lds((const unsigned*)((const char*)(gbase) + (voff)[_i]), (LAS unsigned*)(lds + (bufoff) + ldsw + _i * 8192), 16, 0, 0); } while (0)
; #define PG8_LDA(dst, b, h) do { _Pragma("unroll") for (int m = 0; m < 4; ++m) _Pragma("unroll") for (int k = 0; k < 2; ++k) dst[m][k] = *(const LAS bf16x8*)(lds + PG8_SA(b, h) + aoff + m * 2048 + k * 1024); } while (0)
; #define PG8_LDB(dst, b, h) do { _Pragma("unroll") for (int n = 0; n < 2; ++n) _Pragma("unroll") for (int k = 0; k < 2; ++k) dst[n][k] = *(const LAS bf16x8*)(lds + PG8_SB(b, h) + boff + n * 2048 + k * 1024); } while (0)
; #define PG8_MMA(ai, bj, At, Bt) do { __builtin_amdgcn_s_setprio(1); _Pragma("unroll") for (int m = 0; m < 4; ++m) _Pragma("unroll") for (int n = 0; n < 2; ++n) _Pragma("unroll") for (int k = 0; k < 2; ++k) \
;         acc[ai][bj][m][n] = __builtin_amdgcn_mfma_f32_16x16x32_bf16(Bt[n][k], At[m][k], acc[ai][bj][m][n], 0, 0, 0); __builtin_amdgcn_s_setprio(0); } while (0)
; #define PG8_WAIT_V(n) asm volatile("s_waitcnt vmcnt(" #n ")" ::: "memory")
; #define PG8_WAIT_L(n) asm volatile("s_waitcnt lgkmcnt(" #n ")" ::: "memory")
; #define PG8_BAR __builtin_amdgcn_s_barrier()
; #define PG8_SCHED __builtin_amdgcn_sched_barrier(0)
; template <class Epi, bool SP2 = false>
; __device__ __forceinline__ void gemm_phase(LAS unsigned char* lds, const Gemm g, const StaticOrder& S, const Epi& E) {
;     ...
;             PG8_WAIT_V(8); PG8_WAIT_L(0); PG8_BAR; PG8_MMA(1, 0, At, B0); PG8_MMA(1, 1, At, B1); PG8_BAR; PG8_SCHED;
;             PG8_LDB(B0, 1, 0); PG8_LDB(B1, 1, 1); PG8_SCHED; PG8_LDA(At, 1, 0); PG8_STAGE(PG8_SA(0, 1), a2 + hstepA, voffA);
;             PG8_WAIT_V(8); PG8_WAIT_L(0); PG8_BAR; PG8_MMA(0, 0, At, B0); PG8_MMA(0, 1, At, B1); PG8_BAR; PG8_SCHED;
	v_mfma_f32_16x16x32_bf16 v[60:63], v[146:149], v[184:187], v[60:63]
	v_mfma_f32_16x16x32_bf16 v[56:59], v[160:163], v[184:187], v[56:59]
	v_mfma_f32_16x16x32_bf16 v[44:47], v[146:149], v[192:195], v[44:47]
	v_mfma_f32_16x16x32_bf16 v[40:43], v[160:163], v[192:195], v[40:43]
	v_mfma_f32_16x16x32_bf16 v[28:31], v[146:149], v[200:203], v[28:31]
	v_mfma_f32_16x16x32_bf16 v[24:27], v[160:163], v[200:203], v[24:27]
	v_mfma_f32_16x16x32_bf16 v[12:15], v[146:149], v[208:211], v[12:15]
	v_mfma_f32_16x16x32_bf16 v[8:11], v[160:163], v[208:211], v[8:11]
	v_mfma_f32_16x16x32_bf16 v[60:63], v[156:159], v[188:191], v[60:63]
	v_mfma_f32_16x16x32_bf16 v[56:59], v[164:167], v[188:191], v[56:59]
	v_mfma_f32_16x16x32_bf16 v[44:47], v[156:159], v[196:199], v[44:47]
	v_mfma_f32_16x16x32_bf16 v[40:43], v[164:167], v[196:199], v[40:43]
	v_mfma_f32_16x16x32_bf16 v[28:31], v[156:159], v[204:207], v[28:31]
	v_mfma_f32_16x16x32_bf16 v[24:27], v[164:167], v[204:207], v[24:27]
	v_mfma_f32_16x16x32_bf16 v[12:15], v[156:159], v[212:215], v[12:15]
	v_mfma_f32_16x16x32_bf16 v[8:11], v[164:167], v[212:215], v[8:11]
	v_mfma_f32_16x16x32_bf16 v[52:55], v[168:171], v[184:187], v[52:55]
	v_mfma_f32_16x16x32_bf16 v[48:51], v[176:179], v[184:187], v[48:51]
	v_mfma_f32_16x16x32_bf16 v[36:39], v[168:171], v[192:195], v[36:39]
	v_mfma_f32_16x16x32_bf16 v[32:35], v[176:179], v[192:195], v[32:35]
	v_mfma_f32_16x16x32_bf16 v[20:23], v[168:171], v[200:203], v[20:23]
	v_mfma_f32_16x16x32_bf16 v[16:19], v[176:179], v[200:203], v[16:19]
	v_mfma_f32_16x16x32_bf16 v[4:7], v[168:171], v[208:211], v[4:7]
	v_mfma_f32_16x16x32_bf16 v[0:3], v[176:179], v[208:211], v[0:3]
	v_mfma_f32_16x16x32_bf16 v[52:55], v[172:175], v[188:191], v[52:55]
	v_mfma_f32_16x16x32_bf16 v[48:51], v[180:183], v[188:191], v[48:51]
	v_mfma_f32_16x16x32_bf16 v[36:39], v[172:175], v[196:199], v[36:39]
	v_mfma_f32_16x16x32_bf16 v[32:35], v[180:183], v[196:199], v[32:35]
	v_mfma_f32_16x16x32_bf16 v[20:23], v[172:175], v[204:207], v[20:23]
	v_mfma_f32_16x16x32_bf16 v[16:19], v[180:183], v[204:207], v[16:19]
	v_mfma_f32_16x16x32_bf16 v[4:7], v[172:175], v[212:215], v[4:7]
	v_mfma_f32_16x16x32_bf16 v[0:3], v[180:183], v[212:215], v[0:3]
	s_barrier
	s_add_i32 s68, 0, 0x18000
	s_add_i32 s69, 0, 0x1c000
	v_add_u32_e32 v164, s68, v154
	v_add_u32_e32 v180, s69, v154
	ds_read_b128 v[146:149], v164
	ds_read_b128 v[156:159], v164 offset:1024
	ds_read_b128 v[160:163], v164 offset:2048
	ds_read_b128 v[164:167], v164 offset:3072
	ds_read_b128 v[168:171], v180
	ds_read_b128 v[172:175], v180 offset:1024
	ds_read_b128 v[176:179], v180 offset:2048
	ds_read_b128 v[180:183], v180 offset:3072
	s_add_u32 s50, s50, 0x40000
	s_addc_u32 s51, s51, 0
	s_mov_b32 m0, s57
	v_lshl_add_u64 v[222:223], s[50:51], 0, v[136:137]
	ds_read_b128 v[184:187], v155 offset:32768
	ds_read_b128 v[188:191], v155 offset:33792
	ds_read_b128 v[192:195], v155 offset:34816
	ds_read_b128 v[196:199], v155 offset:35840
	ds_read_b128 v[200:203], v155 offset:36864
	ds_read_b128 v[204:207], v155 offset:37888
	ds_read_b128 v[208:211], v155 offset:38912
	ds_read_b128 v[212:215], v155 offset:39936
	global_load_lds_dwordx4 v[222:223], off
	v_lshl_add_u64 v[222:223], s[50:51], 0, v[132:133]
	s_mov_b32 m0, s58
	s_nop 0
	global_load_lds_dwordx4 v[222:223], off
	s_waitcnt vmcnt(8) lgkmcnt(0)
	s_barrier
	v_mfma_f32_16x16x32_bf16 v[124:127], v[146:149], v[184:187], v[124:127]
	v_mfma_f32_16x16x32_bf16 v[120:123], v[160:163], v[184:187], v[120:123]
	v_mfma_f32_16x16x32_bf16 v[108:111], v[146:149], v[192:195], v[108:111]
	v_mfma_f32_16x16x32_bf16 v[104:107], v[160:163], v[192:195], v[104:107]
	v_mfma_f32_16x16x32_bf16 v[92:95], v[146:149], v[200:203], v[92:95]
	v_mfma_f32_16x16x32_bf16 v[88:91], v[160:163], v[200:203], v[88:91]
	v_mfma_f32_16x16x32_bf16 v[76:79], v[146:149], v[208:211], v[76:79]
	v_mfma_f32_16x16x32_bf16 v[72:75], v[160:163], v[208:211], v[72:75]
	v_mfma_f32_16x16x32_bf16 v[124:127], v[156:159], v[188:191], v[124:127]
	v_mfma_f32_16x16x32_bf16 v[120:123], v[164:167], v[188:191], v[120:123]
	v_mfma_f32_16x16x32_bf16 v[108:111], v[156:159], v[196:199], v[108:111]
	v_mfma_f32_16x16x32_bf16 v[104:107], v[164:167], v[196:199], v[104:107]
	v_mfma_f32_16x16x32_bf16 v[92:95], v[156:159], v[204:207], v[92:95]
	v_mfma_f32_16x16x32_bf16 v[88:91], v[164:167], v[204:207], v[88:91]
	v_mfma_f32_16x16x32_bf16 v[76:79], v[156:159], v[212:215], v[76:79]
	v_mfma_f32_16x16x32_bf16 v[72:75], v[164:167], v[212:215], v[72:75]
	v_mfma_f32_16x16x32_bf16 v[116:119], v[168:171], v[184:187], v[116:119]
	v_mfma_f32_16x16x32_bf16 v[112:115], v[176:179], v[184:187], v[112:115]
	v_mfma_f32_16x16x32_bf16 v[100:103], v[168:171], v[192:195], v[100:103]
	v_mfma_f32_16x16x32_bf16 v[96:99], v[176:179], v[192:195], v[96:99]
	v_mfma_f32_16x16x32_bf16 v[84:87], v[168:171], v[200:203], v[84:87]
	v_mfma_f32_16x16x32_bf16 v[80:83], v[176:179], v[200:203], v[80:83]
	v_mfma_f32_16x16x32_bf16 v[68:71], v[168:171], v[208:211], v[68:71]
	v_mfma_f32_16x16x32_bf16 v[64:67], v[176:179], v[208:211], v[64:67]
	v_mfma_f32_16x16x32_bf16 v[116:119], v[172:175], v[188:191], v[116:119]
	v_mfma_f32_16x16x32_bf16 v[112:115], v[180:183], v[188:191], v[112:115]
	v_mfma_f32_16x16x32_bf16 v[100:103], v[172:175], v[196:199], v[100:103]
	v_mfma_f32_16x16x32_bf16 v[96:99], v[180:183], v[196:199], v[96:99]
	v_mfma_f32_16x16x32_bf16 v[84:87], v[172:175], v[204:207], v[84:87]
	v_mfma_f32_16x16x32_bf16 v[80:83], v[180:183], v[204:207], v[80:83]
	v_mfma_f32_16x16x32_bf16 v[68:71], v[172:175], v[212:215], v[68:71]
	v_mfma_f32_16x16x32_bf16 v[64:67], v[180:183], v[212:215], v[64:67]
	s_barrier
; #define PG8_STAGE(bufoff, gbase, voff) do { _Pragma("unroll") for (int _i = 0; _i < 2; ++_i) \
;         __builtin_amdgcn_global_load_lds((const unsigned*)((const char*)(gbase) + (voff)[_i]), (LAS unsigned*)(lds + (bufoff) + ldsw + _i * 8192), 16, 0, 0); } while (0)
; #define PG8_LDA(dst, b, h) do { _Pragma("unroll") for (int m = 0; m < 4; ++m) _Pragma("unroll") for (int k = 0; k < 2; ++k) dst[m][k] = *(const LAS bf16x8*)(lds + PG8_SA(b, h) + aoff + m * 2048 + k * 1024); } while (0)
; #define PG8_MMA(ai, bj, At, Bt) do { __builtin_amdgcn_s_setprio(1); _Pragma("unroll") for (int m = 0; m < 4; ++m) _Pragma("unroll") for (int n = 0; n < 2; ++n) _Pragma("unroll") for (int k = 0; k < 2; ++k) \
;         acc[ai][bj][m][n] = __builtin_amdgcn_mfma_f32_16x16x32_bf16(Bt[n][k], At[m][k], acc[ai][bj][m][n], 0, 0, 0); __builtin_amdgcn_s_setprio(0); } while (0)
; #define PG8_WAIT_V(n) asm volatile("s_waitcnt vmcnt(" #n ")" ::: "memory")
; #define PG8_WAIT_L(n) asm volatile("s_waitcnt lgkmcnt(" #n ")" ::: "memory")
; #define PG8_BAR __builtin_amdgcn_s_barrier()
; #define PG8_SCHED __builtin_amdgcn_sched_barrier(0)
; template <class Epi, bool SP2 = false>
; __device__ __forceinline__ void gemm_phase(LAS unsigned char* lds, const Gemm g, const StaticOrder& S, const Epi& E) {
;     ...
;         for (int t = 0; t < nt; t += 2) {
;             const bool last = (t == nt - 2);
;             const char* a1 = cA + (size_t)(t + 1) * kstep;
;             const char* a2 = last ? nA : cA + (size_t)(t + 2) * kstep; const char* b2 = last ? nB : cB + (size_t)(t + 2) * kstep;
;             const char* a3 = a2 + kstep; const char* b3 = b2 + kstep;
;     ...
;             PG8_LDA(At, 1, 1); PG8_STAGE(PG8_SB(1, 0), b3, voffB); PG8_STAGE(PG8_SB(1, 1), b3 + hstepB, voffB); PG8_STAGE(PG8_SA(1, 0), a3, voffA);
;             PG8_WAIT_V(8); PG8_WAIT_L(0); PG8_BAR; PG8_MMA(1, 0, At, B0); PG8_MMA(1, 1, At, B1); PG8_BAR; PG8_SCHED;
	s_add_i32 s50, s68, s53
	v_lshl_add_u64 v[150:151], v[150:151], 0, s[10:11]
	s_mov_b32 m0, s50
	ds_read_b128 v[184:187], v155 offset:49152
	ds_read_b128 v[188:191], v155 offset:50176
	ds_read_b128 v[192:195], v155 offset:51200
	ds_read_b128 v[196:199], v155 offset:52224
	ds_read_b128 v[200:203], v155 offset:53248
	ds_read_b128 v[204:207], v155 offset:54272
	ds_read_b128 v[208:211], v155 offset:55296
	ds_read_b128 v[212:215], v155 offset:56320
	global_load_lds_dwordx4 v[150:151], off
	s_add_i32 m0, s50, 0x2000
	s_add_u32 s48, s48, 0x40080
	v_lshl_add_u64 v[150:151], v[216:217], 0, s[10:11]
	s_addc_u32 s49, s49, 0
	s_add_i32 s50, s69, s53
	global_load_lds_dwordx4 v[150:151], off
	v_lshl_add_u64 v[150:151], s[48:49], 0, v[134:135]
	s_mov_b32 m0, s50
	s_nop 0
	global_load_lds_dwordx4 v[150:151], off
	v_lshl_add_u64 v[150:151], s[48:49], 0, v[130:131]
	s_add_i32 m0, s50, 0x2000
	s_nop 0
	global_load_lds_dwordx4 v[150:151], off
	v_lshl_add_u64 v[150:151], v[218:219], 0, s[10:11]
	s_mov_b32 m0, s62
	s_nop 0
	global_load_lds_dwordx4 v[150:151], off
	v_lshl_add_u64 v[150:151], v[220:221], 0, s[10:11]
	s_mov_b32 m0, s63
	s_nop 0
	global_load_lds_dwordx4 v[150:151], off
	s_waitcnt vmcnt(8) lgkmcnt(0)
	s_barrier
	v_mfma_f32_16x16x32_bf16 v[60:63], v[146:149], v[184:187], v[60:63]
	v_mfma_f32_16x16x32_bf16 v[56:59], v[160:163], v[184:187], v[56:59]
	v_mfma_f32_16x16x32_bf16 v[44:47], v[146:149], v[192:195], v[44:47]
	v_mfma_f32_16x16x32_bf16 v[40:43], v[160:163], v[192:195], v[40:43]
	v_mfma_f32_16x16x32_bf16 v[28:31], v[146:149], v[200:203], v[28:31]
	v_mfma_f32_16x16x32_bf16 v[24:27], v[160:163], v[200:203], v[24:27]
	v_mfma_f32_16x16x32_bf16 v[12:15], v[146:149], v[208:211], v[12:15]
	v_mfma_f32_16x16x32_bf16 v[8:11], v[160:163], v[208:211], v[8:11]
	v_mfma_f32_16x16x32_bf16 v[60:63], v[156:159], v[188:191], v[60:63]
	v_mfma_f32_16x16x32_bf16 v[56:59], v[164:167], v[188:191], v[56:59]
	v_mfma_f32_16x16x32_bf16 v[44:47], v[156:159], v[196:199], v[44:47]
	v_mfma_f32_16x16x32_bf16 v[40:43], v[164:167], v[196:199], v[40:43]
	v_mfma_f32_16x16x32_bf16 v[28:31], v[156:159], v[204:207], v[28:31]
	v_mfma_f32_16x16x32_bf16 v[24:27], v[164:167], v[204:207], v[24:27]
	v_mfma_f32_16x16x32_bf16 v[12:15], v[156:159], v[212:215], v[12:15]
	v_mfma_f32_16x16x32_bf16 v[8:11], v[164:167], v[212:215], v[8:11]
	v_mfma_f32_16x16x32_bf16 v[52:55], v[168:171], v[184:187], v[52:55]
	v_mfma_f32_16x16x32_bf16 v[48:51], v[176:179], v[184:187], v[48:51]
	v_mfma_f32_16x16x32_bf16 v[36:39], v[168:171], v[192:195], v[36:39]
	v_mfma_f32_16x16x32_bf16 v[32:35], v[176:179], v[192:195], v[32:35]
	v_mfma_f32_16x16x32_bf16 v[20:23], v[168:171], v[200:203], v[20:23]
	v_mfma_f32_16x16x32_bf16 v[16:19], v[176:179], v[200:203], v[16:19]
	v_mfma_f32_16x16x32_bf16 v[4:7], v[168:171], v[208:211], v[4:7]
	v_mfma_f32_16x16x32_bf16 v[0:3], v[176:179], v[208:211], v[0:3]
	v_mfma_f32_16x16x32_bf16 v[52:55], v[172:175], v[188:191], v[52:55]
	v_mfma_f32_16x16x32_bf16 v[48:51], v[180:183], v[188:191], v[48:51]
	v_mfma_f32_16x16x32_bf16 v[36:39], v[172:175], v[196:199], v[36:39]
	v_mfma_f32_16x16x32_bf16 v[32:35], v[180:183], v[196:199], v[32:35]
	v_mfma_f32_16x16x32_bf16 v[20:23], v[172:175], v[204:207], v[20:23]
	v_mfma_f32_16x16x32_bf16 v[16:19], v[180:183], v[204:207], v[16:19]
	v_mfma_f32_16x16x32_bf16 v[4:7], v[172:175], v[212:215], v[4:7]
	v_mfma_f32_16x16x32_bf16 v[0:3], v[180:183], v[212:215], v[0:3]
	s_barrier
	s_add_i32 s76, s76, 2
	s_add_u32 s34, s34, 0x100
	s_addc_u32 s35, s35, 0
	s_add_u32 s74, s74, 0x100
	s_addc_u32 s75, s75, 0
	s_cmp_gt_u32 s76, 13
	s_cbranch_scc0 .LBB0_888
	s_and_b64 vcc, exec, s[12:13]
	s_cbranch_vccz .LBB0_891
	s_barrier

; #define PG8_STAGE(bufoff, gbase, voff) do { _Pragma("unroll") for (int _i = 0; _i < 2; ++_i) \
;         __builtin_amdgcn_global_load_lds((const unsigned*)((const char*)(gbase) + (voff)[_i]), (LAS unsigned*)(lds + (bufoff) + ldsw + _i * 8192), 16, 0, 0); } while (0)
; #define PG8_LDA(dst, b, h) do { _Pragma("unroll") for (int m = 0; m < 4; ++m) _Pragma("unroll") for (int k = 0; k < 2; ++k) dst[m][k] = *(const LAS bf16x8*)(lds + PG8_SA(b, h) + aoff + m * 2048 + k * 1024); } while (0)
; #define PG8_LDB(dst, b, h) do { _Pragma("unroll") for (int n = 0; n < 2; ++n) _Pragma("unroll") for (int k = 0; k < 2; ++k) dst[n][k] = *(const LAS bf16x8*)(lds + PG8_SB(b, h) + boff + n * 2048 + k * 1024); } while (0)
; #define PG8_MMA(ai, bj, At, Bt) do { __builtin_amdgcn_s_setprio(1); _Pragma("unroll") for (int m = 0; m < 4; ++m) _Pragma("unroll") for (int n = 0; n < 2; ++n) _Pragma("unroll") for (int k = 0; k < 2; ++k) \
;         acc[ai][bj][m][n] = __builtin_amdgcn_mfma_f32_16x16x32_bf16(Bt[n][k], At[m][k], acc[ai][bj][m][n], 0, 0, 0); __builtin_amdgcn_s_setprio(0); } while (0)
; #define PG8_WAIT_V(n) asm volatile("s_waitcnt vmcnt(" #n ")" ::: "memory")
; #define PG8_WAIT_L(n) asm volatile("s_waitcnt lgkmcnt(" #n ")" ::: "memory")
; #define PG8_BAR __builtin_amdgcn_s_barrier()
; #define PG8_SCHED __builtin_amdgcn_sched_barrier(0)
; template <class Epi, bool SP2 = false>
; __device__ __forceinline__ void gemm_phase(LAS unsigned char* lds, const Gemm g, const StaticOrder& S, const Epi& E) {
;     ...
;             const bool last = (t == nt - 2);
;             const char* a1 = cA + (size_t)(t + 1) * kstep;
;             const char* a2 = last ? nA : cA + (size_t)(t + 2) * kstep; const char* b2 = last ? nB : cB + (size_t)(t + 2) * kstep;
;             const char* a3 = a2 + kstep; const char* b3 = b2 + kstep;
;             if constexpr (SP2) {
;             PG8_LDB(B0, 0, 0); PG8_LDB(B1, 0, 1); PG8_SCHED; PG8_LDA(At, 0, 0); PG8_STAGE(PG8_SA(1, 1), a1 + hstepA, voffA);
;             PG8_WAIT_V(8); PG8_WAIT_L(0); PG8_BAR; PG8_MMA(0, 0, At, B0); PG8_MMA(0, 1, At, B1); PG8_BAR; PG8_SCHED;
;             PG8_LDA(At, 0, 1); PG8_STAGE(PG8_SB(0, 0), b2, voffB); PG8_STAGE(PG8_SB(0, 1), b2 + hstepB, voffB); PG8_STAGE(PG8_SA(0, 0), a2, voffA);
;             PG8_WAIT_V(8); PG8_WAIT_L(0); PG8_BAR; PG8_MMA(1, 0, At, B0); PG8_MMA(1, 1, At, B1); PG8_BAR; PG8_SCHED;
.LBB0_955:
	ds_read_b128 v[150:153], v147
	ds_read_b128 v[154:157], v147 offset:1024
	ds_read_b128 v[158:161], v147 offset:2048
	ds_read_b128 v[162:165], v147 offset:3072
	ds_read_b128 v[166:169], v148
	ds_read_b128 v[170:173], v148 offset:1024
	ds_read_b128 v[174:177], v148 offset:2048
	ds_read_b128 v[178:181], v148 offset:3072
	s_add_u32 s46, s34, 0xfffc0080
	s_addc_u32 s47, s35, -1
	s_cmp_eq_u32 s78, 12
	s_cselect_b32 s49, s41, s47
	s_cselect_b32 s48, s74, s46
	s_cselect_b32 s47, s39, s77
	s_cselect_b32 s46, s75, s76
	v_lshl_add_u64 v[214:215], s[34:35], 0, v[138:139]
	s_add_i32 m0, s53, 0xc000
	ds_read_b128 v[182:185], v149
	ds_read_b128 v[186:189], v149 offset:1024
	ds_read_b128 v[190:193], v149 offset:2048
	ds_read_b128 v[194:197], v149 offset:3072
	ds_read_b128 v[198:201], v149 offset:4096
	ds_read_b128 v[202:205], v149 offset:5120
	ds_read_b128 v[206:209], v149 offset:6144
	ds_read_b128 v[210:213], v149 offset:7168
	global_load_lds_dwordx4 v[214:215], off
	v_lshl_add_u64 v[214:215], s[34:35], 0, v[140:141]
	s_add_i32 m0, s53, 0xe000
	s_nop 0
	global_load_lds_dwordx4 v[214:215], off
	s_waitcnt vmcnt(8) lgkmcnt(0)
	s_barrier
	v_mfma_f32_16x16x32_bf16 v[124:127], v[150:153], v[182:185], v[124:127]
	v_mfma_f32_16x16x32_bf16 v[120:123], v[158:161], v[182:185], v[120:123]
	v_mfma_f32_16x16x32_bf16 v[116:119], v[150:153], v[190:193], v[116:119]
	v_mfma_f32_16x16x32_bf16 v[112:115], v[158:161], v[190:193], v[112:115]
	v_mfma_f32_16x16x32_bf16 v[100:103], v[150:153], v[198:201], v[100:103]
	v_mfma_f32_16x16x32_bf16 v[96:99], v[158:161], v[198:201], v[96:99]
	v_mfma_f32_16x16x32_bf16 v[84:87], v[150:153], v[206:209], v[84:87]
	v_mfma_f32_16x16x32_bf16 v[80:83], v[158:161], v[206:209], v[80:83]
	v_mfma_f32_16x16x32_bf16 v[124:127], v[154:157], v[186:189], v[124:127]
	v_mfma_f32_16x16x32_bf16 v[120:123], v[162:165], v[186:189], v[120:123]
	v_mfma_f32_16x16x32_bf16 v[116:119], v[154:157], v[194:197], v[116:119]
	v_mfma_f32_16x16x32_bf16 v[112:115], v[162:165], v[194:197], v[112:115]
	v_mfma_f32_16x16x32_bf16 v[100:103], v[154:157], v[202:205], v[100:103]
	v_mfma_f32_16x16x32_bf16 v[96:99], v[162:165], v[202:205], v[96:99]
	v_mfma_f32_16x16x32_bf16 v[84:87], v[154:157], v[210:213], v[84:87]
	v_mfma_f32_16x16x32_bf16 v[80:83], v[162:165], v[210:213], v[80:83]
	v_mfma_f32_16x16x32_bf16 v[108:111], v[166:169], v[182:185], v[108:111]
	v_mfma_f32_16x16x32_bf16 v[104:107], v[174:177], v[182:185], v[104:107]
	v_mfma_f32_16x16x32_bf16 v[92:95], v[166:169], v[190:193], v[92:95]
	v_mfma_f32_16x16x32_bf16 v[88:91], v[174:177], v[190:193], v[88:91]
	v_mfma_f32_16x16x32_bf16 v[76:79], v[166:169], v[198:201], v[76:79]
	v_mfma_f32_16x16x32_bf16 v[72:75], v[174:177], v[198:201], v[72:75]
	v_mfma_f32_16x16x32_bf16 v[68:71], v[166:169], v[206:209], v[68:71]
	v_mfma_f32_16x16x32_bf16 v[64:67], v[174:177], v[206:209], v[64:67]
	v_mfma_f32_16x16x32_bf16 v[108:111], v[170:173], v[186:189], v[108:111]
	v_mfma_f32_16x16x32_bf16 v[104:107], v[178:181], v[186:189], v[104:107]
	v_mfma_f32_16x16x32_bf16 v[92:95], v[170:173], v[194:197], v[92:95]
	v_mfma_f32_16x16x32_bf16 v[88:91], v[178:181], v[194:197], v[88:91]
	v_mfma_f32_16x16x32_bf16 v[76:79], v[170:173], v[202:205], v[76:79]
	v_mfma_f32_16x16x32_bf16 v[72:75], v[178:181], v[202:205], v[72:75]
	v_mfma_f32_16x16x32_bf16 v[68:71], v[170:173], v[210:213], v[68:71]
	v_mfma_f32_16x16x32_bf16 v[64:67], v[178:181], v[210:213], v[64:67]
	s_barrier
	s_add_i32 s68, s63, s50
	v_lshl_add_u64 v[214:215], s[46:47], 0, v[134:135]
	s_mov_b32 m0, s68
	ds_read_b128 v[182:185], v149 offset:16384
	ds_read_b128 v[186:189], v149 offset:17408
	ds_read_b128 v[190:193], v149 offset:18432
	ds_read_b128 v[194:197], v149 offset:19456
	ds_read_b128 v[198:201], v149 offset:20480
	ds_read_b128 v[202:205], v149 offset:21504
	ds_read_b128 v[206:209], v149 offset:22528
	ds_read_b128 v[210:213], v149 offset:23552
	global_load_lds_dwordx4 v[214:215], off
	s_add_i32 m0, s68, 0x2000
	s_add_u32 s68, s46, 0x40000
	v_lshl_add_u64 v[216:217], s[46:47], 0, v[130:131]
	s_addc_u32 s69, s47, 0
	s_add_i32 s70, s64, s50
	global_load_lds_dwordx4 v[216:217], off
	v_lshl_add_u64 v[218:219], s[68:69], 0, v[134:135]
	s_mov_b32 m0, s70
	v_lshl_add_u64 v[220:221], s[48:49], 0, v[132:133]
	global_load_lds_dwordx4 v[218:219], off
	v_lshl_add_u64 v[218:219], s[68:69], 0, v[130:131]
	s_add_i32 m0, s70, 0x2000
	s_nop 0
	global_load_lds_dwordx4 v[218:219], off
	v_lshl_add_u64 v[218:219], s[48:49], 0, v[136:137]
	s_mov_b32 m0, s53
	s_nop 0
	global_load_lds_dwordx4 v[218:219], off
	s_mov_b32 m0, s54
	s_nop 0
	global_load_lds_dwordx4 v[220:221], off
	s_waitcnt vmcnt(8) lgkmcnt(0)
	s_barrier
; #define PG8_STAGE(bufoff, gbase, voff) do { _Pragma("unroll") for (int _i = 0; _i < 2; ++_i) \
;         __builtin_amdgcn_global_load_lds((const unsigned*)((const char*)(gbase) + (voff)[_i]), (LAS unsigned*)(lds + (bufoff) + ldsw + _i * 8192), 16, 0, 0); } while (0)
; #define PG8_LDA(dst, b, h) do { _Pragma("unroll") for (int m = 0; m < 4; ++m) _Pragma("unroll") for (int k = 0; k < 2; ++k) dst[m][k] = *(const LAS bf16x8*)(lds + PG8_SA(b, h) + aoff + m * 2048 + k * 1024); } while (0)
; #define PG8_LDB(dst, b, h) do { _Pragma("unroll") for (int n = 0; n < 2; ++n) _Pragma("unroll") for (int k = 0; k < 2; ++k) dst[n][k] = *(const LAS bf16x8*)(lds + PG8_SB(b, h) + boff + n * 2048 + k * 1024); } while (0)
; #define PG8_MMA(ai, bj, At, Bt) do { __builtin_amdgcn_s_setprio(1); _Pragma("unroll") for (int m = 0; m < 4; ++m) _Pragma("unroll") for (int n = 0; n < 2; ++n) _Pragma("unroll") for (int k = 0; k < 2; ++k) \
;         acc[ai][bj][m][n] = __builtin_amdgcn_mfma_f32_16x16x32_bf16(Bt[n][k], At[m][k], acc[ai][bj][m][n], 0, 0, 0); __builtin_amdgcn_s_setprio(0); } while (0)
; #define PG8_WAIT_V(n) asm volatile("s_waitcnt vmcnt(" #n ")" ::: "memory")
; #define PG8_WAIT_L(n) asm volatile("s_waitcnt lgkmcnt(" #n ")" ::: "memory")
; #define PG8_BAR __builtin_amdgcn_s_barrier()
; #define PG8_SCHED __builtin_amdgcn_sched_barrier(0)
; template <class Epi, bool SP2 = false>
; __device__ __forceinline__ void gemm_phase(LAS unsigned char* lds, const Gemm g, const StaticOrder& S, const Epi& E) {
;     ...
;             PG8_WAIT_V(8); PG8_WAIT_L(0); PG8_BAR; PG8_MMA(1, 0, At, B0); PG8_MMA(1, 1, At, B1); PG8_BAR; PG8_SCHED;
;             PG8_LDB(B0, 1, 0); PG8_LDB(B1, 1, 1); PG8_SCHED; PG8_LDA(At, 1, 0); PG8_STAGE(PG8_SA(0, 1), a2 + hstepA, voffA);
;             PG8_WAIT_V(8); PG8_WAIT_L(0); PG8_BAR; PG8_MMA(0, 0, At, B0); PG8_MMA(0, 1, At, B1); PG8_BAR; PG8_SCHED;
	v_mfma_f32_16x16x32_bf16 v[60:63], v[150:153], v[182:185], v[60:63]
	v_mfma_f32_16x16x32_bf16 v[56:59], v[158:161], v[182:185], v[56:59]
	v_mfma_f32_16x16x32_bf16 v[52:55], v[150:153], v[190:193], v[52:55]
	v_mfma_f32_16x16x32_bf16 v[48:51], v[158:161], v[190:193], v[48:51]
	v_mfma_f32_16x16x32_bf16 v[36:39], v[150:153], v[198:201], v[36:39]
	v_mfma_f32_16x16x32_bf16 v[32:35], v[158:161], v[198:201], v[32:35]
	v_mfma_f32_16x16x32_bf16 v[20:23], v[150:153], v[206:209], v[20:23]
	v_mfma_f32_16x16x32_bf16 v[16:19], v[158:161], v[206:209], v[16:19]
	v_mfma_f32_16x16x32_bf16 v[60:63], v[154:157], v[186:189], v[60:63]
	v_mfma_f32_16x16x32_bf16 v[56:59], v[162:165], v[186:189], v[56:59]
	v_mfma_f32_16x16x32_bf16 v[52:55], v[154:157], v[194:197], v[52:55]
	v_mfma_f32_16x16x32_bf16 v[48:51], v[162:165], v[194:197], v[48:51]
	v_mfma_f32_16x16x32_bf16 v[36:39], v[154:157], v[202:205], v[36:39]
	v_mfma_f32_16x16x32_bf16 v[32:35], v[162:165], v[202:205], v[32:35]
	v_mfma_f32_16x16x32_bf16 v[20:23], v[154:157], v[210:213], v[20:23]
	v_mfma_f32_16x16x32_bf16 v[16:19], v[162:165], v[210:213], v[16:19]
	v_mfma_f32_16x16x32_bf16 v[44:47], v[166:169], v[182:185], v[44:47]
	v_mfma_f32_16x16x32_bf16 v[40:43], v[174:177], v[182:185], v[40:43]
	v_mfma_f32_16x16x32_bf16 v[28:31], v[166:169], v[190:193], v[28:31]
	v_mfma_f32_16x16x32_bf16 v[24:27], v[174:177], v[190:193], v[24:27]
	v_mfma_f32_16x16x32_bf16 v[12:15], v[166:169], v[198:201], v[12:15]
	v_mfma_f32_16x16x32_bf16 v[8:11], v[174:177], v[198:201], v[8:11]
	v_mfma_f32_16x16x32_bf16 v[4:7], v[166:169], v[206:209], v[4:7]
	v_mfma_f32_16x16x32_bf16 v[0:3], v[174:177], v[206:209], v[0:3]
	v_mfma_f32_16x16x32_bf16 v[44:47], v[170:173], v[186:189], v[44:47]
	v_mfma_f32_16x16x32_bf16 v[40:43], v[178:181], v[186:189], v[40:43]
	v_mfma_f32_16x16x32_bf16 v[28:31], v[170:173], v[194:197], v[28:31]
	v_mfma_f32_16x16x32_bf16 v[24:27], v[178:181], v[194:197], v[24:27]
	v_mfma_f32_16x16x32_bf16 v[12:15], v[170:173], v[202:205], v[12:15]
	v_mfma_f32_16x16x32_bf16 v[8:11], v[178:181], v[202:205], v[8:11]
	v_mfma_f32_16x16x32_bf16 v[4:7], v[170:173], v[210:213], v[4:7]
	v_mfma_f32_16x16x32_bf16 v[0:3], v[178:181], v[210:213], v[0:3]
	s_barrier
	s_add_i32 s68, 0, 0x18000
	s_add_i32 s69, 0, 0x1c000
	v_add_u32_e32 v162, s68, v146
	v_add_u32_e32 v178, s69, v146
	ds_read_b128 v[150:153], v162
	ds_read_b128 v[154:157], v162 offset:1024
	ds_read_b128 v[158:161], v162 offset:2048
	ds_read_b128 v[162:165], v162 offset:3072
	ds_read_b128 v[166:169], v178
	ds_read_b128 v[170:173], v178 offset:1024
	ds_read_b128 v[174:177], v178 offset:2048
	ds_read_b128 v[178:181], v178 offset:3072
	s_add_u32 s48, s48, 0x40000
	s_addc_u32 s49, s49, 0
	s_mov_b32 m0, s55
	v_lshl_add_u64 v[222:223], s[48:49], 0, v[136:137]
	ds_read_b128 v[182:185], v149 offset:32768
	ds_read_b128 v[186:189], v149 offset:33792
	ds_read_b128 v[190:193], v149 offset:34816
	ds_read_b128 v[194:197], v149 offset:35840
	ds_read_b128 v[198:201], v149 offset:36864
	ds_read_b128 v[202:205], v149 offset:37888
	ds_read_b128 v[206:209], v149 offset:38912
	ds_read_b128 v[210:213], v149 offset:39936
	global_load_lds_dwordx4 v[222:223], off
	v_lshl_add_u64 v[222:223], s[48:49], 0, v[132:133]
	s_mov_b32 m0, s56
	s_nop 0
	global_load_lds_dwordx4 v[222:223], off
	s_waitcnt vmcnt(8) lgkmcnt(0)
	s_barrier
	v_mfma_f32_16x16x32_bf16 v[124:127], v[150:153], v[182:185], v[124:127]
	v_mfma_f32_16x16x32_bf16 v[120:123], v[158:161], v[182:185], v[120:123]
	v_mfma_f32_16x16x32_bf16 v[116:119], v[150:153], v[190:193], v[116:119]
	v_mfma_f32_16x16x32_bf16 v[112:115], v[158:161], v[190:193], v[112:115]
	v_mfma_f32_16x16x32_bf16 v[100:103], v[150:153], v[198:201], v[100:103]
	v_mfma_f32_16x16x32_bf16 v[96:99], v[158:161], v[198:201], v[96:99]
	v_mfma_f32_16x16x32_bf16 v[84:87], v[150:153], v[206:209], v[84:87]
	v_mfma_f32_16x16x32_bf16 v[80:83], v[158:161], v[206:209], v[80:83]
	v_mfma_f32_16x16x32_bf16 v[124:127], v[154:157], v[186:189], v[124:127]
	v_mfma_f32_16x16x32_bf16 v[120:123], v[162:165], v[186:189], v[120:123]
	v_mfma_f32_16x16x32_bf16 v[116:119], v[154:157], v[194:197], v[116:119]
	v_mfma_f32_16x16x32_bf16 v[112:115], v[162:165], v[194:197], v[112:115]
	v_mfma_f32_16x16x32_bf16 v[100:103], v[154:157], v[202:205], v[100:103]
	v_mfma_f32_16x16x32_bf16 v[96:99], v[162:165], v[202:205], v[96:99]
	v_mfma_f32_16x16x32_bf16 v[84:87], v[154:157], v[210:213], v[84:87]
	v_mfma_f32_16x16x32_bf16 v[80:83], v[162:165], v[210:213], v[80:83]
	v_mfma_f32_16x16x32_bf16 v[108:111], v[166:169], v[182:185], v[108:111]
	v_mfma_f32_16x16x32_bf16 v[104:107], v[174:177], v[182:185], v[104:107]
	v_mfma_f32_16x16x32_bf16 v[92:95], v[166:169], v[190:193], v[92:95]
	v_mfma_f32_16x16x32_bf16 v[88:91], v[174:177], v[190:193], v[88:91]
	v_mfma_f32_16x16x32_bf16 v[76:79], v[166:169], v[198:201], v[76:79]
	v_mfma_f32_16x16x32_bf16 v[72:75], v[174:177], v[198:201], v[72:75]
	v_mfma_f32_16x16x32_bf16 v[68:71], v[166:169], v[206:209], v[68:71]
	v_mfma_f32_16x16x32_bf16 v[64:67], v[174:177], v[206:209], v[64:67]
	v_mfma_f32_16x16x32_bf16 v[108:111], v[170:173], v[186:189], v[108:111]
	v_mfma_f32_16x16x32_bf16 v[104:107], v[178:181], v[186:189], v[104:107]
	v_mfma_f32_16x16x32_bf16 v[92:95], v[170:173], v[194:197], v[92:95]
	v_mfma_f32_16x16x32_bf16 v[88:91], v[178:181], v[194:197], v[88:91]
	v_mfma_f32_16x16x32_bf16 v[76:79], v[170:173], v[202:205], v[76:79]
	v_mfma_f32_16x16x32_bf16 v[72:75], v[178:181], v[202:205], v[72:75]
	v_mfma_f32_16x16x32_bf16 v[68:71], v[170:173], v[210:213], v[68:71]
	v_mfma_f32_16x16x32_bf16 v[64:67], v[178:181], v[210:213], v[64:67]
	s_barrier
; #define PG8_STAGE(bufoff, gbase, voff) do { _Pragma("unroll") for (int _i = 0; _i < 2; ++_i) \
;         __builtin_amdgcn_global_load_lds((const unsigned*)((const char*)(gbase) + (voff)[_i]), (LAS unsigned*)(lds + (bufoff) + ldsw + _i * 8192), 16, 0, 0); } while (0)
; #define PG8_LDA(dst, b, h) do { _Pragma("unroll") for (int m = 0; m < 4; ++m) _Pragma("unroll") for (int k = 0; k < 2; ++k) dst[m][k] = *(const LAS bf16x8*)(lds + PG8_SA(b, h) + aoff + m * 2048 + k * 1024); } while (0)
; #define PG8_MMA(ai, bj, At, Bt) do { __builtin_amdgcn_s_setprio(1); _Pragma("unroll") for (int m = 0; m < 4; ++m) _Pragma("unroll") for (int n = 0; n < 2; ++n) _Pragma("unroll") for (int k = 0; k < 2; ++k) \
;         acc[ai][bj][m][n] = __builtin_amdgcn_mfma_f32_16x16x32_bf16(Bt[n][k], At[m][k], acc[ai][bj][m][n], 0, 0, 0); __builtin_amdgcn_s_setprio(0); } while (0)
; #define PG8_WAIT_V(n) asm volatile("s_waitcnt vmcnt(" #n ")" ::: "memory")
; #define PG8_WAIT_L(n) asm volatile("s_waitcnt lgkmcnt(" #n ")" ::: "memory")
; #define PG8_BAR __builtin_amdgcn_s_barrier()
; #define PG8_SCHED __builtin_amdgcn_sched_barrier(0)
; template <class Epi, bool SP2 = false>
; __device__ __forceinline__ void gemm_phase(LAS unsigned char* lds, const Gemm g, const StaticOrder& S, const Epi& E) {
;     ...
;         for (int t = 0; t < nt; t += 2) {
;             const bool last = (t == nt - 2);
;             const char* a1 = cA + (size_t)(t + 1) * kstep;
;             const char* a2 = last ? nA : cA + (size_t)(t + 2) * kstep; const char* b2 = last ? nB : cB + (size_t)(t + 2) * kstep;
;             const char* a3 = a2 + kstep; const char* b3 = b2 + kstep;
;     ...
;             PG8_LDA(At, 1, 1); PG8_STAGE(PG8_SB(1, 0), b3, voffB); PG8_STAGE(PG8_SB(1, 1), b3 + hstepB, voffB); PG8_STAGE(PG8_SA(1, 0), a3, voffA);
;             PG8_WAIT_V(8); PG8_WAIT_L(0); PG8_BAR; PG8_MMA(1, 0, At, B0); PG8_MMA(1, 1, At, B1); PG8_BAR; PG8_SCHED;
	s_add_i32 s48, s68, s50
	v_lshl_add_u64 v[214:215], v[214:215], 0, s[12:13]
	s_mov_b32 m0, s48
	ds_read_b128 v[182:185], v149 offset:49152
	ds_read_b128 v[186:189], v149 offset:50176
	ds_read_b128 v[190:193], v149 offset:51200
	ds_read_b128 v[194:197], v149 offset:52224
	ds_read_b128 v[198:201], v149 offset:53248
	ds_read_b128 v[202:205], v149 offset:54272
	ds_read_b128 v[206:209], v149 offset:55296
	ds_read_b128 v[210:213], v149 offset:56320
	global_load_lds_dwordx4 v[214:215], off
	s_add_i32 m0, s48, 0x2000
	s_add_u32 s46, s46, 0x40080
	v_lshl_add_u64 v[214:215], v[216:217], 0, s[12:13]
	s_addc_u32 s47, s47, 0
	s_add_i32 s48, s69, s50
	global_load_lds_dwordx4 v[214:215], off
	v_lshl_add_u64 v[214:215], s[46:47], 0, v[134:135]
	s_mov_b32 m0, s48
	s_nop 0
	global_load_lds_dwordx4 v[214:215], off
	v_lshl_add_u64 v[214:215], s[46:47], 0, v[130:131]
	s_add_i32 m0, s48, 0x2000
	s_nop 0
	global_load_lds_dwordx4 v[214:215], off
	v_lshl_add_u64 v[214:215], v[218:219], 0, s[12:13]
	s_mov_b32 m0, s59
	s_nop 0
	global_load_lds_dwordx4 v[214:215], off
	v_lshl_add_u64 v[214:215], v[220:221], 0, s[12:13]
	s_mov_b32 m0, s60
	s_nop 0
	global_load_lds_dwordx4 v[214:215], off
	s_waitcnt vmcnt(8) lgkmcnt(0)
	s_barrier
	v_mfma_f32_16x16x32_bf16 v[60:63], v[150:153], v[182:185], v[60:63]
	v_mfma_f32_16x16x32_bf16 v[56:59], v[158:161], v[182:185], v[56:59]
	v_mfma_f32_16x16x32_bf16 v[52:55], v[150:153], v[190:193], v[52:55]
	v_mfma_f32_16x16x32_bf16 v[48:51], v[158:161], v[190:193], v[48:51]
	v_mfma_f32_16x16x32_bf16 v[36:39], v[150:153], v[198:201], v[36:39]
	v_mfma_f32_16x16x32_bf16 v[32:35], v[158:161], v[198:201], v[32:35]
	v_mfma_f32_16x16x32_bf16 v[20:23], v[150:153], v[206:209], v[20:23]
	v_mfma_f32_16x16x32_bf16 v[16:19], v[158:161], v[206:209], v[16:19]
	v_mfma_f32_16x16x32_bf16 v[60:63], v[154:157], v[186:189], v[60:63]
	v_mfma_f32_16x16x32_bf16 v[56:59], v[162:165], v[186:189], v[56:59]
	v_mfma_f32_16x16x32_bf16 v[52:55], v[154:157], v[194:197], v[52:55]
	v_mfma_f32_16x16x32_bf16 v[48:51], v[162:165], v[194:197], v[48:51]
	v_mfma_f32_16x16x32_bf16 v[36:39], v[154:157], v[202:205], v[36:39]
	v_mfma_f32_16x16x32_bf16 v[32:35], v[162:165], v[202:205], v[32:35]
	v_mfma_f32_16x16x32_bf16 v[20:23], v[154:157], v[210:213], v[20:23]
	v_mfma_f32_16x16x32_bf16 v[16:19], v[162:165], v[210:213], v[16:19]
	v_mfma_f32_16x16x32_bf16 v[44:47], v[166:169], v[182:185], v[44:47]
	v_mfma_f32_16x16x32_bf16 v[40:43], v[174:177], v[182:185], v[40:43]
	v_mfma_f32_16x16x32_bf16 v[28:31], v[166:169], v[190:193], v[28:31]
	v_mfma_f32_16x16x32_bf16 v[24:27], v[174:177], v[190:193], v[24:27]
	v_mfma_f32_16x16x32_bf16 v[12:15], v[166:169], v[198:201], v[12:15]
	v_mfma_f32_16x16x32_bf16 v[8:11], v[174:177], v[198:201], v[8:11]
	v_mfma_f32_16x16x32_bf16 v[4:7], v[166:169], v[206:209], v[4:7]
	v_mfma_f32_16x16x32_bf16 v[0:3], v[174:177], v[206:209], v[0:3]
	v_mfma_f32_16x16x32_bf16 v[44:47], v[170:173], v[186:189], v[44:47]
	v_mfma_f32_16x16x32_bf16 v[40:43], v[178:181], v[186:189], v[40:43]
	v_mfma_f32_16x16x32_bf16 v[28:31], v[170:173], v[194:197], v[28:31]
	v_mfma_f32_16x16x32_bf16 v[24:27], v[178:181], v[194:197], v[24:27]
	v_mfma_f32_16x16x32_bf16 v[12:15], v[170:173], v[202:205], v[12:15]
	v_mfma_f32_16x16x32_bf16 v[8:11], v[178:181], v[202:205], v[8:11]
	v_mfma_f32_16x16x32_bf16 v[4:7], v[170:173], v[210:213], v[4:7]
	v_mfma_f32_16x16x32_bf16 v[0:3], v[178:181], v[210:213], v[0:3]
	s_barrier
	s_add_i32 s78, s78, 2
	s_add_u32 s34, s34, 0x100
	s_addc_u32 s35, s35, 0
	s_add_u32 s76, s76, 0x100
	s_addc_u32 s77, s77, 0
	s_cmp_gt_u32 s78, 13
	s_cbranch_scc0 .LBB0_955
	s_and_b64 vcc, exec, s[26:27]
	s_cbranch_vccz .LBB0_958
	s_barrier

; #define PG8_STAGE(bufoff, gbase, voff) do { _Pragma("unroll") for (int _i = 0; _i < 2; ++_i) \
;         __builtin_amdgcn_global_load_lds((const unsigned*)((const char*)(gbase) + (voff)[_i]), (LAS unsigned*)(lds + (bufoff) + ldsw + _i * 8192), 16, 0, 0); } while (0)
; #define PG8_LDA(dst, b, h) do { _Pragma("unroll") for (int m = 0; m < 4; ++m) _Pragma("unroll") for (int k = 0; k < 2; ++k) dst[m][k] = *(const LAS bf16x8*)(lds + PG8_SA(b, h) + aoff + m * 2048 + k * 1024); } while (0)
; #define PG8_LDB(dst, b, h) do { _Pragma("unroll") for (int n = 0; n < 2; ++n) _Pragma("unroll") for (int k = 0; k < 2; ++k) dst[n][k] = *(const LAS bf16x8*)(lds + PG8_SB(b, h) + boff + n * 2048 + k * 1024); } while (0)
; #define PG8_MMA(ai, bj, At, Bt) do { __builtin_amdgcn_s_setprio(1); _Pragma("unroll") for (int m = 0; m < 4; ++m) _Pragma("unroll") for (int n = 0; n < 2; ++n) _Pragma("unroll") for (int k = 0; k < 2; ++k) \
;         acc[ai][bj][m][n] = __builtin_amdgcn_mfma_f32_16x16x32_bf16(Bt[n][k], At[m][k], acc[ai][bj][m][n], 0, 0, 0); __builtin_amdgcn_s_setprio(0); } while (0)
; #define PG8_WAIT_V(n) asm volatile("s_waitcnt vmcnt(" #n ")" ::: "memory")
; #define PG8_WAIT_L(n) asm volatile("s_waitcnt lgkmcnt(" #n ")" ::: "memory")
; #define PG8_BAR __builtin_amdgcn_s_barrier()
; #define PG8_SCHED __builtin_amdgcn_sched_barrier(0)
; template <class Epi, bool SP2 = false>
; __device__ __forceinline__ void gemm_phase(LAS unsigned char* lds, const Gemm g, const StaticOrder& S, const Epi& E) {
;     ...
;             const bool last = (t == nt - 2);
;             const char* a1 = cA + (size_t)(t + 1) * kstep;
;             const char* a2 = last ? nA : cA + (size_t)(t + 2) * kstep; const char* b2 = last ? nB : cB + (size_t)(t + 2) * kstep;
;             const char* a3 = a2 + kstep; const char* b3 = b2 + kstep;
;             if constexpr (SP2) {
;             PG8_LDB(B0, 0, 0); PG8_LDB(B1, 0, 1); PG8_SCHED; PG8_LDA(At, 0, 0); PG8_STAGE(PG8_SA(1, 1), a1 + hstepA, voffA);
;             PG8_WAIT_V(8); PG8_WAIT_L(0); PG8_BAR; PG8_MMA(0, 0, At, B0); PG8_MMA(0, 1, At, B1); PG8_BAR; PG8_SCHED;
;             PG8_LDA(At, 0, 1); PG8_STAGE(PG8_SB(0, 0), b2, voffB); PG8_STAGE(PG8_SB(0, 1), b2 + hstepB, voffB); PG8_STAGE(PG8_SA(0, 0), a2, voffA);
;             PG8_WAIT_V(8); PG8_WAIT_L(0); PG8_BAR; PG8_MMA(1, 0, At, B0); PG8_MMA(1, 1, At, B1); PG8_BAR; PG8_SCHED;
.LBB0_1077:
	ds_read_b128 v[152:155], v149
	ds_read_b128 v[156:159], v149 offset:1024
	ds_read_b128 v[160:163], v149 offset:2048
	ds_read_b128 v[164:167], v149 offset:3072
	ds_read_b128 v[168:171], v150
	ds_read_b128 v[172:175], v150 offset:1024
	ds_read_b128 v[176:179], v150 offset:2048
	ds_read_b128 v[180:183], v150 offset:3072
	s_add_u32 s30, s28, 0xfffc0080
	s_addc_u32 s31, s29, -1
	s_cmp_eq_u32 s57, 12
	s_cselect_b32 s35, s19, s31
	s_cselect_b32 s34, s53, s30
	s_cselect_b32 s31, s13, s56
	s_cselect_b32 s30, s54, s55
	v_lshl_add_u64 v[146:147], s[28:29], 0, v[138:139]
	s_add_i32 m0, s27, 0xc000
	ds_read_b128 v[184:187], v151
	ds_read_b128 v[188:191], v151 offset:1024
	ds_read_b128 v[192:195], v151 offset:2048
	ds_read_b128 v[196:199], v151 offset:3072
	ds_read_b128 v[200:203], v151 offset:4096
	ds_read_b128 v[204:207], v151 offset:5120
	ds_read_b128 v[208:211], v151 offset:6144
	ds_read_b128 v[212:215], v151 offset:7168
	global_load_lds_dwordx4 v[146:147], off
	v_lshl_add_u64 v[146:147], s[28:29], 0, v[140:141]
	s_add_i32 m0, s27, 0xe000
	s_nop 0
	global_load_lds_dwordx4 v[146:147], off
	s_waitcnt vmcnt(8) lgkmcnt(0)
	s_barrier
	v_mfma_f32_16x16x32_bf16 v[124:127], v[152:155], v[184:187], v[124:127]
	v_mfma_f32_16x16x32_bf16 v[120:123], v[160:163], v[184:187], v[120:123]
	v_mfma_f32_16x16x32_bf16 v[108:111], v[152:155], v[192:195], v[108:111]
	v_mfma_f32_16x16x32_bf16 v[104:107], v[160:163], v[192:195], v[104:107]
	v_mfma_f32_16x16x32_bf16 v[92:95], v[152:155], v[200:203], v[92:95]
	v_mfma_f32_16x16x32_bf16 v[88:91], v[160:163], v[200:203], v[88:91]
	v_mfma_f32_16x16x32_bf16 v[76:79], v[152:155], v[208:211], v[76:79]
	v_mfma_f32_16x16x32_bf16 v[72:75], v[160:163], v[208:211], v[72:75]
	v_mfma_f32_16x16x32_bf16 v[124:127], v[156:159], v[188:191], v[124:127]
	v_mfma_f32_16x16x32_bf16 v[120:123], v[164:167], v[188:191], v[120:123]
	v_mfma_f32_16x16x32_bf16 v[108:111], v[156:159], v[196:199], v[108:111]
	v_mfma_f32_16x16x32_bf16 v[104:107], v[164:167], v[196:199], v[104:107]
	v_mfma_f32_16x16x32_bf16 v[92:95], v[156:159], v[204:207], v[92:95]
	v_mfma_f32_16x16x32_bf16 v[88:91], v[164:167], v[204:207], v[88:91]
	v_mfma_f32_16x16x32_bf16 v[76:79], v[156:159], v[212:215], v[76:79]
	v_mfma_f32_16x16x32_bf16 v[72:75], v[164:167], v[212:215], v[72:75]
	v_mfma_f32_16x16x32_bf16 v[116:119], v[168:171], v[184:187], v[116:119]
	v_mfma_f32_16x16x32_bf16 v[112:115], v[176:179], v[184:187], v[112:115]
	v_mfma_f32_16x16x32_bf16 v[100:103], v[168:171], v[192:195], v[100:103]
	v_mfma_f32_16x16x32_bf16 v[96:99], v[176:179], v[192:195], v[96:99]
	v_mfma_f32_16x16x32_bf16 v[84:87], v[168:171], v[200:203], v[84:87]
	v_mfma_f32_16x16x32_bf16 v[80:83], v[176:179], v[200:203], v[80:83]
	v_mfma_f32_16x16x32_bf16 v[68:71], v[168:171], v[208:211], v[68:71]
	v_mfma_f32_16x16x32_bf16 v[64:67], v[176:179], v[208:211], v[64:67]
	v_mfma_f32_16x16x32_bf16 v[116:119], v[172:175], v[188:191], v[116:119]
	v_mfma_f32_16x16x32_bf16 v[112:115], v[180:183], v[188:191], v[112:115]
	v_mfma_f32_16x16x32_bf16 v[100:103], v[172:175], v[196:199], v[100:103]
	v_mfma_f32_16x16x32_bf16 v[96:99], v[180:183], v[196:199], v[96:99]
	v_mfma_f32_16x16x32_bf16 v[84:87], v[172:175], v[204:207], v[84:87]
	v_mfma_f32_16x16x32_bf16 v[80:83], v[180:183], v[204:207], v[80:83]
	v_mfma_f32_16x16x32_bf16 v[68:71], v[172:175], v[212:215], v[68:71]
	v_mfma_f32_16x16x32_bf16 v[64:67], v[180:183], v[212:215], v[64:67]
	s_barrier
	s_add_i32 s58, s50, s37
	v_lshl_add_u64 v[146:147], s[30:31], 0, v[134:135]
	s_mov_b32 m0, s58
	ds_read_b128 v[184:187], v151 offset:16384
	ds_read_b128 v[188:191], v151 offset:17408
	ds_read_b128 v[192:195], v151 offset:18432
	ds_read_b128 v[196:199], v151 offset:19456
	ds_read_b128 v[200:203], v151 offset:20480
	ds_read_b128 v[204:207], v151 offset:21504
	ds_read_b128 v[208:211], v151 offset:22528
	ds_read_b128 v[212:215], v151 offset:23552
	global_load_lds_dwordx4 v[146:147], off
	s_add_i32 m0, s58, 0x2000
	s_add_u32 s58, s30, 0x40000
	v_lshl_add_u64 v[216:217], s[30:31], 0, v[130:131]
	s_addc_u32 s59, s31, 0
	s_add_i32 s60, s51, s37
	global_load_lds_dwordx4 v[216:217], off
	v_lshl_add_u64 v[218:219], s[58:59], 0, v[134:135]
	s_mov_b32 m0, s60
	v_lshl_add_u64 v[220:221], s[34:35], 0, v[132:133]
	global_load_lds_dwordx4 v[218:219], off
	v_lshl_add_u64 v[218:219], s[58:59], 0, v[130:131]
	s_add_i32 m0, s60, 0x2000
	s_nop 0
	global_load_lds_dwordx4 v[218:219], off
	v_lshl_add_u64 v[218:219], s[34:35], 0, v[136:137]
	s_mov_b32 m0, s27
	s_nop 0
	global_load_lds_dwordx4 v[218:219], off
	s_mov_b32 m0, s40
	s_nop 0
	global_load_lds_dwordx4 v[220:221], off
	s_waitcnt vmcnt(8) lgkmcnt(0)
	s_barrier
; #define PG8_STAGE(bufoff, gbase, voff) do { _Pragma("unroll") for (int _i = 0; _i < 2; ++_i) \
;         __builtin_amdgcn_global_load_lds((const unsigned*)((const char*)(gbase) + (voff)[_i]), (LAS unsigned*)(lds + (bufoff) + ldsw + _i * 8192), 16, 0, 0); } while (0)
; #define PG8_LDA(dst, b, h) do { _Pragma("unroll") for (int m = 0; m < 4; ++m) _Pragma("unroll") for (int k = 0; k < 2; ++k) dst[m][k] = *(const LAS bf16x8*)(lds + PG8_SA(b, h) + aoff + m * 2048 + k * 1024); } while (0)
; #define PG8_LDB(dst, b, h) do { _Pragma("unroll") for (int n = 0; n < 2; ++n) _Pragma("unroll") for (int k = 0; k < 2; ++k) dst[n][k] = *(const LAS bf16x8*)(lds + PG8_SB(b, h) + boff + n * 2048 + k * 1024); } while (0)
; #define PG8_MMA(ai, bj, At, Bt) do { __builtin_amdgcn_s_setprio(1); _Pragma("unroll") for (int m = 0; m < 4; ++m) _Pragma("unroll") for (int n = 0; n < 2; ++n) _Pragma("unroll") for (int k = 0; k < 2; ++k) \
;         acc[ai][bj][m][n] = __builtin_amdgcn_mfma_f32_16x16x32_bf16(Bt[n][k], At[m][k], acc[ai][bj][m][n], 0, 0, 0); __builtin_amdgcn_s_setprio(0); } while (0)
; #define PG8_WAIT_V(n) asm volatile("s_waitcnt vmcnt(" #n ")" ::: "memory")
; #define PG8_WAIT_L(n) asm volatile("s_waitcnt lgkmcnt(" #n ")" ::: "memory")
; #define PG8_BAR __builtin_amdgcn_s_barrier()
; #define PG8_SCHED __builtin_amdgcn_sched_barrier(0)
; template <class Epi, bool SP2 = false>
; __device__ __forceinline__ void gemm_phase(LAS unsigned char* lds, const Gemm g, const StaticOrder& S, const Epi& E) {
;     ...
;             PG8_WAIT_V(8); PG8_WAIT_L(0); PG8_BAR; PG8_MMA(1, 0, At, B0); PG8_MMA(1, 1, At, B1); PG8_BAR; PG8_SCHED;
;             PG8_LDB(B0, 1, 0); PG8_LDB(B1, 1, 1); PG8_SCHED; PG8_LDA(At, 1, 0); PG8_STAGE(PG8_SA(0, 1), a2 + hstepA, voffA);
;             PG8_WAIT_V(8); PG8_WAIT_L(0); PG8_BAR; PG8_MMA(0, 0, At, B0); PG8_MMA(0, 1, At, B1); PG8_BAR; PG8_SCHED;
	v_mfma_f32_16x16x32_bf16 v[60:63], v[152:155], v[184:187], v[60:63]
	v_mfma_f32_16x16x32_bf16 v[56:59], v[160:163], v[184:187], v[56:59]
	v_mfma_f32_16x16x32_bf16 v[44:47], v[152:155], v[192:195], v[44:47]
	v_mfma_f32_16x16x32_bf16 v[40:43], v[160:163], v[192:195], v[40:43]
	v_mfma_f32_16x16x32_bf16 v[28:31], v[152:155], v[200:203], v[28:31]
	v_mfma_f32_16x16x32_bf16 v[24:27], v[160:163], v[200:203], v[24:27]
	v_mfma_f32_16x16x32_bf16 v[12:15], v[152:155], v[208:211], v[12:15]
	v_mfma_f32_16x16x32_bf16 v[8:11], v[160:163], v[208:211], v[8:11]
	v_mfma_f32_16x16x32_bf16 v[60:63], v[156:159], v[188:191], v[60:63]
	v_mfma_f32_16x16x32_bf16 v[56:59], v[164:167], v[188:191], v[56:59]
	v_mfma_f32_16x16x32_bf16 v[44:47], v[156:159], v[196:199], v[44:47]
	v_mfma_f32_16x16x32_bf16 v[40:43], v[164:167], v[196:199], v[40:43]
	v_mfma_f32_16x16x32_bf16 v[28:31], v[156:159], v[204:207], v[28:31]
	v_mfma_f32_16x16x32_bf16 v[24:27], v[164:167], v[204:207], v[24:27]
	v_mfma_f32_16x16x32_bf16 v[12:15], v[156:159], v[212:215], v[12:15]
	v_mfma_f32_16x16x32_bf16 v[8:11], v[164:167], v[212:215], v[8:11]
	v_mfma_f32_16x16x32_bf16 v[52:55], v[168:171], v[184:187], v[52:55]
	v_mfma_f32_16x16x32_bf16 v[48:51], v[176:179], v[184:187], v[48:51]
	v_mfma_f32_16x16x32_bf16 v[36:39], v[168:171], v[192:195], v[36:39]
	v_mfma_f32_16x16x32_bf16 v[32:35], v[176:179], v[192:195], v[32:35]
	v_mfma_f32_16x16x32_bf16 v[20:23], v[168:171], v[200:203], v[20:23]
	v_mfma_f32_16x16x32_bf16 v[16:19], v[176:179], v[200:203], v[16:19]
	v_mfma_f32_16x16x32_bf16 v[4:7], v[168:171], v[208:211], v[4:7]
	v_mfma_f32_16x16x32_bf16 v[0:3], v[176:179], v[208:211], v[0:3]
	v_mfma_f32_16x16x32_bf16 v[52:55], v[172:175], v[188:191], v[52:55]
	v_mfma_f32_16x16x32_bf16 v[48:51], v[180:183], v[188:191], v[48:51]
	v_mfma_f32_16x16x32_bf16 v[36:39], v[172:175], v[196:199], v[36:39]
	v_mfma_f32_16x16x32_bf16 v[32:35], v[180:183], v[196:199], v[32:35]
	v_mfma_f32_16x16x32_bf16 v[20:23], v[172:175], v[204:207], v[20:23]
	v_mfma_f32_16x16x32_bf16 v[16:19], v[180:183], v[204:207], v[16:19]
	v_mfma_f32_16x16x32_bf16 v[4:7], v[172:175], v[212:215], v[4:7]
	v_mfma_f32_16x16x32_bf16 v[0:3], v[180:183], v[212:215], v[0:3]
	s_barrier
	s_add_i32 s58, 0, 0x18000
	s_add_i32 s59, 0, 0x1c000
	v_add_u32_e32 v164, s58, v148
	v_add_u32_e32 v180, s59, v148
	ds_read_b128 v[152:155], v164
	ds_read_b128 v[156:159], v164 offset:1024
	ds_read_b128 v[160:163], v164 offset:2048
	ds_read_b128 v[164:167], v164 offset:3072
	ds_read_b128 v[168:171], v180
	ds_read_b128 v[172:175], v180 offset:1024
	ds_read_b128 v[176:179], v180 offset:2048
	ds_read_b128 v[180:183], v180 offset:3072
	s_add_u32 s34, s34, 0x40000
	s_addc_u32 s35, s35, 0
	s_mov_b32 m0, s41
	v_lshl_add_u64 v[222:223], s[34:35], 0, v[136:137]
	ds_read_b128 v[184:187], v151 offset:32768
	ds_read_b128 v[188:191], v151 offset:33792
	ds_read_b128 v[192:195], v151 offset:34816
	ds_read_b128 v[196:199], v151 offset:35840
	ds_read_b128 v[200:203], v151 offset:36864
	ds_read_b128 v[204:207], v151 offset:37888
	ds_read_b128 v[208:211], v151 offset:38912
	ds_read_b128 v[212:215], v151 offset:39936
	global_load_lds_dwordx4 v[222:223], off
	v_lshl_add_u64 v[222:223], s[34:35], 0, v[132:133]
	s_mov_b32 m0, s42
	s_nop 0
	global_load_lds_dwordx4 v[222:223], off
	s_waitcnt vmcnt(8) lgkmcnt(0)
	s_barrier
	v_mfma_f32_16x16x32_bf16 v[124:127], v[152:155], v[184:187], v[124:127]
	v_mfma_f32_16x16x32_bf16 v[120:123], v[160:163], v[184:187], v[120:123]
	v_mfma_f32_16x16x32_bf16 v[108:111], v[152:155], v[192:195], v[108:111]
	v_mfma_f32_16x16x32_bf16 v[104:107], v[160:163], v[192:195], v[104:107]
	v_mfma_f32_16x16x32_bf16 v[92:95], v[152:155], v[200:203], v[92:95]
	v_mfma_f32_16x16x32_bf16 v[88:91], v[160:163], v[200:203], v[88:91]
	v_mfma_f32_16x16x32_bf16 v[76:79], v[152:155], v[208:211], v[76:79]
	v_mfma_f32_16x16x32_bf16 v[72:75], v[160:163], v[208:211], v[72:75]
	v_mfma_f32_16x16x32_bf16 v[124:127], v[156:159], v[188:191], v[124:127]
	v_mfma_f32_16x16x32_bf16 v[120:123], v[164:167], v[188:191], v[120:123]
	v_mfma_f32_16x16x32_bf16 v[108:111], v[156:159], v[196:199], v[108:111]
	v_mfma_f32_16x16x32_bf16 v[104:107], v[164:167], v[196:199], v[104:107]
	v_mfma_f32_16x16x32_bf16 v[92:95], v[156:159], v[204:207], v[92:95]
	v_mfma_f32_16x16x32_bf16 v[88:91], v[164:167], v[204:207], v[88:91]
	v_mfma_f32_16x16x32_bf16 v[76:79], v[156:159], v[212:215], v[76:79]
	v_mfma_f32_16x16x32_bf16 v[72:75], v[164:167], v[212:215], v[72:75]
	v_mfma_f32_16x16x32_bf16 v[116:119], v[168:171], v[184:187], v[116:119]
	v_mfma_f32_16x16x32_bf16 v[112:115], v[176:179], v[184:187], v[112:115]
	v_mfma_f32_16x16x32_bf16 v[100:103], v[168:171], v[192:195], v[100:103]
	v_mfma_f32_16x16x32_bf16 v[96:99], v[176:179], v[192:195], v[96:99]
	v_mfma_f32_16x16x32_bf16 v[84:87], v[168:171], v[200:203], v[84:87]
	v_mfma_f32_16x16x32_bf16 v[80:83], v[176:179], v[200:203], v[80:83]
	v_mfma_f32_16x16x32_bf16 v[68:71], v[168:171], v[208:211], v[68:71]
	v_mfma_f32_16x16x32_bf16 v[64:67], v[176:179], v[208:211], v[64:67]
	v_mfma_f32_16x16x32_bf16 v[116:119], v[172:175], v[188:191], v[116:119]
	v_mfma_f32_16x16x32_bf16 v[112:115], v[180:183], v[188:191], v[112:115]
	v_mfma_f32_16x16x32_bf16 v[100:103], v[172:175], v[196:199], v[100:103]
	v_mfma_f32_16x16x32_bf16 v[96:99], v[180:183], v[196:199], v[96:99]
	v_mfma_f32_16x16x32_bf16 v[84:87], v[172:175], v[204:207], v[84:87]
	v_mfma_f32_16x16x32_bf16 v[80:83], v[180:183], v[204:207], v[80:83]
	v_mfma_f32_16x16x32_bf16 v[68:71], v[172:175], v[212:215], v[68:71]
	v_mfma_f32_16x16x32_bf16 v[64:67], v[180:183], v[212:215], v[64:67]
	s_barrier
; #define PG8_STAGE(bufoff, gbase, voff) do { _Pragma("unroll") for (int _i = 0; _i < 2; ++_i) \
;         __builtin_amdgcn_global_load_lds((const unsigned*)((const char*)(gbase) + (voff)[_i]), (LAS unsigned*)(lds + (bufoff) + ldsw + _i * 8192), 16, 0, 0); } while (0)
; #define PG8_LDA(dst, b, h) do { _Pragma("unroll") for (int m = 0; m < 4; ++m) _Pragma("unroll") for (int k = 0; k < 2; ++k) dst[m][k] = *(const LAS bf16x8*)(lds + PG8_SA(b, h) + aoff + m * 2048 + k * 1024); } while (0)
; #define PG8_MMA(ai, bj, At, Bt) do { __builtin_amdgcn_s_setprio(1); _Pragma("unroll") for (int m = 0; m < 4; ++m) _Pragma("unroll") for (int n = 0; n < 2; ++n) _Pragma("unroll") for (int k = 0; k < 2; ++k) \
;         acc[ai][bj][m][n] = __builtin_amdgcn_mfma_f32_16x16x32_bf16(Bt[n][k], At[m][k], acc[ai][bj][m][n], 0, 0, 0); __builtin_amdgcn_s_setprio(0); } while (0)
; #define PG8_WAIT_V(n) asm volatile("s_waitcnt vmcnt(" #n ")" ::: "memory")
; #define PG8_WAIT_L(n) asm volatile("s_waitcnt lgkmcnt(" #n ")" ::: "memory")
; #define PG8_BAR __builtin_amdgcn_s_barrier()
; #define PG8_SCHED __builtin_amdgcn_sched_barrier(0)
; template <class Epi, bool SP2 = false>
; __device__ __forceinline__ void gemm_phase(LAS unsigned char* lds, const Gemm g, const StaticOrder& S, const Epi& E) {
;     ...
;         for (int t = 0; t < nt; t += 2) {
;             const bool last = (t == nt - 2);
;             const char* a1 = cA + (size_t)(t + 1) * kstep;
;             const char* a2 = last ? nA : cA + (size_t)(t + 2) * kstep; const char* b2 = last ? nB : cB + (size_t)(t + 2) * kstep;
;             const char* a3 = a2 + kstep; const char* b3 = b2 + kstep;
;     ...
;             PG8_LDA(At, 1, 1); PG8_STAGE(PG8_SB(1, 0), b3, voffB); PG8_STAGE(PG8_SB(1, 1), b3 + hstepB, voffB); PG8_STAGE(PG8_SA(1, 0), a3, voffA);
;             PG8_WAIT_V(8); PG8_WAIT_L(0); PG8_BAR; PG8_MMA(1, 0, At, B0); PG8_MMA(1, 1, At, B1); PG8_BAR; PG8_SCHED;
	s_add_i32 s34, s58, s37
	v_lshl_add_u64 v[146:147], v[146:147], 0, s[8:9]
	s_mov_b32 m0, s34
	ds_read_b128 v[184:187], v151 offset:49152
	ds_read_b128 v[188:191], v151 offset:50176
	ds_read_b128 v[192:195], v151 offset:51200
	ds_read_b128 v[196:199], v151 offset:52224
	ds_read_b128 v[200:203], v151 offset:53248
	ds_read_b128 v[204:207], v151 offset:54272
	ds_read_b128 v[208:211], v151 offset:55296
	ds_read_b128 v[212:215], v151 offset:56320
	global_load_lds_dwordx4 v[146:147], off
	s_add_i32 m0, s34, 0x2000
	s_add_u32 s30, s30, 0x40080
	v_lshl_add_u64 v[146:147], v[216:217], 0, s[8:9]
	s_addc_u32 s31, s31, 0
	s_add_i32 s34, s59, s37
	global_load_lds_dwordx4 v[146:147], off
	v_lshl_add_u64 v[146:147], s[30:31], 0, v[134:135]
	s_mov_b32 m0, s34
	s_nop 0
	global_load_lds_dwordx4 v[146:147], off
	v_lshl_add_u64 v[146:147], s[30:31], 0, v[130:131]
	s_add_i32 m0, s34, 0x2000
	s_nop 0
	global_load_lds_dwordx4 v[146:147], off
	v_lshl_add_u64 v[146:147], v[218:219], 0, s[8:9]
	s_mov_b32 m0, s46
	s_nop 0
	global_load_lds_dwordx4 v[146:147], off
	v_lshl_add_u64 v[146:147], v[220:221], 0, s[8:9]
	s_mov_b32 m0, s47
	s_nop 0
	global_load_lds_dwordx4 v[146:147], off
	s_waitcnt vmcnt(8) lgkmcnt(0)
	s_barrier
	v_mfma_f32_16x16x32_bf16 v[60:63], v[152:155], v[184:187], v[60:63]
	v_mfma_f32_16x16x32_bf16 v[56:59], v[160:163], v[184:187], v[56:59]
	v_mfma_f32_16x16x32_bf16 v[44:47], v[152:155], v[192:195], v[44:47]
	v_mfma_f32_16x16x32_bf16 v[40:43], v[160:163], v[192:195], v[40:43]
	v_mfma_f32_16x16x32_bf16 v[28:31], v[152:155], v[200:203], v[28:31]
	v_mfma_f32_16x16x32_bf16 v[24:27], v[160:163], v[200:203], v[24:27]
	v_mfma_f32_16x16x32_bf16 v[12:15], v[152:155], v[208:211], v[12:15]
	v_mfma_f32_16x16x32_bf16 v[8:11], v[160:163], v[208:211], v[8:11]
	v_mfma_f32_16x16x32_bf16 v[60:63], v[156:159], v[188:191], v[60:63]
	v_mfma_f32_16x16x32_bf16 v[56:59], v[164:167], v[188:191], v[56:59]
	v_mfma_f32_16x16x32_bf16 v[44:47], v[156:159], v[196:199], v[44:47]
	v_mfma_f32_16x16x32_bf16 v[40:43], v[164:167], v[196:199], v[40:43]
	v_mfma_f32_16x16x32_bf16 v[28:31], v[156:159], v[204:207], v[28:31]
	v_mfma_f32_16x16x32_bf16 v[24:27], v[164:167], v[204:207], v[24:27]
	v_mfma_f32_16x16x32_bf16 v[12:15], v[156:159], v[212:215], v[12:15]
	v_mfma_f32_16x16x32_bf16 v[8:11], v[164:167], v[212:215], v[8:11]
	v_mfma_f32_16x16x32_bf16 v[52:55], v[168:171], v[184:187], v[52:55]
	v_mfma_f32_16x16x32_bf16 v[48:51], v[176:179], v[184:187], v[48:51]
	v_mfma_f32_16x16x32_bf16 v[36:39], v[168:171], v[192:195], v[36:39]
	v_mfma_f32_16x16x32_bf16 v[32:35], v[176:179], v[192:195], v[32:35]
	v_mfma_f32_16x16x32_bf16 v[20:23], v[168:171], v[200:203], v[20:23]
	v_mfma_f32_16x16x32_bf16 v[16:19], v[176:179], v[200:203], v[16:19]
	v_mfma_f32_16x16x32_bf16 v[4:7], v[168:171], v[208:211], v[4:7]
	v_mfma_f32_16x16x32_bf16 v[0:3], v[176:179], v[208:211], v[0:3]
	v_mfma_f32_16x16x32_bf16 v[52:55], v[172:175], v[188:191], v[52:55]
	v_mfma_f32_16x16x32_bf16 v[48:51], v[180:183], v[188:191], v[48:51]
	v_mfma_f32_16x16x32_bf16 v[36:39], v[172:175], v[196:199], v[36:39]
	v_mfma_f32_16x16x32_bf16 v[32:35], v[180:183], v[196:199], v[32:35]
	v_mfma_f32_16x16x32_bf16 v[20:23], v[172:175], v[204:207], v[20:23]
	v_mfma_f32_16x16x32_bf16 v[16:19], v[180:183], v[204:207], v[16:19]
	v_mfma_f32_16x16x32_bf16 v[4:7], v[172:175], v[212:215], v[4:7]
	v_mfma_f32_16x16x32_bf16 v[0:3], v[180:183], v[212:215], v[0:3]
	s_barrier
	s_add_i32 s57, s57, 2
	s_add_u32 s28, s28, 0x100
	s_addc_u32 s29, s29, 0
	s_add_u32 s55, s55, 0x100
	s_addc_u32 s56, s56, 0
	s_cmp_gt_u32 s57, 13
	s_cbranch_scc0 .LBB0_1077
	s_and_b64 vcc, exec, s[10:11]
	s_cbranch_vccz .LBB0_1080
	s_barrier

; #define PG8_STAGE(bufoff, gbase, voff) do { _Pragma("unroll") for (int _i = 0; _i < 2; ++_i) \
;         __builtin_amdgcn_global_load_lds((const unsigned*)((const char*)(gbase) + (voff)[_i]), (LAS unsigned*)(lds + (bufoff) + ldsw + _i * 8192), 16, 0, 0); } while (0)
; #define PG8_LDA(dst, b, h) do { _Pragma("unroll") for (int m = 0; m < 4; ++m) _Pragma("unroll") for (int k = 0; k < 2; ++k) dst[m][k] = *(const LAS bf16x8*)(lds + PG8_SA(b, h) + aoff + m * 2048 + k * 1024); } while (0)
; #define PG8_LDB(dst, b, h) do { _Pragma("unroll") for (int n = 0; n < 2; ++n) _Pragma("unroll") for (int k = 0; k < 2; ++k) dst[n][k] = *(const LAS bf16x8*)(lds + PG8_SB(b, h) + boff + n * 2048 + k * 1024); } while (0)
; #define PG8_MMA(ai, bj, At, Bt) do { __builtin_amdgcn_s_setprio(1); _Pragma("unroll") for (int m = 0; m < 4; ++m) _Pragma("unroll") for (int n = 0; n < 2; ++n) _Pragma("unroll") for (int k = 0; k < 2; ++k) \
;         acc[ai][bj][m][n] = __builtin_amdgcn_mfma_f32_16x16x32_bf16(Bt[n][k], At[m][k], acc[ai][bj][m][n], 0, 0, 0); __builtin_amdgcn_s_setprio(0); } while (0)
; #define PG8_WAIT_V(n) asm volatile("s_waitcnt vmcnt(" #n ")" ::: "memory")
; #define PG8_WAIT_L(n) asm volatile("s_waitcnt lgkmcnt(" #n ")" ::: "memory")
; #define PG8_BAR __builtin_amdgcn_s_barrier()
; #define PG8_SCHED __builtin_amdgcn_sched_barrier(0)
; template <class Epi, bool SP2 = false>
; __device__ __forceinline__ void gemm_phase(LAS unsigned char* lds, const Gemm g, const StaticOrder& S, const Epi& E) {
;     ...
;             const bool last = (t == nt - 2);
;             const char* a1 = cA + (size_t)(t + 1) * kstep;
;             const char* a2 = last ? nA : cA + (size_t)(t + 2) * kstep; const char* b2 = last ? nB : cB + (size_t)(t + 2) * kstep;
;             const char* a3 = a2 + kstep; const char* b3 = b2 + kstep;
;             if constexpr (SP2) {
;             PG8_LDB(B0, 0, 0); PG8_LDB(B1, 0, 1); PG8_SCHED; PG8_LDA(At, 0, 0); PG8_STAGE(PG8_SA(1, 1), a1 + hstepA, voffA);
;             PG8_WAIT_V(8); PG8_WAIT_L(0); PG8_BAR; PG8_MMA(0, 0, At, B0); PG8_MMA(0, 1, At, B1); PG8_BAR; PG8_SCHED;
;             PG8_LDA(At, 0, 1); PG8_STAGE(PG8_SB(0, 0), b2, voffB); PG8_STAGE(PG8_SB(0, 1), b2 + hstepB, voffB); PG8_STAGE(PG8_SA(0, 0), a2, voffA);
;             PG8_WAIT_V(8); PG8_WAIT_L(0); PG8_BAR; PG8_MMA(1, 0, At, B0); PG8_MMA(1, 1, At, B1); PG8_BAR; PG8_SCHED;
.LBB0_1148:
	ds_read_b128 v[150:153], v147
	ds_read_b128 v[154:157], v147 offset:1024
	ds_read_b128 v[158:161], v147 offset:2048
	ds_read_b128 v[162:165], v147 offset:3072
	ds_read_b128 v[166:169], v148
	ds_read_b128 v[170:173], v148 offset:1024
	ds_read_b128 v[174:177], v148 offset:2048
	ds_read_b128 v[178:181], v148 offset:3072
	s_add_u32 s34, s30, 0xfff50080
	s_addc_u32 s35, s31, -1
	s_cmp_eq_u32 s64, 40
	s_cselect_b32 s37, s5, s35
	s_cselect_b32 s36, s4, s34
	s_cselect_b32 s35, s29, s63
	s_cselect_b32 s34, s28, s62
	v_lshl_add_u64 v[214:215], s[30:31], 0, v[138:139]
	s_add_i32 m0, s41, 0xc000
	ds_read_b128 v[182:185], v149
	ds_read_b128 v[186:189], v149 offset:1024
	ds_read_b128 v[190:193], v149 offset:2048
	ds_read_b128 v[194:197], v149 offset:3072
	ds_read_b128 v[198:201], v149 offset:4096
	ds_read_b128 v[202:205], v149 offset:5120
	ds_read_b128 v[206:209], v149 offset:6144
	ds_read_b128 v[210:213], v149 offset:7168
	global_load_lds_dwordx4 v[214:215], off
	v_lshl_add_u64 v[214:215], s[30:31], 0, v[140:141]
	s_add_i32 m0, s41, 0xe000
	s_nop 0
	global_load_lds_dwordx4 v[214:215], off
	s_waitcnt vmcnt(8) lgkmcnt(0)
	s_barrier
	v_mfma_f32_16x16x32_bf16 v[124:127], v[150:153], v[182:185], v[124:127]
	v_mfma_f32_16x16x32_bf16 v[120:123], v[158:161], v[182:185], v[120:123]
	v_mfma_f32_16x16x32_bf16 v[116:119], v[150:153], v[190:193], v[116:119]
	v_mfma_f32_16x16x32_bf16 v[112:115], v[158:161], v[190:193], v[112:115]
	v_mfma_f32_16x16x32_bf16 v[100:103], v[150:153], v[198:201], v[100:103]
	v_mfma_f32_16x16x32_bf16 v[96:99], v[158:161], v[198:201], v[96:99]
	v_mfma_f32_16x16x32_bf16 v[84:87], v[150:153], v[206:209], v[84:87]
	v_mfma_f32_16x16x32_bf16 v[80:83], v[158:161], v[206:209], v[80:83]
	v_mfma_f32_16x16x32_bf16 v[124:127], v[154:157], v[186:189], v[124:127]
	v_mfma_f32_16x16x32_bf16 v[120:123], v[162:165], v[186:189], v[120:123]
	v_mfma_f32_16x16x32_bf16 v[116:119], v[154:157], v[194:197], v[116:119]
	v_mfma_f32_16x16x32_bf16 v[112:115], v[162:165], v[194:197], v[112:115]
	v_mfma_f32_16x16x32_bf16 v[100:103], v[154:157], v[202:205], v[100:103]
	v_mfma_f32_16x16x32_bf16 v[96:99], v[162:165], v[202:205], v[96:99]
	v_mfma_f32_16x16x32_bf16 v[84:87], v[154:157], v[210:213], v[84:87]
	v_mfma_f32_16x16x32_bf16 v[80:83], v[162:165], v[210:213], v[80:83]
	v_mfma_f32_16x16x32_bf16 v[108:111], v[166:169], v[182:185], v[108:111]
	v_mfma_f32_16x16x32_bf16 v[104:107], v[174:177], v[182:185], v[104:107]
	v_mfma_f32_16x16x32_bf16 v[92:95], v[166:169], v[190:193], v[92:95]
	v_mfma_f32_16x16x32_bf16 v[88:91], v[174:177], v[190:193], v[88:91]
	v_mfma_f32_16x16x32_bf16 v[76:79], v[166:169], v[198:201], v[76:79]
	v_mfma_f32_16x16x32_bf16 v[72:75], v[174:177], v[198:201], v[72:75]
	v_mfma_f32_16x16x32_bf16 v[68:71], v[166:169], v[206:209], v[68:71]
	v_mfma_f32_16x16x32_bf16 v[64:67], v[174:177], v[206:209], v[64:67]
	v_mfma_f32_16x16x32_bf16 v[108:111], v[170:173], v[186:189], v[108:111]
	v_mfma_f32_16x16x32_bf16 v[104:107], v[178:181], v[186:189], v[104:107]
	v_mfma_f32_16x16x32_bf16 v[92:95], v[170:173], v[194:197], v[92:95]
	v_mfma_f32_16x16x32_bf16 v[88:91], v[178:181], v[194:197], v[88:91]
	v_mfma_f32_16x16x32_bf16 v[76:79], v[170:173], v[202:205], v[76:79]
	v_mfma_f32_16x16x32_bf16 v[72:75], v[178:181], v[202:205], v[72:75]
	v_mfma_f32_16x16x32_bf16 v[68:71], v[170:173], v[210:213], v[68:71]
	v_mfma_f32_16x16x32_bf16 v[64:67], v[178:181], v[210:213], v[64:67]
	s_barrier
	s_add_i32 s65, s52, s38
	v_lshl_add_u64 v[214:215], s[34:35], 0, v[134:135]
	s_mov_b32 m0, s65
	ds_read_b128 v[182:185], v149 offset:16384
	ds_read_b128 v[186:189], v149 offset:17408
	ds_read_b128 v[190:193], v149 offset:18432
	ds_read_b128 v[194:197], v149 offset:19456
	ds_read_b128 v[198:201], v149 offset:20480
	ds_read_b128 v[202:205], v149 offset:21504
	ds_read_b128 v[206:209], v149 offset:22528
	ds_read_b128 v[210:213], v149 offset:23552
	global_load_lds_dwordx4 v[214:215], off
	s_add_i32 m0, s65, 0x2000
	s_add_u32 s66, s34, 0xb0000
	v_lshl_add_u64 v[216:217], s[34:35], 0, v[130:131]
	s_addc_u32 s67, s35, 0
	s_add_i32 s65, s53, s38
	global_load_lds_dwordx4 v[216:217], off
	v_lshl_add_u64 v[218:219], s[66:67], 0, v[134:135]
	s_mov_b32 m0, s65
	v_lshl_add_u64 v[220:221], s[36:37], 0, v[132:133]
	global_load_lds_dwordx4 v[218:219], off
	v_lshl_add_u64 v[218:219], s[66:67], 0, v[130:131]
	s_add_i32 m0, s65, 0x2000
	s_nop 0
	global_load_lds_dwordx4 v[218:219], off
	v_lshl_add_u64 v[218:219], s[36:37], 0, v[136:137]
	s_mov_b32 m0, s41
	s_nop 0
	global_load_lds_dwordx4 v[218:219], off
	s_mov_b32 m0, s42
	s_nop 0
	global_load_lds_dwordx4 v[220:221], off
	s_waitcnt vmcnt(8) lgkmcnt(0)
	s_barrier
; #define PG8_STAGE(bufoff, gbase, voff) do { _Pragma("unroll") for (int _i = 0; _i < 2; ++_i) \
;         __builtin_amdgcn_global_load_lds((const unsigned*)((const char*)(gbase) + (voff)[_i]), (LAS unsigned*)(lds + (bufoff) + ldsw + _i * 8192), 16, 0, 0); } while (0)
; #define PG8_LDA(dst, b, h) do { _Pragma("unroll") for (int m = 0; m < 4; ++m) _Pragma("unroll") for (int k = 0; k < 2; ++k) dst[m][k] = *(const LAS bf16x8*)(lds + PG8_SA(b, h) + aoff + m * 2048 + k * 1024); } while (0)
; #define PG8_LDB(dst, b, h) do { _Pragma("unroll") for (int n = 0; n < 2; ++n) _Pragma("unroll") for (int k = 0; k < 2; ++k) dst[n][k] = *(const LAS bf16x8*)(lds + PG8_SB(b, h) + boff + n * 2048 + k * 1024); } while (0)
; #define PG8_MMA(ai, bj, At, Bt) do { __builtin_amdgcn_s_setprio(1); _Pragma("unroll") for (int m = 0; m < 4; ++m) _Pragma("unroll") for (int n = 0; n < 2; ++n) _Pragma("unroll") for (int k = 0; k < 2; ++k) \
;         acc[ai][bj][m][n] = __builtin_amdgcn_mfma_f32_16x16x32_bf16(Bt[n][k], At[m][k], acc[ai][bj][m][n], 0, 0, 0); __builtin_amdgcn_s_setprio(0); } while (0)
; #define PG8_WAIT_V(n) asm volatile("s_waitcnt vmcnt(" #n ")" ::: "memory")
; #define PG8_WAIT_L(n) asm volatile("s_waitcnt lgkmcnt(" #n ")" ::: "memory")
; #define PG8_BAR __builtin_amdgcn_s_barrier()
; #define PG8_SCHED __builtin_amdgcn_sched_barrier(0)
; template <class Epi, bool SP2 = false>
; __device__ __forceinline__ void gemm_phase(LAS unsigned char* lds, const Gemm g, const StaticOrder& S, const Epi& E) {
;     ...
;             PG8_WAIT_V(8); PG8_WAIT_L(0); PG8_BAR; PG8_MMA(1, 0, At, B0); PG8_MMA(1, 1, At, B1); PG8_BAR; PG8_SCHED;
;             PG8_LDB(B0, 1, 0); PG8_LDB(B1, 1, 1); PG8_SCHED; PG8_LDA(At, 1, 0); PG8_STAGE(PG8_SA(0, 1), a2 + hstepA, voffA);
;             PG8_WAIT_V(8); PG8_WAIT_L(0); PG8_BAR; PG8_MMA(0, 0, At, B0); PG8_MMA(0, 1, At, B1); PG8_BAR; PG8_SCHED;
	v_mfma_f32_16x16x32_bf16 v[60:63], v[150:153], v[182:185], v[60:63]
	v_mfma_f32_16x16x32_bf16 v[56:59], v[158:161], v[182:185], v[56:59]
	v_mfma_f32_16x16x32_bf16 v[52:55], v[150:153], v[190:193], v[52:55]
	v_mfma_f32_16x16x32_bf16 v[48:51], v[158:161], v[190:193], v[48:51]
	v_mfma_f32_16x16x32_bf16 v[36:39], v[150:153], v[198:201], v[36:39]
	v_mfma_f32_16x16x32_bf16 v[32:35], v[158:161], v[198:201], v[32:35]
	v_mfma_f32_16x16x32_bf16 v[20:23], v[150:153], v[206:209], v[20:23]
	v_mfma_f32_16x16x32_bf16 v[16:19], v[158:161], v[206:209], v[16:19]
	v_mfma_f32_16x16x32_bf16 v[60:63], v[154:157], v[186:189], v[60:63]
	v_mfma_f32_16x16x32_bf16 v[56:59], v[162:165], v[186:189], v[56:59]
	v_mfma_f32_16x16x32_bf16 v[52:55], v[154:157], v[194:197], v[52:55]
	v_mfma_f32_16x16x32_bf16 v[48:51], v[162:165], v[194:197], v[48:51]
	v_mfma_f32_16x16x32_bf16 v[36:39], v[154:157], v[202:205], v[36:39]
	v_mfma_f32_16x16x32_bf16 v[32:35], v[162:165], v[202:205], v[32:35]
	v_mfma_f32_16x16x32_bf16 v[20:23], v[154:157], v[210:213], v[20:23]
	v_mfma_f32_16x16x32_bf16 v[16:19], v[162:165], v[210:213], v[16:19]
	v_mfma_f32_16x16x32_bf16 v[44:47], v[166:169], v[182:185], v[44:47]
	v_mfma_f32_16x16x32_bf16 v[40:43], v[174:177], v[182:185], v[40:43]
	v_mfma_f32_16x16x32_bf16 v[28:31], v[166:169], v[190:193], v[28:31]
	v_mfma_f32_16x16x32_bf16 v[24:27], v[174:177], v[190:193], v[24:27]
	v_mfma_f32_16x16x32_bf16 v[12:15], v[166:169], v[198:201], v[12:15]
	v_mfma_f32_16x16x32_bf16 v[8:11], v[174:177], v[198:201], v[8:11]
	v_mfma_f32_16x16x32_bf16 v[4:7], v[166:169], v[206:209], v[4:7]
	v_mfma_f32_16x16x32_bf16 v[0:3], v[174:177], v[206:209], v[0:3]
	v_mfma_f32_16x16x32_bf16 v[44:47], v[170:173], v[186:189], v[44:47]
	v_mfma_f32_16x16x32_bf16 v[40:43], v[178:181], v[186:189], v[40:43]
	v_mfma_f32_16x16x32_bf16 v[28:31], v[170:173], v[194:197], v[28:31]
	v_mfma_f32_16x16x32_bf16 v[24:27], v[178:181], v[194:197], v[24:27]
	v_mfma_f32_16x16x32_bf16 v[12:15], v[170:173], v[202:205], v[12:15]
	v_mfma_f32_16x16x32_bf16 v[8:11], v[178:181], v[202:205], v[8:11]
	v_mfma_f32_16x16x32_bf16 v[4:7], v[170:173], v[210:213], v[4:7]
	v_mfma_f32_16x16x32_bf16 v[0:3], v[178:181], v[210:213], v[0:3]
	s_barrier
	s_add_i32 s65, 0, 0x18000
	s_add_i32 s66, 0, 0x1c000
	v_add_u32_e32 v162, s65, v146
	v_add_u32_e32 v178, s66, v146
	ds_read_b128 v[150:153], v162
	ds_read_b128 v[154:157], v162 offset:1024
	ds_read_b128 v[158:161], v162 offset:2048
	ds_read_b128 v[162:165], v162 offset:3072
	ds_read_b128 v[166:169], v178
	ds_read_b128 v[170:173], v178 offset:1024
	ds_read_b128 v[174:177], v178 offset:2048
	ds_read_b128 v[178:181], v178 offset:3072
	s_add_u32 s36, s36, 0xb0000
	s_addc_u32 s37, s37, 0
	s_mov_b32 m0, s43
	v_lshl_add_u64 v[222:223], s[36:37], 0, v[136:137]
	ds_read_b128 v[182:185], v149 offset:32768
	ds_read_b128 v[186:189], v149 offset:33792
	ds_read_b128 v[190:193], v149 offset:34816
	ds_read_b128 v[194:197], v149 offset:35840
	ds_read_b128 v[198:201], v149 offset:36864
	ds_read_b128 v[202:205], v149 offset:37888
	ds_read_b128 v[206:209], v149 offset:38912
	ds_read_b128 v[210:213], v149 offset:39936
	global_load_lds_dwordx4 v[222:223], off
	v_lshl_add_u64 v[222:223], s[36:37], 0, v[132:133]
	s_mov_b32 m0, s44
	s_nop 0
	global_load_lds_dwordx4 v[222:223], off
	s_waitcnt vmcnt(8) lgkmcnt(0)
	s_barrier
	v_mfma_f32_16x16x32_bf16 v[124:127], v[150:153], v[182:185], v[124:127]
	v_mfma_f32_16x16x32_bf16 v[120:123], v[158:161], v[182:185], v[120:123]
	v_mfma_f32_16x16x32_bf16 v[116:119], v[150:153], v[190:193], v[116:119]
	v_mfma_f32_16x16x32_bf16 v[112:115], v[158:161], v[190:193], v[112:115]
	v_mfma_f32_16x16x32_bf16 v[100:103], v[150:153], v[198:201], v[100:103]
	v_mfma_f32_16x16x32_bf16 v[96:99], v[158:161], v[198:201], v[96:99]
	v_mfma_f32_16x16x32_bf16 v[84:87], v[150:153], v[206:209], v[84:87]
	v_mfma_f32_16x16x32_bf16 v[80:83], v[158:161], v[206:209], v[80:83]
	v_mfma_f32_16x16x32_bf16 v[124:127], v[154:157], v[186:189], v[124:127]
	v_mfma_f32_16x16x32_bf16 v[120:123], v[162:165], v[186:189], v[120:123]
	v_mfma_f32_16x16x32_bf16 v[116:119], v[154:157], v[194:197], v[116:119]
	v_mfma_f32_16x16x32_bf16 v[112:115], v[162:165], v[194:197], v[112:115]
	v_mfma_f32_16x16x32_bf16 v[100:103], v[154:157], v[202:205], v[100:103]
	v_mfma_f32_16x16x32_bf16 v[96:99], v[162:165], v[202:205], v[96:99]
	v_mfma_f32_16x16x32_bf16 v[84:87], v[154:157], v[210:213], v[84:87]
	v_mfma_f32_16x16x32_bf16 v[80:83], v[162:165], v[210:213], v[80:83]
	v_mfma_f32_16x16x32_bf16 v[108:111], v[166:169], v[182:185], v[108:111]
	v_mfma_f32_16x16x32_bf16 v[104:107], v[174:177], v[182:185], v[104:107]
	v_mfma_f32_16x16x32_bf16 v[92:95], v[166:169], v[190:193], v[92:95]
	v_mfma_f32_16x16x32_bf16 v[88:91], v[174:177], v[190:193], v[88:91]
	v_mfma_f32_16x16x32_bf16 v[76:79], v[166:169], v[198:201], v[76:79]
	v_mfma_f32_16x16x32_bf16 v[72:75], v[174:177], v[198:201], v[72:75]
	v_mfma_f32_16x16x32_bf16 v[68:71], v[166:169], v[206:209], v[68:71]
	v_mfma_f32_16x16x32_bf16 v[64:67], v[174:177], v[206:209], v[64:67]
	v_mfma_f32_16x16x32_bf16 v[108:111], v[170:173], v[186:189], v[108:111]
	v_mfma_f32_16x16x32_bf16 v[104:107], v[178:181], v[186:189], v[104:107]
	v_mfma_f32_16x16x32_bf16 v[92:95], v[170:173], v[194:197], v[92:95]
	v_mfma_f32_16x16x32_bf16 v[88:91], v[178:181], v[194:197], v[88:91]
	v_mfma_f32_16x16x32_bf16 v[76:79], v[170:173], v[202:205], v[76:79]
	v_mfma_f32_16x16x32_bf16 v[72:75], v[178:181], v[202:205], v[72:75]
	v_mfma_f32_16x16x32_bf16 v[68:71], v[170:173], v[210:213], v[68:71]
	v_mfma_f32_16x16x32_bf16 v[64:67], v[178:181], v[210:213], v[64:67]
	s_barrier
; #define PG8_STAGE(bufoff, gbase, voff) do { _Pragma("unroll") for (int _i = 0; _i < 2; ++_i) \
;         __builtin_amdgcn_global_load_lds((const unsigned*)((const char*)(gbase) + (voff)[_i]), (LAS unsigned*)(lds + (bufoff) + ldsw + _i * 8192), 16, 0, 0); } while (0)
; #define PG8_LDA(dst, b, h) do { _Pragma("unroll") for (int m = 0; m < 4; ++m) _Pragma("unroll") for (int k = 0; k < 2; ++k) dst[m][k] = *(const LAS bf16x8*)(lds + PG8_SA(b, h) + aoff + m * 2048 + k * 1024); } while (0)
; #define PG8_MMA(ai, bj, At, Bt) do { __builtin_amdgcn_s_setprio(1); _Pragma("unroll") for (int m = 0; m < 4; ++m) _Pragma("unroll") for (int n = 0; n < 2; ++n) _Pragma("unroll") for (int k = 0; k < 2; ++k) \
;         acc[ai][bj][m][n] = __builtin_amdgcn_mfma_f32_16x16x32_bf16(Bt[n][k], At[m][k], acc[ai][bj][m][n], 0, 0, 0); __builtin_amdgcn_s_setprio(0); } while (0)
; #define PG8_WAIT_V(n) asm volatile("s_waitcnt vmcnt(" #n ")" ::: "memory")
; #define PG8_WAIT_L(n) asm volatile("s_waitcnt lgkmcnt(" #n ")" ::: "memory")
; #define PG8_BAR __builtin_amdgcn_s_barrier()
; #define PG8_SCHED __builtin_amdgcn_sched_barrier(0)
; template <class Epi, bool SP2 = false>
; __device__ __forceinline__ void gemm_phase(LAS unsigned char* lds, const Gemm g, const StaticOrder& S, const Epi& E) {
;     ...
;         for (int t = 0; t < nt; t += 2) {
;             const bool last = (t == nt - 2);
;             const char* a1 = cA + (size_t)(t + 1) * kstep;
;             const char* a2 = last ? nA : cA + (size_t)(t + 2) * kstep; const char* b2 = last ? nB : cB + (size_t)(t + 2) * kstep;
;             const char* a3 = a2 + kstep; const char* b3 = b2 + kstep;
;     ...
;             PG8_LDA(At, 1, 1); PG8_STAGE(PG8_SB(1, 0), b3, voffB); PG8_STAGE(PG8_SB(1, 1), b3 + hstepB, voffB); PG8_STAGE(PG8_SA(1, 0), a3, voffA);
;             PG8_WAIT_V(8); PG8_WAIT_L(0); PG8_BAR; PG8_MMA(1, 0, At, B0); PG8_MMA(1, 1, At, B1); PG8_BAR; PG8_SCHED;
	s_add_i32 s36, s65, s38
	v_lshl_add_u64 v[214:215], v[214:215], 0, s[10:11]
	s_mov_b32 m0, s36
	ds_read_b128 v[182:185], v149 offset:49152
	ds_read_b128 v[186:189], v149 offset:50176
	ds_read_b128 v[190:193], v149 offset:51200
	ds_read_b128 v[194:197], v149 offset:52224
	ds_read_b128 v[198:201], v149 offset:53248
	ds_read_b128 v[202:205], v149 offset:54272
	ds_read_b128 v[206:209], v149 offset:55296
	ds_read_b128 v[210:213], v149 offset:56320
	global_load_lds_dwordx4 v[214:215], off
	s_add_i32 m0, s36, 0x2000
	s_add_u32 s34, s34, 0xb0080
	v_lshl_add_u64 v[214:215], v[216:217], 0, s[10:11]
	s_addc_u32 s35, s35, 0
	s_add_i32 s36, s66, s38
	global_load_lds_dwordx4 v[214:215], off
	v_lshl_add_u64 v[214:215], s[34:35], 0, v[134:135]
	s_mov_b32 m0, s36
	s_nop 0
	global_load_lds_dwordx4 v[214:215], off
	v_lshl_add_u64 v[214:215], s[34:35], 0, v[130:131]
	s_add_i32 m0, s36, 0x2000
	s_nop 0
	global_load_lds_dwordx4 v[214:215], off
	v_lshl_add_u64 v[214:215], v[218:219], 0, s[10:11]
	s_mov_b32 m0, s48
	s_nop 0
	global_load_lds_dwordx4 v[214:215], off
	v_lshl_add_u64 v[214:215], v[220:221], 0, s[10:11]
	s_mov_b32 m0, s49
	s_nop 0
	global_load_lds_dwordx4 v[214:215], off
	s_waitcnt vmcnt(8) lgkmcnt(0)
	s_barrier
	v_mfma_f32_16x16x32_bf16 v[60:63], v[150:153], v[182:185], v[60:63]
	v_mfma_f32_16x16x32_bf16 v[56:59], v[158:161], v[182:185], v[56:59]
	v_mfma_f32_16x16x32_bf16 v[52:55], v[150:153], v[190:193], v[52:55]
	v_mfma_f32_16x16x32_bf16 v[48:51], v[158:161], v[190:193], v[48:51]
	v_mfma_f32_16x16x32_bf16 v[36:39], v[150:153], v[198:201], v[36:39]
	v_mfma_f32_16x16x32_bf16 v[32:35], v[158:161], v[198:201], v[32:35]
	v_mfma_f32_16x16x32_bf16 v[20:23], v[150:153], v[206:209], v[20:23]
	v_mfma_f32_16x16x32_bf16 v[16:19], v[158:161], v[206:209], v[16:19]
	v_mfma_f32_16x16x32_bf16 v[60:63], v[154:157], v[186:189], v[60:63]
	v_mfma_f32_16x16x32_bf16 v[56:59], v[162:165], v[186:189], v[56:59]
	v_mfma_f32_16x16x32_bf16 v[52:55], v[154:157], v[194:197], v[52:55]
	v_mfma_f32_16x16x32_bf16 v[48:51], v[162:165], v[194:197], v[48:51]
	v_mfma_f32_16x16x32_bf16 v[36:39], v[154:157], v[202:205], v[36:39]
	v_mfma_f32_16x16x32_bf16 v[32:35], v[162:165], v[202:205], v[32:35]
	v_mfma_f32_16x16x32_bf16 v[20:23], v[154:157], v[210:213], v[20:23]
	v_mfma_f32_16x16x32_bf16 v[16:19], v[162:165], v[210:213], v[16:19]
	v_mfma_f32_16x16x32_bf16 v[44:47], v[166:169], v[182:185], v[44:47]
	v_mfma_f32_16x16x32_bf16 v[40:43], v[174:177], v[182:185], v[40:43]
	v_mfma_f32_16x16x32_bf16 v[28:31], v[166:169], v[190:193], v[28:31]
	v_mfma_f32_16x16x32_bf16 v[24:27], v[174:177], v[190:193], v[24:27]
	v_mfma_f32_16x16x32_bf16 v[12:15], v[166:169], v[198:201], v[12:15]
	v_mfma_f32_16x16x32_bf16 v[8:11], v[174:177], v[198:201], v[8:11]
	v_mfma_f32_16x16x32_bf16 v[4:7], v[166:169], v[206:209], v[4:7]
	v_mfma_f32_16x16x32_bf16 v[0:3], v[174:177], v[206:209], v[0:3]
	v_mfma_f32_16x16x32_bf16 v[44:47], v[170:173], v[186:189], v[44:47]
	v_mfma_f32_16x16x32_bf16 v[40:43], v[178:181], v[186:189], v[40:43]
	v_mfma_f32_16x16x32_bf16 v[28:31], v[170:173], v[194:197], v[28:31]
	v_mfma_f32_16x16x32_bf16 v[24:27], v[178:181], v[194:197], v[24:27]
	v_mfma_f32_16x16x32_bf16 v[12:15], v[170:173], v[202:205], v[12:15]
	v_mfma_f32_16x16x32_bf16 v[8:11], v[178:181], v[202:205], v[8:11]
	v_mfma_f32_16x16x32_bf16 v[4:7], v[170:173], v[210:213], v[4:7]
	v_mfma_f32_16x16x32_bf16 v[0:3], v[178:181], v[210:213], v[0:3]
	s_barrier
	s_add_i32 s64, s64, 2
	s_add_u32 s30, s30, 0x100
	s_addc_u32 s31, s31, 0
	s_add_u32 s62, s62, 0x100
	s_addc_u32 s63, s63, 0
	s_cmp_gt_u32 s64, 41
	s_cbranch_scc0 .LBB0_1148
	s_and_b64 vcc, exec, s[12:13]
	s_cbranch_vccz .LBB0_1151
	s_barrier
